# MFMA order: accumulate-chain pairs grouped by A-fragment (A operand alternates between two quads for eight MFMAs)
# speedup vs baseline: 1.0129x; 1.0129x over previous
; #define PG8_STAGE(bufoff, gbase, voff) do { _Pragma("unroll") for (int _i = 0; _i < 2; ++_i) \
;         __builtin_amdgcn_global_load_lds((const unsigned*)((const char*)(gbase) + (voff)[_i]), (LAS unsigned*)(lds + (bufoff) + ldsw + _i * 8192), 16, 0, 0); } while (0)
; #define PG8_LDA(dst, b, h) do { _Pragma("unroll") for (int m = 0; m < 4; ++m) _Pragma("unroll") for (int k = 0; k < 2; ++k) dst[m][k] = *(const LAS bf16x8*)(lds + PG8_SA(b, h) + aoff + m * 2048 + k * 1024); } while (0)
; #define PG8_LDB(dst, b, h) do { _Pragma("unroll") for (int n = 0; n < 2; ++n) _Pragma("unroll") for (int k = 0; k < 2; ++k) dst[n][k] = *(const LAS bf16x8*)(lds + PG8_SB(b, h) + boff + n * 2048 + k * 1024); } while (0)
; #define PG8_MMA(ai, bj, At, Bt) do { __builtin_amdgcn_s_setprio(1); _Pragma("unroll") for (int m = 0; m < 4; ++m) _Pragma("unroll") for (int n = 0; n < 2; ++n) _Pragma("unroll") for (int k = 0; k < 2; ++k) \
;         acc[ai][bj][m][n] = __builtin_amdgcn_mfma_f32_16x16x32_bf16(Bt[n][k], At[m][k], acc[ai][bj][m][n], 0, 0, 0); __builtin_amdgcn_s_setprio(0); } while (0)
; #define PG8_WAIT_V(n) asm volatile("s_waitcnt vmcnt(" #n ")" ::: "memory")
; template <class EpiT>
; __device__ __forceinline__ void gemm_phase(LAS unsigned char* lds, const Gemm g, const StaticOrder& S, const EpiT& E) {
;     ...
;         const char* nA = has_next ? (const char*)g.A + (size_t)nxt.pm * tstepA + (size_t)nxt.pn * g.a_koff * 2 : cA; const char* nB = has_next ? (const char*)g.Bt + (size_t)nxt.pn * tstepB : cB;
;         for (int t = 0; t < nt; t += 2) {
;             const bool last = (t == nt - 2);
;             const char* a1 = cA + (size_t)(t + 1) * kstep;
;             const char* a2 = last ? nA : cA + (size_t)(t + 2) * kstep; const char* b2 = last ? nB : cB + (size_t)(t + 2) * kstep;
;             const char* a3 = a2 + kstep; const char* b3 = b2 + kstep;
;             PG8_LDB(B0, 0, 0); PG8_LDB(B1, 0, 1); PG8_SCHED; PG8_LDA(At, 0, 0); PG8_STAGE(PG8_SA(1, 1), a1 + hstepA, voffA);
;             PG8_WAIT_V(8); PG8_WAIT_L(0); PG8_BAR; PG8_MMA(0, 0, At, B0); PG8_MMA(0, 1, At, B1); PG8_BAR; PG8_SCHED;
;             PG8_LDA(At, 0, 1); PG8_STAGE(PG8_SB(0, 0), b2, voffB); PG8_STAGE(PG8_SB(0, 1), b2 + hstepB, voffB); PG8_STAGE(PG8_SA(0, 0), a2, voffA);
;             PG8_WAIT_V(8); PG8_WAIT_L(0); PG8_BAR; PG8_MMA(1, 0, At, B0); PG8_MMA(1, 1, At, B1); PG8_BAR; PG8_SCHED;
.LBB0_100:
	ds_read_b128 v[128:131], v160
	ds_read_b128 v[170:173], v160 offset:1024
	ds_read_b128 v[174:177], v160 offset:2048
	ds_read_b128 v[178:181], v160 offset:3072
	ds_read_b128 v[182:185], v161
	ds_read_b128 v[186:189], v161 offset:1024
	ds_read_b128 v[190:193], v161 offset:2048
	ds_read_b128 v[194:197], v161 offset:3072
	s_add_u32 s18, s16, 0xfff7c080
	s_addc_u32 s19, s17, -1
	s_cmp_eq_u32 s53, 28
	s_cselect_b32 s21, s3, s19
	s_cselect_b32 s20, s2, s18
	s_cselect_b32 s19, s15, s52
	s_cselect_b32 s18, s14, s51
	v_lshl_add_u64 v[158:159], s[16:17], 0, v[150:151]
	s_add_i32 m0, s35, 0xc000
	ds_read_b128 v[198:201], v162
	ds_read_b128 v[202:205], v162 offset:1024
	ds_read_b128 v[206:209], v162 offset:2048
	ds_read_b128 v[210:213], v162 offset:3072
	ds_read_b128 v[214:217], v162 offset:4096
	ds_read_b128 v[218:221], v162 offset:5120
	ds_read_b128 v[222:225], v162 offset:6144
	ds_read_b128 v[226:229], v162 offset:7168
	global_load_lds_dwordx4 v[158:159], off
	v_lshl_add_u64 v[158:159], s[16:17], 0, v[152:153]
	s_add_i32 m0, s35, 0xe000
	s_nop 0
	global_load_lds_dwordx4 v[158:159], off
	s_waitcnt vmcnt(8)
	s_waitcnt lgkmcnt(0)
	s_barrier
	s_setprio 1
	s_waitcnt lgkmcnt(0)
	v_mfma_f32_16x16x32_bf16 v[124:127], v[128:131], v[198:201], v[124:127]
	v_mfma_f32_16x16x32_bf16 v[124:127], v[170:173], v[202:205], v[124:127]
	v_mfma_f32_16x16x32_bf16 v[108:111], v[128:131], v[206:209], v[108:111]
	v_mfma_f32_16x16x32_bf16 v[108:111], v[170:173], v[210:213], v[108:111]
	v_mfma_f32_16x16x32_bf16 v[92:95], v[128:131], v[214:217], v[92:95]
	v_mfma_f32_16x16x32_bf16 v[92:95], v[170:173], v[218:221], v[92:95]
	v_mfma_f32_16x16x32_bf16 v[76:79], v[128:131], v[222:225], v[76:79]
	v_mfma_f32_16x16x32_bf16 v[76:79], v[170:173], v[226:229], v[76:79]
	v_mfma_f32_16x16x32_bf16 v[120:123], v[174:177], v[198:201], v[120:123]
	v_mfma_f32_16x16x32_bf16 v[120:123], v[178:181], v[202:205], v[120:123]
	v_mfma_f32_16x16x32_bf16 v[104:107], v[174:177], v[206:209], v[104:107]
	v_mfma_f32_16x16x32_bf16 v[104:107], v[178:181], v[210:213], v[104:107]
	v_mfma_f32_16x16x32_bf16 v[88:91], v[174:177], v[214:217], v[88:91]
	v_mfma_f32_16x16x32_bf16 v[88:91], v[178:181], v[218:221], v[88:91]
	v_mfma_f32_16x16x32_bf16 v[72:75], v[174:177], v[222:225], v[72:75]
	v_mfma_f32_16x16x32_bf16 v[72:75], v[178:181], v[226:229], v[72:75]
	s_setprio 0
	s_setprio 1
	v_mfma_f32_16x16x32_bf16 v[116:119], v[182:185], v[198:201], v[116:119]
	v_mfma_f32_16x16x32_bf16 v[116:119], v[186:189], v[202:205], v[116:119]
	v_mfma_f32_16x16x32_bf16 v[100:103], v[182:185], v[206:209], v[100:103]
	v_mfma_f32_16x16x32_bf16 v[100:103], v[186:189], v[210:213], v[100:103]
	v_mfma_f32_16x16x32_bf16 v[84:87], v[182:185], v[214:217], v[84:87]
	v_mfma_f32_16x16x32_bf16 v[84:87], v[186:189], v[218:221], v[84:87]
	v_mfma_f32_16x16x32_bf16 v[68:71], v[182:185], v[222:225], v[68:71]
	v_mfma_f32_16x16x32_bf16 v[68:71], v[186:189], v[226:229], v[68:71]
	v_mfma_f32_16x16x32_bf16 v[112:115], v[190:193], v[198:201], v[112:115]
	v_mfma_f32_16x16x32_bf16 v[112:115], v[194:197], v[202:205], v[112:115]
	v_mfma_f32_16x16x32_bf16 v[96:99], v[190:193], v[206:209], v[96:99]
	v_mfma_f32_16x16x32_bf16 v[96:99], v[194:197], v[210:213], v[96:99]
	v_mfma_f32_16x16x32_bf16 v[80:83], v[190:193], v[214:217], v[80:83]
	v_mfma_f32_16x16x32_bf16 v[80:83], v[194:197], v[218:221], v[80:83]
	v_mfma_f32_16x16x32_bf16 v[64:67], v[190:193], v[222:225], v[64:67]
	v_mfma_f32_16x16x32_bf16 v[64:67], v[194:197], v[226:229], v[64:67]
	s_setprio 0
	s_barrier
	s_add_i32 s54, s43, s25
	v_lshl_add_u64 v[158:159], s[18:19], 0, v[136:137]
	s_mov_b32 m0, s54
	ds_read_b128 v[198:201], v162 offset:16384
	ds_read_b128 v[202:205], v162 offset:17408
	ds_read_b128 v[206:209], v162 offset:18432
	ds_read_b128 v[210:213], v162 offset:19456
	ds_read_b128 v[214:217], v162 offset:20480
	ds_read_b128 v[218:221], v162 offset:21504
	ds_read_b128 v[222:225], v162 offset:22528
	ds_read_b128 v[226:229], v162 offset:23552
	global_load_lds_dwordx4 v[158:159], off
	s_add_i32 m0, s54, 0x2000
	s_add_u32 s54, s18, 0x84000
	v_lshl_add_u64 v[166:167], s[18:19], 0, v[132:133]
	s_addc_u32 s55, s19, 0
	s_add_i32 s56, s44, s25
	global_load_lds_dwordx4 v[166:167], off
	v_lshl_add_u64 v[230:231], s[54:55], 0, v[136:137]
	s_mov_b32 m0, s56
	v_lshl_add_u64 v[232:233], s[20:21], 0, v[134:135]
	global_load_lds_dwordx4 v[230:231], off
	v_lshl_add_u64 v[230:231], s[54:55], 0, v[132:133]
	s_add_i32 m0, s56, 0x2000
	s_nop 0
	global_load_lds_dwordx4 v[230:231], off
	v_lshl_add_u64 v[230:231], s[20:21], 0, v[138:139]
	s_mov_b32 m0, s35
	s_nop 0
	global_load_lds_dwordx4 v[230:231], off
	s_mov_b32 m0, s36
	s_nop 0
	global_load_lds_dwordx4 v[232:233], off
	s_waitcnt vmcnt(8)
	s_waitcnt lgkmcnt(0)
	s_barrier
; #define PG8_STAGE(bufoff, gbase, voff) do { _Pragma("unroll") for (int _i = 0; _i < 2; ++_i) \
;         __builtin_amdgcn_global_load_lds((const unsigned*)((const char*)(gbase) + (voff)[_i]), (LAS unsigned*)(lds + (bufoff) + ldsw + _i * 8192), 16, 0, 0); } while (0)
; #define PG8_LDA(dst, b, h) do { _Pragma("unroll") for (int m = 0; m < 4; ++m) _Pragma("unroll") for (int k = 0; k < 2; ++k) dst[m][k] = *(const LAS bf16x8*)(lds + PG8_SA(b, h) + aoff + m * 2048 + k * 1024); } while (0)
; #define PG8_LDB(dst, b, h) do { _Pragma("unroll") for (int n = 0; n < 2; ++n) _Pragma("unroll") for (int k = 0; k < 2; ++k) dst[n][k] = *(const LAS bf16x8*)(lds + PG8_SB(b, h) + boff + n * 2048 + k * 1024); } while (0)
; #define PG8_MMA(ai, bj, At, Bt) do { __builtin_amdgcn_s_setprio(1); _Pragma("unroll") for (int m = 0; m < 4; ++m) _Pragma("unroll") for (int n = 0; n < 2; ++n) _Pragma("unroll") for (int k = 0; k < 2; ++k) \
;         acc[ai][bj][m][n] = __builtin_amdgcn_mfma_f32_16x16x32_bf16(Bt[n][k], At[m][k], acc[ai][bj][m][n], 0, 0, 0); __builtin_amdgcn_s_setprio(0); } while (0)
; #define PG8_WAIT_V(n) asm volatile("s_waitcnt vmcnt(" #n ")" ::: "memory")
; #define PG8_WAIT_L(n) asm volatile("s_waitcnt lgkmcnt(" #n ")" ::: "memory")
; #define PG8_BAR __builtin_amdgcn_s_barrier()
; #define PG8_SCHED __builtin_amdgcn_sched_barrier(0)
; template <class EpiT>
; __device__ __forceinline__ void gemm_phase(LAS unsigned char* lds, const Gemm g, const StaticOrder& S, const EpiT& E) {
;     ...
;             PG8_WAIT_V(8); PG8_WAIT_L(0); PG8_BAR; PG8_MMA(1, 0, At, B0); PG8_MMA(1, 1, At, B1); PG8_BAR; PG8_SCHED;
;             PG8_LDB(B0, 1, 0); PG8_LDB(B1, 1, 1); PG8_SCHED; PG8_LDA(At, 1, 0); PG8_STAGE(PG8_SA(0, 1), a2 + hstepA, voffA);
;             PG8_WAIT_V(8); PG8_WAIT_L(0); PG8_BAR; PG8_MMA(0, 0, At, B0); PG8_MMA(0, 1, At, B1); PG8_BAR; PG8_SCHED;
	s_setprio 1
	s_waitcnt lgkmcnt(0)
	v_mfma_f32_16x16x32_bf16 v[60:63], v[128:131], v[198:201], v[60:63]
	v_mfma_f32_16x16x32_bf16 v[60:63], v[170:173], v[202:205], v[60:63]
	v_mfma_f32_16x16x32_bf16 v[44:47], v[128:131], v[206:209], v[44:47]
	v_mfma_f32_16x16x32_bf16 v[44:47], v[170:173], v[210:213], v[44:47]
	v_mfma_f32_16x16x32_bf16 v[28:31], v[128:131], v[214:217], v[28:31]
	v_mfma_f32_16x16x32_bf16 v[28:31], v[170:173], v[218:221], v[28:31]
	v_mfma_f32_16x16x32_bf16 v[12:15], v[128:131], v[222:225], v[12:15]
	v_mfma_f32_16x16x32_bf16 v[12:15], v[170:173], v[226:229], v[12:15]
	v_mfma_f32_16x16x32_bf16 v[56:59], v[174:177], v[198:201], v[56:59]
	v_mfma_f32_16x16x32_bf16 v[56:59], v[178:181], v[202:205], v[56:59]
	v_mfma_f32_16x16x32_bf16 v[40:43], v[174:177], v[206:209], v[40:43]
	v_mfma_f32_16x16x32_bf16 v[40:43], v[178:181], v[210:213], v[40:43]
	v_mfma_f32_16x16x32_bf16 v[24:27], v[174:177], v[214:217], v[24:27]
	v_mfma_f32_16x16x32_bf16 v[24:27], v[178:181], v[218:221], v[24:27]
	v_mfma_f32_16x16x32_bf16 v[8:11], v[174:177], v[222:225], v[8:11]
	v_mfma_f32_16x16x32_bf16 v[8:11], v[178:181], v[226:229], v[8:11]
	s_setprio 0
	s_setprio 1
	v_mfma_f32_16x16x32_bf16 v[52:55], v[182:185], v[198:201], v[52:55]
	v_mfma_f32_16x16x32_bf16 v[52:55], v[186:189], v[202:205], v[52:55]
	v_mfma_f32_16x16x32_bf16 v[36:39], v[182:185], v[206:209], v[36:39]
	v_mfma_f32_16x16x32_bf16 v[36:39], v[186:189], v[210:213], v[36:39]
	v_mfma_f32_16x16x32_bf16 v[20:23], v[182:185], v[214:217], v[20:23]
	v_mfma_f32_16x16x32_bf16 v[20:23], v[186:189], v[218:221], v[20:23]
	v_mfma_f32_16x16x32_bf16 v[4:7], v[182:185], v[222:225], v[4:7]
	v_mfma_f32_16x16x32_bf16 v[4:7], v[186:189], v[226:229], v[4:7]
	v_mfma_f32_16x16x32_bf16 v[48:51], v[190:193], v[198:201], v[48:51]
	v_mfma_f32_16x16x32_bf16 v[48:51], v[194:197], v[202:205], v[48:51]
	v_mfma_f32_16x16x32_bf16 v[32:35], v[190:193], v[206:209], v[32:35]
	v_mfma_f32_16x16x32_bf16 v[32:35], v[194:197], v[210:213], v[32:35]
	v_mfma_f32_16x16x32_bf16 v[16:19], v[190:193], v[214:217], v[16:19]
	v_mfma_f32_16x16x32_bf16 v[16:19], v[194:197], v[218:221], v[16:19]
	v_mfma_f32_16x16x32_bf16 v[0:3], v[190:193], v[222:225], v[0:3]
	v_mfma_f32_16x16x32_bf16 v[0:3], v[194:197], v[226:229], v[0:3]
	s_setprio 0
	s_barrier
	s_add_i32 s54, 0, 0x18000
	v_add_u32_e32 v140, s54, v145
	s_add_i32 s55, 0, 0x1c000
	ds_read_b128 v[128:131], v140
	ds_read_b128 v[170:173], v140 offset:1024
	ds_read_b128 v[174:177], v140 offset:2048
	ds_read_b128 v[178:181], v140 offset:3072
	v_add_u32_e32 v140, s55, v145
	ds_read_b128 v[182:185], v140
	ds_read_b128 v[186:189], v140 offset:1024
	ds_read_b128 v[190:193], v140 offset:2048
	ds_read_b128 v[194:197], v140 offset:3072
	s_add_u32 s20, s20, 0x84000
	s_addc_u32 s21, s21, 0
	s_mov_b32 m0, s37
	v_lshl_add_u64 v[234:235], s[20:21], 0, v[138:139]
	ds_read_b128 v[198:201], v162 offset:32768
	ds_read_b128 v[202:205], v162 offset:33792
	ds_read_b128 v[206:209], v162 offset:34816
	ds_read_b128 v[210:213], v162 offset:35840
	ds_read_b128 v[214:217], v162 offset:36864
	ds_read_b128 v[218:221], v162 offset:37888
	ds_read_b128 v[222:225], v162 offset:38912
	ds_read_b128 v[226:229], v162 offset:39936
	global_load_lds_dwordx4 v[234:235], off
	v_lshl_add_u64 v[234:235], s[20:21], 0, v[134:135]
	s_mov_b32 m0, s38
	s_nop 0
	global_load_lds_dwordx4 v[234:235], off
	s_waitcnt vmcnt(8)
	s_waitcnt lgkmcnt(0)
	s_barrier
	s_setprio 1
	s_waitcnt lgkmcnt(0)
	v_mfma_f32_16x16x32_bf16 v[124:127], v[128:131], v[198:201], v[124:127]
	v_mfma_f32_16x16x32_bf16 v[124:127], v[170:173], v[202:205], v[124:127]
	v_mfma_f32_16x16x32_bf16 v[108:111], v[128:131], v[206:209], v[108:111]
	v_mfma_f32_16x16x32_bf16 v[108:111], v[170:173], v[210:213], v[108:111]
	v_mfma_f32_16x16x32_bf16 v[92:95], v[128:131], v[214:217], v[92:95]
	v_mfma_f32_16x16x32_bf16 v[92:95], v[170:173], v[218:221], v[92:95]
	v_mfma_f32_16x16x32_bf16 v[76:79], v[128:131], v[222:225], v[76:79]
	v_mfma_f32_16x16x32_bf16 v[76:79], v[170:173], v[226:229], v[76:79]
	v_mfma_f32_16x16x32_bf16 v[120:123], v[174:177], v[198:201], v[120:123]
	v_mfma_f32_16x16x32_bf16 v[120:123], v[178:181], v[202:205], v[120:123]
	v_mfma_f32_16x16x32_bf16 v[104:107], v[174:177], v[206:209], v[104:107]
	v_mfma_f32_16x16x32_bf16 v[104:107], v[178:181], v[210:213], v[104:107]
	v_mfma_f32_16x16x32_bf16 v[88:91], v[174:177], v[214:217], v[88:91]
	v_mfma_f32_16x16x32_bf16 v[88:91], v[178:181], v[218:221], v[88:91]
	v_mfma_f32_16x16x32_bf16 v[72:75], v[174:177], v[222:225], v[72:75]
	v_mfma_f32_16x16x32_bf16 v[72:75], v[178:181], v[226:229], v[72:75]
	s_setprio 0
	s_setprio 1
	v_mfma_f32_16x16x32_bf16 v[116:119], v[182:185], v[198:201], v[116:119]
	v_mfma_f32_16x16x32_bf16 v[116:119], v[186:189], v[202:205], v[116:119]
	v_mfma_f32_16x16x32_bf16 v[100:103], v[182:185], v[206:209], v[100:103]
	v_mfma_f32_16x16x32_bf16 v[100:103], v[186:189], v[210:213], v[100:103]
	v_mfma_f32_16x16x32_bf16 v[84:87], v[182:185], v[214:217], v[84:87]
	v_mfma_f32_16x16x32_bf16 v[84:87], v[186:189], v[218:221], v[84:87]
	v_mfma_f32_16x16x32_bf16 v[68:71], v[182:185], v[222:225], v[68:71]
	v_mfma_f32_16x16x32_bf16 v[68:71], v[186:189], v[226:229], v[68:71]
	v_mfma_f32_16x16x32_bf16 v[112:115], v[190:193], v[198:201], v[112:115]
	v_mfma_f32_16x16x32_bf16 v[112:115], v[194:197], v[202:205], v[112:115]
	v_mfma_f32_16x16x32_bf16 v[96:99], v[190:193], v[206:209], v[96:99]
	v_mfma_f32_16x16x32_bf16 v[96:99], v[194:197], v[210:213], v[96:99]
	v_mfma_f32_16x16x32_bf16 v[80:83], v[190:193], v[214:217], v[80:83]
	v_mfma_f32_16x16x32_bf16 v[80:83], v[194:197], v[218:221], v[80:83]
	v_mfma_f32_16x16x32_bf16 v[64:67], v[190:193], v[222:225], v[64:67]
	v_mfma_f32_16x16x32_bf16 v[64:67], v[194:197], v[226:229], v[64:67]
	s_setprio 0
	s_barrier
; #define PG8_STAGE(bufoff, gbase, voff) do { _Pragma("unroll") for (int _i = 0; _i < 2; ++_i) \
;         __builtin_amdgcn_global_load_lds((const unsigned*)((const char*)(gbase) + (voff)[_i]), (LAS unsigned*)(lds + (bufoff) + ldsw + _i * 8192), 16, 0, 0); } while (0)
; #define PG8_LDA(dst, b, h) do { _Pragma("unroll") for (int m = 0; m < 4; ++m) _Pragma("unroll") for (int k = 0; k < 2; ++k) dst[m][k] = *(const LAS bf16x8*)(lds + PG8_SA(b, h) + aoff + m * 2048 + k * 1024); } while (0)
; #define PG8_MMA(ai, bj, At, Bt) do { __builtin_amdgcn_s_setprio(1); _Pragma("unroll") for (int m = 0; m < 4; ++m) _Pragma("unroll") for (int n = 0; n < 2; ++n) _Pragma("unroll") for (int k = 0; k < 2; ++k) \
;         acc[ai][bj][m][n] = __builtin_amdgcn_mfma_f32_16x16x32_bf16(Bt[n][k], At[m][k], acc[ai][bj][m][n], 0, 0, 0); __builtin_amdgcn_s_setprio(0); } while (0)
; #define PG8_WAIT_V(n) asm volatile("s_waitcnt vmcnt(" #n ")" ::: "memory")
; #define PG8_WAIT_L(n) asm volatile("s_waitcnt lgkmcnt(" #n ")" ::: "memory")
; #define PG8_BAR __builtin_amdgcn_s_barrier()
; #define PG8_SCHED __builtin_amdgcn_sched_barrier(0)
; template <class EpiT>
; __device__ __forceinline__ void gemm_phase(LAS unsigned char* lds, const Gemm g, const StaticOrder& S, const EpiT& E) {
;     ...
;             PG8_LDA(At, 1, 1); PG8_STAGE(PG8_SB(1, 0), b3, voffB); PG8_STAGE(PG8_SB(1, 1), b3 + hstepB, voffB); PG8_STAGE(PG8_SA(1, 0), a3, voffA);
;             PG8_WAIT_V(8); PG8_WAIT_L(0); PG8_BAR; PG8_MMA(1, 0, At, B0); PG8_MMA(1, 1, At, B1); PG8_BAR; PG8_SCHED;
;         }
;         if (wr == 0) PG8_BAR;
	s_add_i32 s20, s54, s25
	v_lshl_add_u64 v[158:159], v[158:159], 0, s[10:11]
	s_mov_b32 m0, s20
	ds_read_b128 v[198:201], v162 offset:49152
	ds_read_b128 v[202:205], v162 offset:50176
	ds_read_b128 v[206:209], v162 offset:51200
	ds_read_b128 v[210:213], v162 offset:52224
	ds_read_b128 v[214:217], v162 offset:53248
	ds_read_b128 v[218:221], v162 offset:54272
	ds_read_b128 v[222:225], v162 offset:55296
	ds_read_b128 v[226:229], v162 offset:56320
	global_load_lds_dwordx4 v[158:159], off
	s_add_i32 m0, s20, 0x2000
	s_add_u32 s18, s18, 0x84080
	v_lshl_add_u64 v[158:159], v[166:167], 0, s[10:11]
	s_addc_u32 s19, s19, 0
	s_add_i32 s20, s55, s25
	global_load_lds_dwordx4 v[158:159], off
	v_lshl_add_u64 v[158:159], s[18:19], 0, v[136:137]
	s_mov_b32 m0, s20
	s_nop 0
	global_load_lds_dwordx4 v[158:159], off
	v_lshl_add_u64 v[158:159], s[18:19], 0, v[132:133]
	s_add_i32 m0, s20, 0x2000
	s_nop 0
	global_load_lds_dwordx4 v[158:159], off
	v_lshl_add_u64 v[158:159], v[230:231], 0, s[10:11]
	s_mov_b32 m0, s40
	s_nop 0
	global_load_lds_dwordx4 v[158:159], off
	v_lshl_add_u64 v[158:159], v[232:233], 0, s[10:11]
	s_mov_b32 m0, s41
	s_nop 0
	global_load_lds_dwordx4 v[158:159], off
	s_waitcnt vmcnt(8)
	s_waitcnt lgkmcnt(0)
	s_barrier
	s_setprio 1
	s_waitcnt lgkmcnt(0)
	v_mfma_f32_16x16x32_bf16 v[60:63], v[128:131], v[198:201], v[60:63]
	v_mfma_f32_16x16x32_bf16 v[60:63], v[170:173], v[202:205], v[60:63]
	v_mfma_f32_16x16x32_bf16 v[44:47], v[128:131], v[206:209], v[44:47]
	v_mfma_f32_16x16x32_bf16 v[44:47], v[170:173], v[210:213], v[44:47]
	v_mfma_f32_16x16x32_bf16 v[28:31], v[128:131], v[214:217], v[28:31]
	v_mfma_f32_16x16x32_bf16 v[28:31], v[170:173], v[218:221], v[28:31]
	v_mfma_f32_16x16x32_bf16 v[12:15], v[128:131], v[222:225], v[12:15]
	v_mfma_f32_16x16x32_bf16 v[12:15], v[170:173], v[226:229], v[12:15]
	v_mfma_f32_16x16x32_bf16 v[56:59], v[174:177], v[198:201], v[56:59]
	v_mfma_f32_16x16x32_bf16 v[56:59], v[178:181], v[202:205], v[56:59]
	v_mfma_f32_16x16x32_bf16 v[40:43], v[174:177], v[206:209], v[40:43]
	v_mfma_f32_16x16x32_bf16 v[40:43], v[178:181], v[210:213], v[40:43]
	v_mfma_f32_16x16x32_bf16 v[24:27], v[174:177], v[214:217], v[24:27]
	v_mfma_f32_16x16x32_bf16 v[24:27], v[178:181], v[218:221], v[24:27]
	v_mfma_f32_16x16x32_bf16 v[8:11], v[174:177], v[222:225], v[8:11]
	v_mfma_f32_16x16x32_bf16 v[8:11], v[178:181], v[226:229], v[8:11]
	s_setprio 0
	s_setprio 1
	v_mfma_f32_16x16x32_bf16 v[52:55], v[182:185], v[198:201], v[52:55]
	v_mfma_f32_16x16x32_bf16 v[52:55], v[186:189], v[202:205], v[52:55]
	v_mfma_f32_16x16x32_bf16 v[36:39], v[182:185], v[206:209], v[36:39]
	v_mfma_f32_16x16x32_bf16 v[36:39], v[186:189], v[210:213], v[36:39]
	v_mfma_f32_16x16x32_bf16 v[20:23], v[182:185], v[214:217], v[20:23]
	v_mfma_f32_16x16x32_bf16 v[20:23], v[186:189], v[218:221], v[20:23]
	v_mfma_f32_16x16x32_bf16 v[4:7], v[182:185], v[222:225], v[4:7]
	v_mfma_f32_16x16x32_bf16 v[4:7], v[186:189], v[226:229], v[4:7]
	v_mfma_f32_16x16x32_bf16 v[48:51], v[190:193], v[198:201], v[48:51]
	v_mfma_f32_16x16x32_bf16 v[48:51], v[194:197], v[202:205], v[48:51]
	v_mfma_f32_16x16x32_bf16 v[32:35], v[190:193], v[206:209], v[32:35]
	v_mfma_f32_16x16x32_bf16 v[32:35], v[194:197], v[210:213], v[32:35]
	v_mfma_f32_16x16x32_bf16 v[16:19], v[190:193], v[214:217], v[16:19]
	v_mfma_f32_16x16x32_bf16 v[16:19], v[194:197], v[218:221], v[16:19]
	v_mfma_f32_16x16x32_bf16 v[0:3], v[190:193], v[222:225], v[0:3]
	v_mfma_f32_16x16x32_bf16 v[0:3], v[194:197], v[226:229], v[0:3]
	s_setprio 0
	s_barrier
	s_add_i32 s53, s53, 2
	s_add_u32 s16, s16, 0x100
	s_addc_u32 s17, s17, 0
	s_add_u32 s51, s51, 0x100
	s_addc_u32 s52, s52, 0
	s_cmp_gt_u32 s53, 29
	s_cbranch_scc0 .LBB0_100
	s_and_b64 vcc, exec, s[12:13]
	s_cbranch_vccz .LBB0_103
	s_barrier

; #define PG8_STAGE(bufoff, gbase, voff) do { _Pragma("unroll") for (int _i = 0; _i < 2; ++_i) \
;         __builtin_amdgcn_global_load_lds((const unsigned*)((const char*)(gbase) + (voff)[_i]), (LAS unsigned*)(lds + (bufoff) + ldsw + _i * 8192), 16, 0, 0); } while (0)
; #define PG8_LDA(dst, b, h) do { _Pragma("unroll") for (int m = 0; m < 4; ++m) _Pragma("unroll") for (int k = 0; k < 2; ++k) dst[m][k] = *(const LAS bf16x8*)(lds + PG8_SA(b, h) + aoff + m * 2048 + k * 1024); } while (0)
; #define PG8_LDB(dst, b, h) do { _Pragma("unroll") for (int n = 0; n < 2; ++n) _Pragma("unroll") for (int k = 0; k < 2; ++k) dst[n][k] = *(const LAS bf16x8*)(lds + PG8_SB(b, h) + boff + n * 2048 + k * 1024); } while (0)
; #define PG8_MMA(ai, bj, At, Bt) do { __builtin_amdgcn_s_setprio(1); _Pragma("unroll") for (int m = 0; m < 4; ++m) _Pragma("unroll") for (int n = 0; n < 2; ++n) _Pragma("unroll") for (int k = 0; k < 2; ++k) \
;         acc[ai][bj][m][n] = __builtin_amdgcn_mfma_f32_16x16x32_bf16(Bt[n][k], At[m][k], acc[ai][bj][m][n], 0, 0, 0); __builtin_amdgcn_s_setprio(0); } while (0)
; #define PG8_WAIT_V(n) asm volatile("s_waitcnt vmcnt(" #n ")" ::: "memory")
; #define PG8_WAIT_L(n) asm volatile("s_waitcnt lgkmcnt(" #n ")" ::: "memory")
; #define PG8_BAR __builtin_amdgcn_s_barrier()
; #define PG8_SCHED __builtin_amdgcn_sched_barrier(0)
; template <class EpiT>
; __device__ __forceinline__ void gemm_phase(LAS unsigned char* lds, const Gemm g, const StaticOrder& S, const EpiT& E) {
;     ...
;         for (int t = 0; t < nt; t += 2) {
;             const bool last = (t == nt - 2);
;             const char* a1 = cA + (size_t)(t + 1) * kstep;
;             const char* a2 = last ? nA : cA + (size_t)(t + 2) * kstep; const char* b2 = last ? nB : cB + (size_t)(t + 2) * kstep;
;             const char* a3 = a2 + kstep; const char* b3 = b2 + kstep;
;             PG8_LDB(B0, 0, 0); PG8_LDB(B1, 0, 1); PG8_SCHED; PG8_LDA(At, 0, 0); PG8_STAGE(PG8_SA(1, 1), a1 + hstepA, voffA);
;             PG8_WAIT_V(8); PG8_WAIT_L(0); PG8_BAR; PG8_MMA(0, 0, At, B0); PG8_MMA(0, 1, At, B1); PG8_BAR; PG8_SCHED;
;             PG8_LDA(At, 0, 1); PG8_STAGE(PG8_SB(0, 0), b2, voffB); PG8_STAGE(PG8_SB(0, 1), b2 + hstepB, voffB); PG8_STAGE(PG8_SA(0, 0), a2, voffA);
;             PG8_WAIT_V(8); PG8_WAIT_L(0); PG8_BAR; PG8_MMA(1, 0, At, B0); PG8_MMA(1, 1, At, B1); PG8_BAR; PG8_SCHED;
.LBB0_392:
	ds_read_b128 v[154:157], v149
	ds_read_b128 v[158:161], v149 offset:1024
	ds_read_b128 v[170:173], v149 offset:2048
	ds_read_b128 v[174:177], v149 offset:3072
	ds_read_b128 v[178:181], v150
	ds_read_b128 v[182:185], v150 offset:1024
	ds_read_b128 v[186:189], v150 offset:2048
	ds_read_b128 v[190:193], v150 offset:3072
	s_add_u32 s20, s18, 0xfff7c080
	s_addc_u32 s21, s19, -1
	s_cmp_eq_u32 s53, 28
	s_cselect_b32 s23, s5, s21
	s_cselect_b32 s22, s4, s20
	s_cselect_b32 s21, s17, s52
	s_cselect_b32 s20, s16, s51
	v_lshl_add_u64 v[162:163], s[18:19], 0, v[138:139]
	s_add_i32 m0, s35, 0xc000
	ds_read_b128 v[194:197], v151
	ds_read_b128 v[198:201], v151 offset:1024
	ds_read_b128 v[202:205], v151 offset:2048
	ds_read_b128 v[206:209], v151 offset:3072
	ds_read_b128 v[210:213], v151 offset:4096
	ds_read_b128 v[214:217], v151 offset:5120
	ds_read_b128 v[218:221], v151 offset:6144
	ds_read_b128 v[222:225], v151 offset:7168
	global_load_lds_dwordx4 v[162:163], off
	v_lshl_add_u64 v[162:163], s[18:19], 0, v[140:141]
	s_add_i32 m0, s35, 0xe000
	s_nop 0
	global_load_lds_dwordx4 v[162:163], off
	s_waitcnt vmcnt(8)
	s_waitcnt lgkmcnt(0)
	s_barrier
	s_setprio 1
	s_waitcnt lgkmcnt(0)
	v_mfma_f32_16x16x32_bf16 v[124:127], v[154:157], v[194:197], v[124:127]
	v_mfma_f32_16x16x32_bf16 v[124:127], v[158:161], v[198:201], v[124:127]
	v_mfma_f32_16x16x32_bf16 v[108:111], v[154:157], v[202:205], v[108:111]
	v_mfma_f32_16x16x32_bf16 v[108:111], v[158:161], v[206:209], v[108:111]
	v_mfma_f32_16x16x32_bf16 v[92:95], v[154:157], v[210:213], v[92:95]
	v_mfma_f32_16x16x32_bf16 v[92:95], v[158:161], v[214:217], v[92:95]
	v_mfma_f32_16x16x32_bf16 v[76:79], v[154:157], v[218:221], v[76:79]
	v_mfma_f32_16x16x32_bf16 v[76:79], v[158:161], v[222:225], v[76:79]
	v_mfma_f32_16x16x32_bf16 v[120:123], v[170:173], v[194:197], v[120:123]
	v_mfma_f32_16x16x32_bf16 v[120:123], v[174:177], v[198:201], v[120:123]
	v_mfma_f32_16x16x32_bf16 v[104:107], v[170:173], v[202:205], v[104:107]
	v_mfma_f32_16x16x32_bf16 v[104:107], v[174:177], v[206:209], v[104:107]
	v_mfma_f32_16x16x32_bf16 v[88:91], v[170:173], v[210:213], v[88:91]
	v_mfma_f32_16x16x32_bf16 v[88:91], v[174:177], v[214:217], v[88:91]
	v_mfma_f32_16x16x32_bf16 v[72:75], v[170:173], v[218:221], v[72:75]
	v_mfma_f32_16x16x32_bf16 v[72:75], v[174:177], v[222:225], v[72:75]
	s_setprio 0
	s_setprio 1
	v_mfma_f32_16x16x32_bf16 v[116:119], v[178:181], v[194:197], v[116:119]
	v_mfma_f32_16x16x32_bf16 v[116:119], v[182:185], v[198:201], v[116:119]
	v_mfma_f32_16x16x32_bf16 v[100:103], v[178:181], v[202:205], v[100:103]
	v_mfma_f32_16x16x32_bf16 v[100:103], v[182:185], v[206:209], v[100:103]
	v_mfma_f32_16x16x32_bf16 v[84:87], v[178:181], v[210:213], v[84:87]
	v_mfma_f32_16x16x32_bf16 v[84:87], v[182:185], v[214:217], v[84:87]
	v_mfma_f32_16x16x32_bf16 v[68:71], v[178:181], v[218:221], v[68:71]
	v_mfma_f32_16x16x32_bf16 v[68:71], v[182:185], v[222:225], v[68:71]
	v_mfma_f32_16x16x32_bf16 v[112:115], v[186:189], v[194:197], v[112:115]
	v_mfma_f32_16x16x32_bf16 v[112:115], v[190:193], v[198:201], v[112:115]
	v_mfma_f32_16x16x32_bf16 v[96:99], v[186:189], v[202:205], v[96:99]
	v_mfma_f32_16x16x32_bf16 v[96:99], v[190:193], v[206:209], v[96:99]
	v_mfma_f32_16x16x32_bf16 v[80:83], v[186:189], v[210:213], v[80:83]
	v_mfma_f32_16x16x32_bf16 v[80:83], v[190:193], v[214:217], v[80:83]
	v_mfma_f32_16x16x32_bf16 v[64:67], v[186:189], v[218:221], v[64:67]
	v_mfma_f32_16x16x32_bf16 v[64:67], v[190:193], v[222:225], v[64:67]
	s_setprio 0
	s_barrier
	s_add_i32 s54, s44, s33
	v_lshl_add_u64 v[162:163], s[20:21], 0, v[130:131]
	s_mov_b32 m0, s54
	ds_read_b128 v[194:197], v151 offset:16384
	ds_read_b128 v[198:201], v151 offset:17408
	ds_read_b128 v[202:205], v151 offset:18432
	ds_read_b128 v[206:209], v151 offset:19456
	ds_read_b128 v[210:213], v151 offset:20480
	ds_read_b128 v[214:217], v151 offset:21504
	ds_read_b128 v[218:221], v151 offset:22528
	ds_read_b128 v[222:225], v151 offset:23552
	global_load_lds_dwordx4 v[162:163], off
	s_add_i32 m0, s54, 0x2000
	s_add_u32 s54, s20, 0x84000
	v_lshl_add_u64 v[166:167], s[20:21], 0, v[134:135]
	s_addc_u32 s55, s21, 0
	s_add_i32 s56, s45, s33
	global_load_lds_dwordx4 v[166:167], off
	v_lshl_add_u64 v[226:227], s[54:55], 0, v[130:131]
	s_mov_b32 m0, s56
	v_lshl_add_u64 v[228:229], s[22:23], 0, v[132:133]
	global_load_lds_dwordx4 v[226:227], off
	v_lshl_add_u64 v[226:227], s[54:55], 0, v[134:135]
	s_add_i32 m0, s56, 0x2000
	s_nop 0
	global_load_lds_dwordx4 v[226:227], off
	v_lshl_add_u64 v[226:227], s[22:23], 0, v[128:129]
	s_mov_b32 m0, s35
	s_nop 0
	global_load_lds_dwordx4 v[226:227], off
	s_mov_b32 m0, s36
	s_nop 0
	global_load_lds_dwordx4 v[228:229], off
	s_waitcnt vmcnt(8)
	s_waitcnt lgkmcnt(0)
	s_barrier
; #define PG8_STAGE(bufoff, gbase, voff) do { _Pragma("unroll") for (int _i = 0; _i < 2; ++_i) \
;         __builtin_amdgcn_global_load_lds((const unsigned*)((const char*)(gbase) + (voff)[_i]), (LAS unsigned*)(lds + (bufoff) + ldsw + _i * 8192), 16, 0, 0); } while (0)
; #define PG8_LDA(dst, b, h) do { _Pragma("unroll") for (int m = 0; m < 4; ++m) _Pragma("unroll") for (int k = 0; k < 2; ++k) dst[m][k] = *(const LAS bf16x8*)(lds + PG8_SA(b, h) + aoff + m * 2048 + k * 1024); } while (0)
; #define PG8_LDB(dst, b, h) do { _Pragma("unroll") for (int n = 0; n < 2; ++n) _Pragma("unroll") for (int k = 0; k < 2; ++k) dst[n][k] = *(const LAS bf16x8*)(lds + PG8_SB(b, h) + boff + n * 2048 + k * 1024); } while (0)
; #define PG8_MMA(ai, bj, At, Bt) do { __builtin_amdgcn_s_setprio(1); _Pragma("unroll") for (int m = 0; m < 4; ++m) _Pragma("unroll") for (int n = 0; n < 2; ++n) _Pragma("unroll") for (int k = 0; k < 2; ++k) \
;         acc[ai][bj][m][n] = __builtin_amdgcn_mfma_f32_16x16x32_bf16(Bt[n][k], At[m][k], acc[ai][bj][m][n], 0, 0, 0); __builtin_amdgcn_s_setprio(0); } while (0)
; #define PG8_WAIT_V(n) asm volatile("s_waitcnt vmcnt(" #n ")" ::: "memory")
; #define PG8_WAIT_L(n) asm volatile("s_waitcnt lgkmcnt(" #n ")" ::: "memory")
; #define PG8_BAR __builtin_amdgcn_s_barrier()
; #define PG8_SCHED __builtin_amdgcn_sched_barrier(0)
; template <class EpiT>
; __device__ __forceinline__ void gemm_phase(LAS unsigned char* lds, const Gemm g, const StaticOrder& S, const EpiT& E) {
;     ...
;             PG8_WAIT_V(8); PG8_WAIT_L(0); PG8_BAR; PG8_MMA(1, 0, At, B0); PG8_MMA(1, 1, At, B1); PG8_BAR; PG8_SCHED;
;             PG8_LDB(B0, 1, 0); PG8_LDB(B1, 1, 1); PG8_SCHED; PG8_LDA(At, 1, 0); PG8_STAGE(PG8_SA(0, 1), a2 + hstepA, voffA);
;             PG8_WAIT_V(8); PG8_WAIT_L(0); PG8_BAR; PG8_MMA(0, 0, At, B0); PG8_MMA(0, 1, At, B1); PG8_BAR; PG8_SCHED;
	s_setprio 1
	s_waitcnt lgkmcnt(0)
	v_mfma_f32_16x16x32_bf16 v[60:63], v[154:157], v[194:197], v[60:63]
	v_mfma_f32_16x16x32_bf16 v[60:63], v[158:161], v[198:201], v[60:63]
	v_mfma_f32_16x16x32_bf16 v[44:47], v[154:157], v[202:205], v[44:47]
	v_mfma_f32_16x16x32_bf16 v[44:47], v[158:161], v[206:209], v[44:47]
	v_mfma_f32_16x16x32_bf16 v[28:31], v[154:157], v[210:213], v[28:31]
	v_mfma_f32_16x16x32_bf16 v[28:31], v[158:161], v[214:217], v[28:31]
	v_mfma_f32_16x16x32_bf16 v[12:15], v[154:157], v[218:221], v[12:15]
	v_mfma_f32_16x16x32_bf16 v[12:15], v[158:161], v[222:225], v[12:15]
	v_mfma_f32_16x16x32_bf16 v[56:59], v[170:173], v[194:197], v[56:59]
	v_mfma_f32_16x16x32_bf16 v[56:59], v[174:177], v[198:201], v[56:59]
	v_mfma_f32_16x16x32_bf16 v[40:43], v[170:173], v[202:205], v[40:43]
	v_mfma_f32_16x16x32_bf16 v[40:43], v[174:177], v[206:209], v[40:43]
	v_mfma_f32_16x16x32_bf16 v[24:27], v[170:173], v[210:213], v[24:27]
	v_mfma_f32_16x16x32_bf16 v[24:27], v[174:177], v[214:217], v[24:27]
	v_mfma_f32_16x16x32_bf16 v[8:11], v[170:173], v[218:221], v[8:11]
	v_mfma_f32_16x16x32_bf16 v[8:11], v[174:177], v[222:225], v[8:11]
	s_setprio 0
	s_setprio 1
	v_mfma_f32_16x16x32_bf16 v[52:55], v[178:181], v[194:197], v[52:55]
	v_mfma_f32_16x16x32_bf16 v[52:55], v[182:185], v[198:201], v[52:55]
	v_mfma_f32_16x16x32_bf16 v[36:39], v[178:181], v[202:205], v[36:39]
	v_mfma_f32_16x16x32_bf16 v[36:39], v[182:185], v[206:209], v[36:39]
	v_mfma_f32_16x16x32_bf16 v[20:23], v[178:181], v[210:213], v[20:23]
	v_mfma_f32_16x16x32_bf16 v[20:23], v[182:185], v[214:217], v[20:23]
	v_mfma_f32_16x16x32_bf16 v[4:7], v[178:181], v[218:221], v[4:7]
	v_mfma_f32_16x16x32_bf16 v[4:7], v[182:185], v[222:225], v[4:7]
	v_mfma_f32_16x16x32_bf16 v[48:51], v[186:189], v[194:197], v[48:51]
	v_mfma_f32_16x16x32_bf16 v[48:51], v[190:193], v[198:201], v[48:51]
	v_mfma_f32_16x16x32_bf16 v[32:35], v[186:189], v[202:205], v[32:35]
	v_mfma_f32_16x16x32_bf16 v[32:35], v[190:193], v[206:209], v[32:35]
	v_mfma_f32_16x16x32_bf16 v[16:19], v[186:189], v[210:213], v[16:19]
	v_mfma_f32_16x16x32_bf16 v[16:19], v[190:193], v[214:217], v[16:19]
	v_mfma_f32_16x16x32_bf16 v[0:3], v[186:189], v[218:221], v[0:3]
	v_mfma_f32_16x16x32_bf16 v[0:3], v[190:193], v[222:225], v[0:3]
	s_setprio 0
	s_barrier
	s_add_i32 s54, 0, 0x18000
	v_add_u32_e32 v153, s54, v146
	s_add_i32 s55, 0, 0x1c000
	ds_read_b128 v[154:157], v153
	ds_read_b128 v[158:161], v153 offset:1024
	ds_read_b128 v[170:173], v153 offset:2048
	ds_read_b128 v[174:177], v153 offset:3072
	v_add_u32_e32 v153, s55, v146
	ds_read_b128 v[178:181], v153
	ds_read_b128 v[182:185], v153 offset:1024
	ds_read_b128 v[186:189], v153 offset:2048
	ds_read_b128 v[190:193], v153 offset:3072
	s_add_u32 s22, s22, 0x84000
	s_addc_u32 s23, s23, 0
	s_mov_b32 m0, s37
	v_lshl_add_u64 v[230:231], s[22:23], 0, v[128:129]
	ds_read_b128 v[194:197], v151 offset:32768
	ds_read_b128 v[198:201], v151 offset:33792
	ds_read_b128 v[202:205], v151 offset:34816
	ds_read_b128 v[206:209], v151 offset:35840
	ds_read_b128 v[210:213], v151 offset:36864
	ds_read_b128 v[214:217], v151 offset:37888
	ds_read_b128 v[218:221], v151 offset:38912
	ds_read_b128 v[222:225], v151 offset:39936
	global_load_lds_dwordx4 v[230:231], off
	v_lshl_add_u64 v[230:231], s[22:23], 0, v[132:133]
	s_mov_b32 m0, s38
	s_nop 0
	global_load_lds_dwordx4 v[230:231], off
	s_waitcnt vmcnt(8)
	s_waitcnt lgkmcnt(0)
	s_barrier
	s_setprio 1
	s_waitcnt lgkmcnt(0)
	v_mfma_f32_16x16x32_bf16 v[124:127], v[154:157], v[194:197], v[124:127]
	v_mfma_f32_16x16x32_bf16 v[124:127], v[158:161], v[198:201], v[124:127]
	v_mfma_f32_16x16x32_bf16 v[108:111], v[154:157], v[202:205], v[108:111]
	v_mfma_f32_16x16x32_bf16 v[108:111], v[158:161], v[206:209], v[108:111]
	v_mfma_f32_16x16x32_bf16 v[92:95], v[154:157], v[210:213], v[92:95]
	v_mfma_f32_16x16x32_bf16 v[92:95], v[158:161], v[214:217], v[92:95]
	v_mfma_f32_16x16x32_bf16 v[76:79], v[154:157], v[218:221], v[76:79]
	v_mfma_f32_16x16x32_bf16 v[76:79], v[158:161], v[222:225], v[76:79]
	v_mfma_f32_16x16x32_bf16 v[120:123], v[170:173], v[194:197], v[120:123]
	v_mfma_f32_16x16x32_bf16 v[120:123], v[174:177], v[198:201], v[120:123]
	v_mfma_f32_16x16x32_bf16 v[104:107], v[170:173], v[202:205], v[104:107]
	v_mfma_f32_16x16x32_bf16 v[104:107], v[174:177], v[206:209], v[104:107]
	v_mfma_f32_16x16x32_bf16 v[88:91], v[170:173], v[210:213], v[88:91]
	v_mfma_f32_16x16x32_bf16 v[88:91], v[174:177], v[214:217], v[88:91]
	v_mfma_f32_16x16x32_bf16 v[72:75], v[170:173], v[218:221], v[72:75]
	v_mfma_f32_16x16x32_bf16 v[72:75], v[174:177], v[222:225], v[72:75]
	s_setprio 0
	s_setprio 1
	v_mfma_f32_16x16x32_bf16 v[116:119], v[178:181], v[194:197], v[116:119]
	v_mfma_f32_16x16x32_bf16 v[116:119], v[182:185], v[198:201], v[116:119]
	v_mfma_f32_16x16x32_bf16 v[100:103], v[178:181], v[202:205], v[100:103]
	v_mfma_f32_16x16x32_bf16 v[100:103], v[182:185], v[206:209], v[100:103]
	v_mfma_f32_16x16x32_bf16 v[84:87], v[178:181], v[210:213], v[84:87]
	v_mfma_f32_16x16x32_bf16 v[84:87], v[182:185], v[214:217], v[84:87]
	v_mfma_f32_16x16x32_bf16 v[68:71], v[178:181], v[218:221], v[68:71]
	v_mfma_f32_16x16x32_bf16 v[68:71], v[182:185], v[222:225], v[68:71]
	v_mfma_f32_16x16x32_bf16 v[112:115], v[186:189], v[194:197], v[112:115]
	v_mfma_f32_16x16x32_bf16 v[112:115], v[190:193], v[198:201], v[112:115]
	v_mfma_f32_16x16x32_bf16 v[96:99], v[186:189], v[202:205], v[96:99]
	v_mfma_f32_16x16x32_bf16 v[96:99], v[190:193], v[206:209], v[96:99]
	v_mfma_f32_16x16x32_bf16 v[80:83], v[186:189], v[210:213], v[80:83]
	v_mfma_f32_16x16x32_bf16 v[80:83], v[190:193], v[214:217], v[80:83]
	v_mfma_f32_16x16x32_bf16 v[64:67], v[186:189], v[218:221], v[64:67]
	v_mfma_f32_16x16x32_bf16 v[64:67], v[190:193], v[222:225], v[64:67]
	s_setprio 0
	s_barrier
; #define PG8_STAGE(bufoff, gbase, voff) do { _Pragma("unroll") for (int _i = 0; _i < 2; ++_i) \
;         __builtin_amdgcn_global_load_lds((const unsigned*)((const char*)(gbase) + (voff)[_i]), (LAS unsigned*)(lds + (bufoff) + ldsw + _i * 8192), 16, 0, 0); } while (0)
; #define PG8_LDA(dst, b, h) do { _Pragma("unroll") for (int m = 0; m < 4; ++m) _Pragma("unroll") for (int k = 0; k < 2; ++k) dst[m][k] = *(const LAS bf16x8*)(lds + PG8_SA(b, h) + aoff + m * 2048 + k * 1024); } while (0)
; #define PG8_MMA(ai, bj, At, Bt) do { __builtin_amdgcn_s_setprio(1); _Pragma("unroll") for (int m = 0; m < 4; ++m) _Pragma("unroll") for (int n = 0; n < 2; ++n) _Pragma("unroll") for (int k = 0; k < 2; ++k) \
;         acc[ai][bj][m][n] = __builtin_amdgcn_mfma_f32_16x16x32_bf16(Bt[n][k], At[m][k], acc[ai][bj][m][n], 0, 0, 0); __builtin_amdgcn_s_setprio(0); } while (0)
; #define PG8_WAIT_V(n) asm volatile("s_waitcnt vmcnt(" #n ")" ::: "memory")
; #define PG8_WAIT_L(n) asm volatile("s_waitcnt lgkmcnt(" #n ")" ::: "memory")
; #define PG8_BAR __builtin_amdgcn_s_barrier()
; #define PG8_SCHED __builtin_amdgcn_sched_barrier(0)
; template <class EpiT>
; __device__ __forceinline__ void gemm_phase(LAS unsigned char* lds, const Gemm g, const StaticOrder& S, const EpiT& E) {
;     ...
;             PG8_LDA(At, 1, 1); PG8_STAGE(PG8_SB(1, 0), b3, voffB); PG8_STAGE(PG8_SB(1, 1), b3 + hstepB, voffB); PG8_STAGE(PG8_SA(1, 0), a3, voffA);
;             PG8_WAIT_V(8); PG8_WAIT_L(0); PG8_BAR; PG8_MMA(1, 0, At, B0); PG8_MMA(1, 1, At, B1); PG8_BAR; PG8_SCHED;
;         }
;         if (wr == 0) PG8_BAR;
	s_add_i32 s22, s54, s33
	v_lshl_add_u64 v[162:163], v[162:163], 0, s[12:13]
	s_mov_b32 m0, s22
	ds_read_b128 v[194:197], v151 offset:49152
	ds_read_b128 v[198:201], v151 offset:50176
	ds_read_b128 v[202:205], v151 offset:51200
	ds_read_b128 v[206:209], v151 offset:52224
	ds_read_b128 v[210:213], v151 offset:53248
	ds_read_b128 v[214:217], v151 offset:54272
	ds_read_b128 v[218:221], v151 offset:55296
	ds_read_b128 v[222:225], v151 offset:56320
	global_load_lds_dwordx4 v[162:163], off
	s_add_i32 m0, s22, 0x2000
	s_add_u32 s20, s20, 0x84080
	v_lshl_add_u64 v[162:163], v[166:167], 0, s[12:13]
	s_addc_u32 s21, s21, 0
	s_add_i32 s22, s55, s33
	global_load_lds_dwordx4 v[162:163], off
	v_lshl_add_u64 v[162:163], s[20:21], 0, v[130:131]
	s_mov_b32 m0, s22
	s_nop 0
	global_load_lds_dwordx4 v[162:163], off
	v_lshl_add_u64 v[162:163], s[20:21], 0, v[134:135]
	s_add_i32 m0, s22, 0x2000
	s_nop 0
	global_load_lds_dwordx4 v[162:163], off
	v_lshl_add_u64 v[162:163], v[226:227], 0, s[12:13]
	s_mov_b32 m0, s40
	s_nop 0
	global_load_lds_dwordx4 v[162:163], off
	v_lshl_add_u64 v[162:163], v[228:229], 0, s[12:13]
	s_mov_b32 m0, s41
	s_nop 0
	global_load_lds_dwordx4 v[162:163], off
	s_waitcnt vmcnt(8)
	s_waitcnt lgkmcnt(0)
	s_barrier
	s_setprio 1
	s_waitcnt lgkmcnt(0)
	v_mfma_f32_16x16x32_bf16 v[60:63], v[154:157], v[194:197], v[60:63]
	v_mfma_f32_16x16x32_bf16 v[60:63], v[158:161], v[198:201], v[60:63]
	v_mfma_f32_16x16x32_bf16 v[44:47], v[154:157], v[202:205], v[44:47]
	v_mfma_f32_16x16x32_bf16 v[44:47], v[158:161], v[206:209], v[44:47]
	v_mfma_f32_16x16x32_bf16 v[28:31], v[154:157], v[210:213], v[28:31]
	v_mfma_f32_16x16x32_bf16 v[28:31], v[158:161], v[214:217], v[28:31]
	v_mfma_f32_16x16x32_bf16 v[12:15], v[154:157], v[218:221], v[12:15]
	v_mfma_f32_16x16x32_bf16 v[12:15], v[158:161], v[222:225], v[12:15]
	v_mfma_f32_16x16x32_bf16 v[56:59], v[170:173], v[194:197], v[56:59]
	v_mfma_f32_16x16x32_bf16 v[56:59], v[174:177], v[198:201], v[56:59]
	v_mfma_f32_16x16x32_bf16 v[40:43], v[170:173], v[202:205], v[40:43]
	v_mfma_f32_16x16x32_bf16 v[40:43], v[174:177], v[206:209], v[40:43]
	v_mfma_f32_16x16x32_bf16 v[24:27], v[170:173], v[210:213], v[24:27]
	v_mfma_f32_16x16x32_bf16 v[24:27], v[174:177], v[214:217], v[24:27]
	v_mfma_f32_16x16x32_bf16 v[8:11], v[170:173], v[218:221], v[8:11]
	v_mfma_f32_16x16x32_bf16 v[8:11], v[174:177], v[222:225], v[8:11]
	s_setprio 0
	s_setprio 1
	v_mfma_f32_16x16x32_bf16 v[52:55], v[178:181], v[194:197], v[52:55]
	v_mfma_f32_16x16x32_bf16 v[52:55], v[182:185], v[198:201], v[52:55]
	v_mfma_f32_16x16x32_bf16 v[36:39], v[178:181], v[202:205], v[36:39]
	v_mfma_f32_16x16x32_bf16 v[36:39], v[182:185], v[206:209], v[36:39]
	v_mfma_f32_16x16x32_bf16 v[20:23], v[178:181], v[210:213], v[20:23]
	v_mfma_f32_16x16x32_bf16 v[20:23], v[182:185], v[214:217], v[20:23]
	v_mfma_f32_16x16x32_bf16 v[4:7], v[178:181], v[218:221], v[4:7]
	v_mfma_f32_16x16x32_bf16 v[4:7], v[182:185], v[222:225], v[4:7]
	v_mfma_f32_16x16x32_bf16 v[48:51], v[186:189], v[194:197], v[48:51]
	v_mfma_f32_16x16x32_bf16 v[48:51], v[190:193], v[198:201], v[48:51]
	v_mfma_f32_16x16x32_bf16 v[32:35], v[186:189], v[202:205], v[32:35]
	v_mfma_f32_16x16x32_bf16 v[32:35], v[190:193], v[206:209], v[32:35]
	v_mfma_f32_16x16x32_bf16 v[16:19], v[186:189], v[210:213], v[16:19]
	v_mfma_f32_16x16x32_bf16 v[16:19], v[190:193], v[214:217], v[16:19]
	v_mfma_f32_16x16x32_bf16 v[0:3], v[186:189], v[218:221], v[0:3]
	v_mfma_f32_16x16x32_bf16 v[0:3], v[190:193], v[222:225], v[0:3]
	s_setprio 0
	s_barrier
	s_add_i32 s53, s53, 2
	s_add_u32 s18, s18, 0x100
	s_addc_u32 s19, s19, 0
	s_add_u32 s51, s51, 0x100
	s_addc_u32 s52, s52, 0
	s_cmp_gt_u32 s53, 29
	s_cbranch_scc0 .LBB0_392
	s_and_b64 vcc, exec, s[14:15]
	s_cbranch_vccz .LBB0_395
	s_barrier

; #define PG8_STAGE(bufoff, gbase, voff) do { _Pragma("unroll") for (int _i = 0; _i < 2; ++_i) \
;         __builtin_amdgcn_global_load_lds((const unsigned*)((const char*)(gbase) + (voff)[_i]), (LAS unsigned*)(lds + (bufoff) + ldsw + _i * 8192), 16, 0, 0); } while (0)
; #define PG8_LDA(dst, b, h) do { _Pragma("unroll") for (int m = 0; m < 4; ++m) _Pragma("unroll") for (int k = 0; k < 2; ++k) dst[m][k] = *(const LAS bf16x8*)(lds + PG8_SA(b, h) + aoff + m * 2048 + k * 1024); } while (0)
; #define PG8_LDB(dst, b, h) do { _Pragma("unroll") for (int n = 0; n < 2; ++n) _Pragma("unroll") for (int k = 0; k < 2; ++k) dst[n][k] = *(const LAS bf16x8*)(lds + PG8_SB(b, h) + boff + n * 2048 + k * 1024); } while (0)
; #define PG8_MMA(ai, bj, At, Bt) do { __builtin_amdgcn_s_setprio(1); _Pragma("unroll") for (int m = 0; m < 4; ++m) _Pragma("unroll") for (int n = 0; n < 2; ++n) _Pragma("unroll") for (int k = 0; k < 2; ++k) \
;         acc[ai][bj][m][n] = __builtin_amdgcn_mfma_f32_16x16x32_bf16(Bt[n][k], At[m][k], acc[ai][bj][m][n], 0, 0, 0); __builtin_amdgcn_s_setprio(0); } while (0)
; #define PG8_WAIT_V(n) asm volatile("s_waitcnt vmcnt(" #n ")" ::: "memory")
; #define PG8_WAIT_L(n) asm volatile("s_waitcnt lgkmcnt(" #n ")" ::: "memory")
; #define PG8_BAR __builtin_amdgcn_s_barrier()
; #define PG8_SCHED __builtin_amdgcn_sched_barrier(0)
; template <class EpiT>
; __device__ __forceinline__ void gemm_phase(LAS unsigned char* lds, const Gemm g, const StaticOrder& S, const EpiT& E) {
;     ...
;         for (int t = 0; t < nt; t += 2) {
;             const bool last = (t == nt - 2);
;             const char* a1 = cA + (size_t)(t + 1) * kstep;
;             const char* a2 = last ? nA : cA + (size_t)(t + 2) * kstep; const char* b2 = last ? nB : cB + (size_t)(t + 2) * kstep;
;             const char* a3 = a2 + kstep; const char* b3 = b2 + kstep;
;             PG8_LDB(B0, 0, 0); PG8_LDB(B1, 0, 1); PG8_SCHED; PG8_LDA(At, 0, 0); PG8_STAGE(PG8_SA(1, 1), a1 + hstepA, voffA);
;             PG8_WAIT_V(8); PG8_WAIT_L(0); PG8_BAR; PG8_MMA(0, 0, At, B0); PG8_MMA(0, 1, At, B1); PG8_BAR; PG8_SCHED;
;             PG8_LDA(At, 0, 1); PG8_STAGE(PG8_SB(0, 0), b2, voffB); PG8_STAGE(PG8_SB(0, 1), b2 + hstepB, voffB); PG8_STAGE(PG8_SA(0, 0), a2, voffA);
;             PG8_WAIT_V(8); PG8_WAIT_L(0); PG8_BAR; PG8_MMA(1, 0, At, B0); PG8_MMA(1, 1, At, B1); PG8_BAR; PG8_SCHED;
.LBB0_516:
	ds_read_b128 v[154:157], v150
	ds_read_b128 v[158:161], v150 offset:1024
	ds_read_b128 v[170:173], v150 offset:2048
	ds_read_b128 v[174:177], v150 offset:3072
	ds_read_b128 v[178:181], v151
	ds_read_b128 v[182:185], v151 offset:1024
	ds_read_b128 v[186:189], v151 offset:2048
	ds_read_b128 v[190:193], v151 offset:3072
	s_add_u32 s18, s16, 0xfff7c080
	s_addc_u32 s19, s17, -1
	s_cmp_eq_u32 s53, 28
	s_cselect_b32 s21, s3, s19
	s_cselect_b32 s20, s2, s18
	s_cselect_b32 s19, s15, s52
	s_cselect_b32 s18, s14, s51
	v_lshl_add_u64 v[144:145], s[16:17], 0, v[136:137]
	s_add_i32 m0, s36, 0xc000
	ds_read_b128 v[194:197], v152
	ds_read_b128 v[198:201], v152 offset:1024
	ds_read_b128 v[202:205], v152 offset:2048
	ds_read_b128 v[206:209], v152 offset:3072
	ds_read_b128 v[210:213], v152 offset:4096
	ds_read_b128 v[214:217], v152 offset:5120
	ds_read_b128 v[218:221], v152 offset:6144
	ds_read_b128 v[222:225], v152 offset:7168
	global_load_lds_dwordx4 v[144:145], off
	v_lshl_add_u64 v[144:145], s[16:17], 0, v[138:139]
	s_add_i32 m0, s36, 0xe000
	s_nop 0
	global_load_lds_dwordx4 v[144:145], off
	s_waitcnt vmcnt(8)
	s_waitcnt lgkmcnt(0)
	s_barrier
	s_setprio 1
	s_waitcnt lgkmcnt(0)
	v_mfma_f32_16x16x32_bf16 v[124:127], v[154:157], v[194:197], v[124:127]
	v_mfma_f32_16x16x32_bf16 v[124:127], v[158:161], v[198:201], v[124:127]
	v_mfma_f32_16x16x32_bf16 v[108:111], v[154:157], v[202:205], v[108:111]
	v_mfma_f32_16x16x32_bf16 v[108:111], v[158:161], v[206:209], v[108:111]
	v_mfma_f32_16x16x32_bf16 v[92:95], v[154:157], v[210:213], v[92:95]
	v_mfma_f32_16x16x32_bf16 v[92:95], v[158:161], v[214:217], v[92:95]
	v_mfma_f32_16x16x32_bf16 v[76:79], v[154:157], v[218:221], v[76:79]
	v_mfma_f32_16x16x32_bf16 v[76:79], v[158:161], v[222:225], v[76:79]
	v_mfma_f32_16x16x32_bf16 v[120:123], v[170:173], v[194:197], v[120:123]
	v_mfma_f32_16x16x32_bf16 v[120:123], v[174:177], v[198:201], v[120:123]
	v_mfma_f32_16x16x32_bf16 v[104:107], v[170:173], v[202:205], v[104:107]
	v_mfma_f32_16x16x32_bf16 v[104:107], v[174:177], v[206:209], v[104:107]
	v_mfma_f32_16x16x32_bf16 v[88:91], v[170:173], v[210:213], v[88:91]
	v_mfma_f32_16x16x32_bf16 v[88:91], v[174:177], v[214:217], v[88:91]
	v_mfma_f32_16x16x32_bf16 v[72:75], v[170:173], v[218:221], v[72:75]
	v_mfma_f32_16x16x32_bf16 v[72:75], v[174:177], v[222:225], v[72:75]
	s_setprio 0
	s_setprio 1
	v_mfma_f32_16x16x32_bf16 v[116:119], v[178:181], v[194:197], v[116:119]
	v_mfma_f32_16x16x32_bf16 v[116:119], v[182:185], v[198:201], v[116:119]
	v_mfma_f32_16x16x32_bf16 v[100:103], v[178:181], v[202:205], v[100:103]
	v_mfma_f32_16x16x32_bf16 v[100:103], v[182:185], v[206:209], v[100:103]
	v_mfma_f32_16x16x32_bf16 v[84:87], v[178:181], v[210:213], v[84:87]
	v_mfma_f32_16x16x32_bf16 v[84:87], v[182:185], v[214:217], v[84:87]
	v_mfma_f32_16x16x32_bf16 v[68:71], v[178:181], v[218:221], v[68:71]
	v_mfma_f32_16x16x32_bf16 v[68:71], v[182:185], v[222:225], v[68:71]
	v_mfma_f32_16x16x32_bf16 v[112:115], v[186:189], v[194:197], v[112:115]
	v_mfma_f32_16x16x32_bf16 v[112:115], v[190:193], v[198:201], v[112:115]
	v_mfma_f32_16x16x32_bf16 v[96:99], v[186:189], v[202:205], v[96:99]
	v_mfma_f32_16x16x32_bf16 v[96:99], v[190:193], v[206:209], v[96:99]
	v_mfma_f32_16x16x32_bf16 v[80:83], v[186:189], v[210:213], v[80:83]
	v_mfma_f32_16x16x32_bf16 v[80:83], v[190:193], v[214:217], v[80:83]
	v_mfma_f32_16x16x32_bf16 v[64:67], v[186:189], v[218:221], v[64:67]
	v_mfma_f32_16x16x32_bf16 v[64:67], v[190:193], v[222:225], v[64:67]
	s_setprio 0
	s_barrier
	s_add_i32 s54, s44, s27
	v_lshl_add_u64 v[144:145], s[18:19], 0, v[132:133]
	s_mov_b32 m0, s54
	ds_read_b128 v[194:197], v152 offset:16384
	ds_read_b128 v[198:201], v152 offset:17408
	ds_read_b128 v[202:205], v152 offset:18432
	ds_read_b128 v[206:209], v152 offset:19456
	ds_read_b128 v[210:213], v152 offset:20480
	ds_read_b128 v[214:217], v152 offset:21504
	ds_read_b128 v[218:221], v152 offset:22528
	ds_read_b128 v[222:225], v152 offset:23552
	global_load_lds_dwordx4 v[144:145], off
	s_add_i32 m0, s54, 0x2000
	s_add_u32 s54, s18, 0x84000
	v_lshl_add_u64 v[162:163], s[18:19], 0, v[128:129]
	s_addc_u32 s55, s19, 0
	s_add_i32 s56, s45, s27
	global_load_lds_dwordx4 v[162:163], off
	v_lshl_add_u64 v[166:167], s[54:55], 0, v[132:133]
	s_mov_b32 m0, s56
	v_lshl_add_u64 v[226:227], s[20:21], 0, v[130:131]
	global_load_lds_dwordx4 v[166:167], off
	v_lshl_add_u64 v[166:167], s[54:55], 0, v[128:129]
	s_add_i32 m0, s56, 0x2000
	s_nop 0
	global_load_lds_dwordx4 v[166:167], off
	v_lshl_add_u64 v[166:167], s[20:21], 0, v[134:135]
	s_mov_b32 m0, s36
	s_nop 0
	global_load_lds_dwordx4 v[166:167], off
	s_mov_b32 m0, s37
	s_nop 0
	global_load_lds_dwordx4 v[226:227], off
	s_waitcnt vmcnt(8)
	s_waitcnt lgkmcnt(0)
	s_barrier
; #define PG8_STAGE(bufoff, gbase, voff) do { _Pragma("unroll") for (int _i = 0; _i < 2; ++_i) \
;         __builtin_amdgcn_global_load_lds((const unsigned*)((const char*)(gbase) + (voff)[_i]), (LAS unsigned*)(lds + (bufoff) + ldsw + _i * 8192), 16, 0, 0); } while (0)
; #define PG8_LDA(dst, b, h) do { _Pragma("unroll") for (int m = 0; m < 4; ++m) _Pragma("unroll") for (int k = 0; k < 2; ++k) dst[m][k] = *(const LAS bf16x8*)(lds + PG8_SA(b, h) + aoff + m * 2048 + k * 1024); } while (0)
; #define PG8_LDB(dst, b, h) do { _Pragma("unroll") for (int n = 0; n < 2; ++n) _Pragma("unroll") for (int k = 0; k < 2; ++k) dst[n][k] = *(const LAS bf16x8*)(lds + PG8_SB(b, h) + boff + n * 2048 + k * 1024); } while (0)
; #define PG8_MMA(ai, bj, At, Bt) do { __builtin_amdgcn_s_setprio(1); _Pragma("unroll") for (int m = 0; m < 4; ++m) _Pragma("unroll") for (int n = 0; n < 2; ++n) _Pragma("unroll") for (int k = 0; k < 2; ++k) \
;         acc[ai][bj][m][n] = __builtin_amdgcn_mfma_f32_16x16x32_bf16(Bt[n][k], At[m][k], acc[ai][bj][m][n], 0, 0, 0); __builtin_amdgcn_s_setprio(0); } while (0)
; #define PG8_WAIT_V(n) asm volatile("s_waitcnt vmcnt(" #n ")" ::: "memory")
; #define PG8_WAIT_L(n) asm volatile("s_waitcnt lgkmcnt(" #n ")" ::: "memory")
; #define PG8_BAR __builtin_amdgcn_s_barrier()
; #define PG8_SCHED __builtin_amdgcn_sched_barrier(0)
; template <class EpiT>
; __device__ __forceinline__ void gemm_phase(LAS unsigned char* lds, const Gemm g, const StaticOrder& S, const EpiT& E) {
;     ...
;             PG8_WAIT_V(8); PG8_WAIT_L(0); PG8_BAR; PG8_MMA(1, 0, At, B0); PG8_MMA(1, 1, At, B1); PG8_BAR; PG8_SCHED;
;             PG8_LDB(B0, 1, 0); PG8_LDB(B1, 1, 1); PG8_SCHED; PG8_LDA(At, 1, 0); PG8_STAGE(PG8_SA(0, 1), a2 + hstepA, voffA);
;             PG8_WAIT_V(8); PG8_WAIT_L(0); PG8_BAR; PG8_MMA(0, 0, At, B0); PG8_MMA(0, 1, At, B1); PG8_BAR; PG8_SCHED;
	s_setprio 1
	s_waitcnt lgkmcnt(0)
	v_mfma_f32_16x16x32_bf16 v[60:63], v[154:157], v[194:197], v[60:63]
	v_mfma_f32_16x16x32_bf16 v[60:63], v[158:161], v[198:201], v[60:63]
	v_mfma_f32_16x16x32_bf16 v[44:47], v[154:157], v[202:205], v[44:47]
	v_mfma_f32_16x16x32_bf16 v[44:47], v[158:161], v[206:209], v[44:47]
	v_mfma_f32_16x16x32_bf16 v[28:31], v[154:157], v[210:213], v[28:31]
	v_mfma_f32_16x16x32_bf16 v[28:31], v[158:161], v[214:217], v[28:31]
	v_mfma_f32_16x16x32_bf16 v[12:15], v[154:157], v[218:221], v[12:15]
	v_mfma_f32_16x16x32_bf16 v[12:15], v[158:161], v[222:225], v[12:15]
	v_mfma_f32_16x16x32_bf16 v[56:59], v[170:173], v[194:197], v[56:59]
	v_mfma_f32_16x16x32_bf16 v[56:59], v[174:177], v[198:201], v[56:59]
	v_mfma_f32_16x16x32_bf16 v[40:43], v[170:173], v[202:205], v[40:43]
	v_mfma_f32_16x16x32_bf16 v[40:43], v[174:177], v[206:209], v[40:43]
	v_mfma_f32_16x16x32_bf16 v[24:27], v[170:173], v[210:213], v[24:27]
	v_mfma_f32_16x16x32_bf16 v[24:27], v[174:177], v[214:217], v[24:27]
	v_mfma_f32_16x16x32_bf16 v[8:11], v[170:173], v[218:221], v[8:11]
	v_mfma_f32_16x16x32_bf16 v[8:11], v[174:177], v[222:225], v[8:11]
	s_setprio 0
	s_setprio 1
	v_mfma_f32_16x16x32_bf16 v[52:55], v[178:181], v[194:197], v[52:55]
	v_mfma_f32_16x16x32_bf16 v[52:55], v[182:185], v[198:201], v[52:55]
	v_mfma_f32_16x16x32_bf16 v[36:39], v[178:181], v[202:205], v[36:39]
	v_mfma_f32_16x16x32_bf16 v[36:39], v[182:185], v[206:209], v[36:39]
	v_mfma_f32_16x16x32_bf16 v[20:23], v[178:181], v[210:213], v[20:23]
	v_mfma_f32_16x16x32_bf16 v[20:23], v[182:185], v[214:217], v[20:23]
	v_mfma_f32_16x16x32_bf16 v[4:7], v[178:181], v[218:221], v[4:7]
	v_mfma_f32_16x16x32_bf16 v[4:7], v[182:185], v[222:225], v[4:7]
	v_mfma_f32_16x16x32_bf16 v[48:51], v[186:189], v[194:197], v[48:51]
	v_mfma_f32_16x16x32_bf16 v[48:51], v[190:193], v[198:201], v[48:51]
	v_mfma_f32_16x16x32_bf16 v[32:35], v[186:189], v[202:205], v[32:35]
	v_mfma_f32_16x16x32_bf16 v[32:35], v[190:193], v[206:209], v[32:35]
	v_mfma_f32_16x16x32_bf16 v[16:19], v[186:189], v[210:213], v[16:19]
	v_mfma_f32_16x16x32_bf16 v[16:19], v[190:193], v[214:217], v[16:19]
	v_mfma_f32_16x16x32_bf16 v[0:3], v[186:189], v[218:221], v[0:3]
	v_mfma_f32_16x16x32_bf16 v[0:3], v[190:193], v[222:225], v[0:3]
	s_setprio 0
	s_barrier
	s_add_i32 s54, 0, 0x18000
	v_add_u32_e32 v153, s54, v147
	s_add_i32 s55, 0, 0x1c000
	ds_read_b128 v[154:157], v153
	ds_read_b128 v[158:161], v153 offset:1024
	ds_read_b128 v[170:173], v153 offset:2048
	ds_read_b128 v[174:177], v153 offset:3072
	v_add_u32_e32 v153, s55, v147
	ds_read_b128 v[178:181], v153
	ds_read_b128 v[182:185], v153 offset:1024
	ds_read_b128 v[186:189], v153 offset:2048
	ds_read_b128 v[190:193], v153 offset:3072
	s_add_u32 s20, s20, 0x84000
	s_addc_u32 s21, s21, 0
	s_mov_b32 m0, s38
	v_lshl_add_u64 v[228:229], s[20:21], 0, v[134:135]
	ds_read_b128 v[194:197], v152 offset:32768
	ds_read_b128 v[198:201], v152 offset:33792
	ds_read_b128 v[202:205], v152 offset:34816
	ds_read_b128 v[206:209], v152 offset:35840
	ds_read_b128 v[210:213], v152 offset:36864
	ds_read_b128 v[214:217], v152 offset:37888
	ds_read_b128 v[218:221], v152 offset:38912
	ds_read_b128 v[222:225], v152 offset:39936
	global_load_lds_dwordx4 v[228:229], off
	v_lshl_add_u64 v[228:229], s[20:21], 0, v[130:131]
	s_mov_b32 m0, s39
	s_nop 0
	global_load_lds_dwordx4 v[228:229], off
	s_waitcnt vmcnt(8)
	s_waitcnt lgkmcnt(0)
	s_barrier
	s_setprio 1
	s_waitcnt lgkmcnt(0)
	v_mfma_f32_16x16x32_bf16 v[124:127], v[154:157], v[194:197], v[124:127]
	v_mfma_f32_16x16x32_bf16 v[124:127], v[158:161], v[198:201], v[124:127]
	v_mfma_f32_16x16x32_bf16 v[108:111], v[154:157], v[202:205], v[108:111]
	v_mfma_f32_16x16x32_bf16 v[108:111], v[158:161], v[206:209], v[108:111]
	v_mfma_f32_16x16x32_bf16 v[92:95], v[154:157], v[210:213], v[92:95]
	v_mfma_f32_16x16x32_bf16 v[92:95], v[158:161], v[214:217], v[92:95]
	v_mfma_f32_16x16x32_bf16 v[76:79], v[154:157], v[218:221], v[76:79]
	v_mfma_f32_16x16x32_bf16 v[76:79], v[158:161], v[222:225], v[76:79]
	v_mfma_f32_16x16x32_bf16 v[120:123], v[170:173], v[194:197], v[120:123]
	v_mfma_f32_16x16x32_bf16 v[120:123], v[174:177], v[198:201], v[120:123]
	v_mfma_f32_16x16x32_bf16 v[104:107], v[170:173], v[202:205], v[104:107]
	v_mfma_f32_16x16x32_bf16 v[104:107], v[174:177], v[206:209], v[104:107]
	v_mfma_f32_16x16x32_bf16 v[88:91], v[170:173], v[210:213], v[88:91]
	v_mfma_f32_16x16x32_bf16 v[88:91], v[174:177], v[214:217], v[88:91]
	v_mfma_f32_16x16x32_bf16 v[72:75], v[170:173], v[218:221], v[72:75]
	v_mfma_f32_16x16x32_bf16 v[72:75], v[174:177], v[222:225], v[72:75]
	s_setprio 0
	s_setprio 1
	v_mfma_f32_16x16x32_bf16 v[116:119], v[178:181], v[194:197], v[116:119]
	v_mfma_f32_16x16x32_bf16 v[116:119], v[182:185], v[198:201], v[116:119]
	v_mfma_f32_16x16x32_bf16 v[100:103], v[178:181], v[202:205], v[100:103]
	v_mfma_f32_16x16x32_bf16 v[100:103], v[182:185], v[206:209], v[100:103]
	v_mfma_f32_16x16x32_bf16 v[84:87], v[178:181], v[210:213], v[84:87]
	v_mfma_f32_16x16x32_bf16 v[84:87], v[182:185], v[214:217], v[84:87]
	v_mfma_f32_16x16x32_bf16 v[68:71], v[178:181], v[218:221], v[68:71]
	v_mfma_f32_16x16x32_bf16 v[68:71], v[182:185], v[222:225], v[68:71]
	v_mfma_f32_16x16x32_bf16 v[112:115], v[186:189], v[194:197], v[112:115]
	v_mfma_f32_16x16x32_bf16 v[112:115], v[190:193], v[198:201], v[112:115]
	v_mfma_f32_16x16x32_bf16 v[96:99], v[186:189], v[202:205], v[96:99]
	v_mfma_f32_16x16x32_bf16 v[96:99], v[190:193], v[206:209], v[96:99]
	v_mfma_f32_16x16x32_bf16 v[80:83], v[186:189], v[210:213], v[80:83]
	v_mfma_f32_16x16x32_bf16 v[80:83], v[190:193], v[214:217], v[80:83]
	v_mfma_f32_16x16x32_bf16 v[64:67], v[186:189], v[218:221], v[64:67]
	v_mfma_f32_16x16x32_bf16 v[64:67], v[190:193], v[222:225], v[64:67]
	s_setprio 0
	s_barrier
; #define PG8_STAGE(bufoff, gbase, voff) do { _Pragma("unroll") for (int _i = 0; _i < 2; ++_i) \
;         __builtin_amdgcn_global_load_lds((const unsigned*)((const char*)(gbase) + (voff)[_i]), (LAS unsigned*)(lds + (bufoff) + ldsw + _i * 8192), 16, 0, 0); } while (0)
; #define PG8_LDA(dst, b, h) do { _Pragma("unroll") for (int m = 0; m < 4; ++m) _Pragma("unroll") for (int k = 0; k < 2; ++k) dst[m][k] = *(const LAS bf16x8*)(lds + PG8_SA(b, h) + aoff + m * 2048 + k * 1024); } while (0)
; #define PG8_MMA(ai, bj, At, Bt) do { __builtin_amdgcn_s_setprio(1); _Pragma("unroll") for (int m = 0; m < 4; ++m) _Pragma("unroll") for (int n = 0; n < 2; ++n) _Pragma("unroll") for (int k = 0; k < 2; ++k) \
;         acc[ai][bj][m][n] = __builtin_amdgcn_mfma_f32_16x16x32_bf16(Bt[n][k], At[m][k], acc[ai][bj][m][n], 0, 0, 0); __builtin_amdgcn_s_setprio(0); } while (0)
; #define PG8_WAIT_V(n) asm volatile("s_waitcnt vmcnt(" #n ")" ::: "memory")
; #define PG8_WAIT_L(n) asm volatile("s_waitcnt lgkmcnt(" #n ")" ::: "memory")
; #define PG8_BAR __builtin_amdgcn_s_barrier()
; #define PG8_SCHED __builtin_amdgcn_sched_barrier(0)
; template <class EpiT>
; __device__ __forceinline__ void gemm_phase(LAS unsigned char* lds, const Gemm g, const StaticOrder& S, const EpiT& E) {
;     ...
;             PG8_LDA(At, 1, 1); PG8_STAGE(PG8_SB(1, 0), b3, voffB); PG8_STAGE(PG8_SB(1, 1), b3 + hstepB, voffB); PG8_STAGE(PG8_SA(1, 0), a3, voffA);
;             PG8_WAIT_V(8); PG8_WAIT_L(0); PG8_BAR; PG8_MMA(1, 0, At, B0); PG8_MMA(1, 1, At, B1); PG8_BAR; PG8_SCHED;
;         }
;         if (wr == 0) PG8_BAR;
	s_add_i32 s20, s54, s27
	v_lshl_add_u64 v[144:145], v[144:145], 0, s[10:11]
	s_mov_b32 m0, s20
	ds_read_b128 v[194:197], v152 offset:49152
	ds_read_b128 v[198:201], v152 offset:50176
	ds_read_b128 v[202:205], v152 offset:51200
	ds_read_b128 v[206:209], v152 offset:52224
	ds_read_b128 v[210:213], v152 offset:53248
	ds_read_b128 v[214:217], v152 offset:54272
	ds_read_b128 v[218:221], v152 offset:55296
	ds_read_b128 v[222:225], v152 offset:56320
	global_load_lds_dwordx4 v[144:145], off
	s_add_i32 m0, s20, 0x2000
	s_add_u32 s18, s18, 0x84080
	v_lshl_add_u64 v[144:145], v[162:163], 0, s[10:11]
	s_addc_u32 s19, s19, 0
	s_add_i32 s20, s55, s27
	global_load_lds_dwordx4 v[144:145], off
	v_lshl_add_u64 v[144:145], s[18:19], 0, v[132:133]
	s_mov_b32 m0, s20
	s_nop 0
	global_load_lds_dwordx4 v[144:145], off
	v_lshl_add_u64 v[144:145], s[18:19], 0, v[128:129]
	s_add_i32 m0, s20, 0x2000
	s_nop 0
	global_load_lds_dwordx4 v[144:145], off
	v_lshl_add_u64 v[144:145], v[166:167], 0, s[10:11]
	s_mov_b32 m0, s41
	s_nop 0
	global_load_lds_dwordx4 v[144:145], off
	v_lshl_add_u64 v[144:145], v[226:227], 0, s[10:11]
	s_mov_b32 m0, s42
	s_nop 0
	global_load_lds_dwordx4 v[144:145], off
	s_waitcnt vmcnt(8)
	s_waitcnt lgkmcnt(0)
	s_barrier
	s_setprio 1
	s_waitcnt lgkmcnt(0)
	v_mfma_f32_16x16x32_bf16 v[60:63], v[154:157], v[194:197], v[60:63]
	v_mfma_f32_16x16x32_bf16 v[60:63], v[158:161], v[198:201], v[60:63]
	v_mfma_f32_16x16x32_bf16 v[44:47], v[154:157], v[202:205], v[44:47]
	v_mfma_f32_16x16x32_bf16 v[44:47], v[158:161], v[206:209], v[44:47]
	v_mfma_f32_16x16x32_bf16 v[28:31], v[154:157], v[210:213], v[28:31]
	v_mfma_f32_16x16x32_bf16 v[28:31], v[158:161], v[214:217], v[28:31]
	v_mfma_f32_16x16x32_bf16 v[12:15], v[154:157], v[218:221], v[12:15]
	v_mfma_f32_16x16x32_bf16 v[12:15], v[158:161], v[222:225], v[12:15]
	v_mfma_f32_16x16x32_bf16 v[56:59], v[170:173], v[194:197], v[56:59]
	v_mfma_f32_16x16x32_bf16 v[56:59], v[174:177], v[198:201], v[56:59]
	v_mfma_f32_16x16x32_bf16 v[40:43], v[170:173], v[202:205], v[40:43]
	v_mfma_f32_16x16x32_bf16 v[40:43], v[174:177], v[206:209], v[40:43]
	v_mfma_f32_16x16x32_bf16 v[24:27], v[170:173], v[210:213], v[24:27]
	v_mfma_f32_16x16x32_bf16 v[24:27], v[174:177], v[214:217], v[24:27]
	v_mfma_f32_16x16x32_bf16 v[8:11], v[170:173], v[218:221], v[8:11]
	v_mfma_f32_16x16x32_bf16 v[8:11], v[174:177], v[222:225], v[8:11]
	s_setprio 0
	s_setprio 1
	v_mfma_f32_16x16x32_bf16 v[52:55], v[178:181], v[194:197], v[52:55]
	v_mfma_f32_16x16x32_bf16 v[52:55], v[182:185], v[198:201], v[52:55]
	v_mfma_f32_16x16x32_bf16 v[36:39], v[178:181], v[202:205], v[36:39]
	v_mfma_f32_16x16x32_bf16 v[36:39], v[182:185], v[206:209], v[36:39]
	v_mfma_f32_16x16x32_bf16 v[20:23], v[178:181], v[210:213], v[20:23]
	v_mfma_f32_16x16x32_bf16 v[20:23], v[182:185], v[214:217], v[20:23]
	v_mfma_f32_16x16x32_bf16 v[4:7], v[178:181], v[218:221], v[4:7]
	v_mfma_f32_16x16x32_bf16 v[4:7], v[182:185], v[222:225], v[4:7]
	v_mfma_f32_16x16x32_bf16 v[48:51], v[186:189], v[194:197], v[48:51]
	v_mfma_f32_16x16x32_bf16 v[48:51], v[190:193], v[198:201], v[48:51]
	v_mfma_f32_16x16x32_bf16 v[32:35], v[186:189], v[202:205], v[32:35]
	v_mfma_f32_16x16x32_bf16 v[32:35], v[190:193], v[206:209], v[32:35]
	v_mfma_f32_16x16x32_bf16 v[16:19], v[186:189], v[210:213], v[16:19]
	v_mfma_f32_16x16x32_bf16 v[16:19], v[190:193], v[214:217], v[16:19]
	v_mfma_f32_16x16x32_bf16 v[0:3], v[186:189], v[218:221], v[0:3]
	v_mfma_f32_16x16x32_bf16 v[0:3], v[190:193], v[222:225], v[0:3]
	s_setprio 0
	s_barrier
	s_add_i32 s53, s53, 2
	s_add_u32 s16, s16, 0x100
	s_addc_u32 s17, s17, 0
	s_add_u32 s51, s51, 0x100
	s_addc_u32 s52, s52, 0
	s_cmp_gt_u32 s53, 29
	s_cbranch_scc0 .LBB0_516
	s_and_b64 vcc, exec, s[12:13]
	s_cbranch_vccz .LBB0_519
	s_barrier

; #define PG8_STAGE(bufoff, gbase, voff) do { _Pragma("unroll") for (int _i = 0; _i < 2; ++_i) \
;         __builtin_amdgcn_global_load_lds((const unsigned*)((const char*)(gbase) + (voff)[_i]), (LAS unsigned*)(lds + (bufoff) + ldsw + _i * 8192), 16, 0, 0); } while (0)
; #define PG8_LDA(dst, b, h) do { _Pragma("unroll") for (int m = 0; m < 4; ++m) _Pragma("unroll") for (int k = 0; k < 2; ++k) dst[m][k] = *(const LAS bf16x8*)(lds + PG8_SA(b, h) + aoff + m * 2048 + k * 1024); } while (0)
; #define PG8_LDB(dst, b, h) do { _Pragma("unroll") for (int n = 0; n < 2; ++n) _Pragma("unroll") for (int k = 0; k < 2; ++k) dst[n][k] = *(const LAS bf16x8*)(lds + PG8_SB(b, h) + boff + n * 2048 + k * 1024); } while (0)
; #define PG8_MMA(ai, bj, At, Bt) do { __builtin_amdgcn_s_setprio(1); _Pragma("unroll") for (int m = 0; m < 4; ++m) _Pragma("unroll") for (int n = 0; n < 2; ++n) _Pragma("unroll") for (int k = 0; k < 2; ++k) \
;         acc[ai][bj][m][n] = __builtin_amdgcn_mfma_f32_16x16x32_bf16(Bt[n][k], At[m][k], acc[ai][bj][m][n], 0, 0, 0); __builtin_amdgcn_s_setprio(0); } while (0)
; #define PG8_WAIT_V(n) asm volatile("s_waitcnt vmcnt(" #n ")" ::: "memory")
; #define PG8_WAIT_L(n) asm volatile("s_waitcnt lgkmcnt(" #n ")" ::: "memory")
; #define PG8_BAR __builtin_amdgcn_s_barrier()
; #define PG8_SCHED __builtin_amdgcn_sched_barrier(0)
; template <class EpiT>
; __device__ __forceinline__ void gemm_phase(LAS unsigned char* lds, const Gemm g, const StaticOrder& S, const EpiT& E) {
;     ...
;         for (int t = 0; t < nt; t += 2) {
;             const bool last = (t == nt - 2);
;             const char* a1 = cA + (size_t)(t + 1) * kstep;
;             const char* a2 = last ? nA : cA + (size_t)(t + 2) * kstep; const char* b2 = last ? nB : cB + (size_t)(t + 2) * kstep;
;             const char* a3 = a2 + kstep; const char* b3 = b2 + kstep;
;             PG8_LDB(B0, 0, 0); PG8_LDB(B1, 0, 1); PG8_SCHED; PG8_LDA(At, 0, 0); PG8_STAGE(PG8_SA(1, 1), a1 + hstepA, voffA);
;             PG8_WAIT_V(8); PG8_WAIT_L(0); PG8_BAR; PG8_MMA(0, 0, At, B0); PG8_MMA(0, 1, At, B1); PG8_BAR; PG8_SCHED;
;             PG8_LDA(At, 0, 1); PG8_STAGE(PG8_SB(0, 0), b2, voffB); PG8_STAGE(PG8_SB(0, 1), b2 + hstepB, voffB); PG8_STAGE(PG8_SA(0, 0), a2, voffA);
;             PG8_WAIT_V(8); PG8_WAIT_L(0); PG8_BAR; PG8_MMA(1, 0, At, B0); PG8_MMA(1, 1, At, B1); PG8_BAR; PG8_SCHED;
.LBB0_595:
	ds_read_b128 v[154:157], v150
	ds_read_b128 v[158:161], v150 offset:1024
	ds_read_b128 v[170:173], v150 offset:2048
	ds_read_b128 v[174:177], v150 offset:3072
	ds_read_b128 v[178:181], v151
	ds_read_b128 v[182:185], v151 offset:1024
	ds_read_b128 v[186:189], v151 offset:2048
	ds_read_b128 v[190:193], v151 offset:3072
	s_add_u32 s20, s18, 0xffe9c080
	s_addc_u32 s21, s19, -1
	s_cmpk_eq_i32 s55, 0x54
	s_cselect_b32 s23, s5, s21
	s_cselect_b32 s22, s4, s20
	s_cselect_b32 s21, s17, s54
	s_cselect_b32 s20, s16, s53
	v_lshl_add_u64 v[162:163], s[18:19], 0, v[138:139]
	s_add_i32 m0, s37, 0xc000
	ds_read_b128 v[194:197], v152
	ds_read_b128 v[198:201], v152 offset:1024
	ds_read_b128 v[202:205], v152 offset:2048
	ds_read_b128 v[206:209], v152 offset:3072
	ds_read_b128 v[210:213], v152 offset:4096
	ds_read_b128 v[214:217], v152 offset:5120
	ds_read_b128 v[218:221], v152 offset:6144
	ds_read_b128 v[222:225], v152 offset:7168
	global_load_lds_dwordx4 v[162:163], off
	v_lshl_add_u64 v[162:163], s[18:19], 0, v[140:141]
	s_add_i32 m0, s37, 0xe000
	s_nop 0
	global_load_lds_dwordx4 v[162:163], off
	s_waitcnt vmcnt(8)
	s_waitcnt lgkmcnt(0)
	s_barrier
	s_setprio 1
	s_waitcnt lgkmcnt(0)
	v_mfma_f32_16x16x32_bf16 v[124:127], v[154:157], v[194:197], v[124:127]
	v_mfma_f32_16x16x32_bf16 v[124:127], v[158:161], v[198:201], v[124:127]
	v_mfma_f32_16x16x32_bf16 v[108:111], v[154:157], v[202:205], v[108:111]
	v_mfma_f32_16x16x32_bf16 v[108:111], v[158:161], v[206:209], v[108:111]
	v_mfma_f32_16x16x32_bf16 v[92:95], v[154:157], v[210:213], v[92:95]
	v_mfma_f32_16x16x32_bf16 v[92:95], v[158:161], v[214:217], v[92:95]
	v_mfma_f32_16x16x32_bf16 v[76:79], v[154:157], v[218:221], v[76:79]
	v_mfma_f32_16x16x32_bf16 v[76:79], v[158:161], v[222:225], v[76:79]
	v_mfma_f32_16x16x32_bf16 v[120:123], v[170:173], v[194:197], v[120:123]
	v_mfma_f32_16x16x32_bf16 v[120:123], v[174:177], v[198:201], v[120:123]
	v_mfma_f32_16x16x32_bf16 v[104:107], v[170:173], v[202:205], v[104:107]
	v_mfma_f32_16x16x32_bf16 v[104:107], v[174:177], v[206:209], v[104:107]
	v_mfma_f32_16x16x32_bf16 v[88:91], v[170:173], v[210:213], v[88:91]
	v_mfma_f32_16x16x32_bf16 v[88:91], v[174:177], v[214:217], v[88:91]
	v_mfma_f32_16x16x32_bf16 v[72:75], v[170:173], v[218:221], v[72:75]
	v_mfma_f32_16x16x32_bf16 v[72:75], v[174:177], v[222:225], v[72:75]
	s_setprio 0
	s_setprio 1
	v_mfma_f32_16x16x32_bf16 v[116:119], v[178:181], v[194:197], v[116:119]
	v_mfma_f32_16x16x32_bf16 v[116:119], v[182:185], v[198:201], v[116:119]
	v_mfma_f32_16x16x32_bf16 v[100:103], v[178:181], v[202:205], v[100:103]
	v_mfma_f32_16x16x32_bf16 v[100:103], v[182:185], v[206:209], v[100:103]
	v_mfma_f32_16x16x32_bf16 v[84:87], v[178:181], v[210:213], v[84:87]
	v_mfma_f32_16x16x32_bf16 v[84:87], v[182:185], v[214:217], v[84:87]
	v_mfma_f32_16x16x32_bf16 v[68:71], v[178:181], v[218:221], v[68:71]
	v_mfma_f32_16x16x32_bf16 v[68:71], v[182:185], v[222:225], v[68:71]
	v_mfma_f32_16x16x32_bf16 v[112:115], v[186:189], v[194:197], v[112:115]
	v_mfma_f32_16x16x32_bf16 v[112:115], v[190:193], v[198:201], v[112:115]
	v_mfma_f32_16x16x32_bf16 v[96:99], v[186:189], v[202:205], v[96:99]
	v_mfma_f32_16x16x32_bf16 v[96:99], v[190:193], v[206:209], v[96:99]
	v_mfma_f32_16x16x32_bf16 v[80:83], v[186:189], v[210:213], v[80:83]
	v_mfma_f32_16x16x32_bf16 v[80:83], v[190:193], v[214:217], v[80:83]
	v_mfma_f32_16x16x32_bf16 v[64:67], v[186:189], v[218:221], v[64:67]
	v_mfma_f32_16x16x32_bf16 v[64:67], v[190:193], v[222:225], v[64:67]
	s_setprio 0
	s_barrier
	s_add_i32 s56, s46, s36
	v_lshl_add_u64 v[162:163], s[20:21], 0, v[130:131]
	s_mov_b32 m0, s56
	ds_read_b128 v[194:197], v152 offset:16384
	ds_read_b128 v[198:201], v152 offset:17408
	ds_read_b128 v[202:205], v152 offset:18432
	ds_read_b128 v[206:209], v152 offset:19456
	ds_read_b128 v[210:213], v152 offset:20480
	ds_read_b128 v[214:217], v152 offset:21504
	ds_read_b128 v[218:221], v152 offset:22528
	ds_read_b128 v[222:225], v152 offset:23552
	global_load_lds_dwordx4 v[162:163], off
	s_add_i32 m0, s56, 0x2000
	s_add_u32 s56, s20, 0x164000
	v_lshl_add_u64 v[166:167], s[20:21], 0, v[134:135]
	s_addc_u32 s57, s21, 0
	s_add_i32 s58, s47, s36
	global_load_lds_dwordx4 v[166:167], off
	v_lshl_add_u64 v[226:227], s[56:57], 0, v[130:131]
	s_mov_b32 m0, s58
	v_lshl_add_u64 v[228:229], s[22:23], 0, v[132:133]
	global_load_lds_dwordx4 v[226:227], off
	v_lshl_add_u64 v[226:227], s[56:57], 0, v[134:135]
	s_add_i32 m0, s58, 0x2000
	s_nop 0
	global_load_lds_dwordx4 v[226:227], off
	v_lshl_add_u64 v[226:227], s[22:23], 0, v[128:129]
	s_mov_b32 m0, s37
	s_nop 0
	global_load_lds_dwordx4 v[226:227], off
	s_mov_b32 m0, s38
	s_nop 0
	global_load_lds_dwordx4 v[228:229], off
	s_waitcnt vmcnt(8)
	s_waitcnt lgkmcnt(0)
	s_barrier
; #define PG8_STAGE(bufoff, gbase, voff) do { _Pragma("unroll") for (int _i = 0; _i < 2; ++_i) \
;         __builtin_amdgcn_global_load_lds((const unsigned*)((const char*)(gbase) + (voff)[_i]), (LAS unsigned*)(lds + (bufoff) + ldsw + _i * 8192), 16, 0, 0); } while (0)
; #define PG8_LDA(dst, b, h) do { _Pragma("unroll") for (int m = 0; m < 4; ++m) _Pragma("unroll") for (int k = 0; k < 2; ++k) dst[m][k] = *(const LAS bf16x8*)(lds + PG8_SA(b, h) + aoff + m * 2048 + k * 1024); } while (0)
; #define PG8_LDB(dst, b, h) do { _Pragma("unroll") for (int n = 0; n < 2; ++n) _Pragma("unroll") for (int k = 0; k < 2; ++k) dst[n][k] = *(const LAS bf16x8*)(lds + PG8_SB(b, h) + boff + n * 2048 + k * 1024); } while (0)
; #define PG8_MMA(ai, bj, At, Bt) do { __builtin_amdgcn_s_setprio(1); _Pragma("unroll") for (int m = 0; m < 4; ++m) _Pragma("unroll") for (int n = 0; n < 2; ++n) _Pragma("unroll") for (int k = 0; k < 2; ++k) \
;         acc[ai][bj][m][n] = __builtin_amdgcn_mfma_f32_16x16x32_bf16(Bt[n][k], At[m][k], acc[ai][bj][m][n], 0, 0, 0); __builtin_amdgcn_s_setprio(0); } while (0)
; #define PG8_WAIT_V(n) asm volatile("s_waitcnt vmcnt(" #n ")" ::: "memory")
; #define PG8_WAIT_L(n) asm volatile("s_waitcnt lgkmcnt(" #n ")" ::: "memory")
; #define PG8_BAR __builtin_amdgcn_s_barrier()
; #define PG8_SCHED __builtin_amdgcn_sched_barrier(0)
; template <class EpiT>
; __device__ __forceinline__ void gemm_phase(LAS unsigned char* lds, const Gemm g, const StaticOrder& S, const EpiT& E) {
;     ...
;             PG8_WAIT_V(8); PG8_WAIT_L(0); PG8_BAR; PG8_MMA(1, 0, At, B0); PG8_MMA(1, 1, At, B1); PG8_BAR; PG8_SCHED;
;             PG8_LDB(B0, 1, 0); PG8_LDB(B1, 1, 1); PG8_SCHED; PG8_LDA(At, 1, 0); PG8_STAGE(PG8_SA(0, 1), a2 + hstepA, voffA);
;             PG8_WAIT_V(8); PG8_WAIT_L(0); PG8_BAR; PG8_MMA(0, 0, At, B0); PG8_MMA(0, 1, At, B1); PG8_BAR; PG8_SCHED;
	s_setprio 1
	s_waitcnt lgkmcnt(0)
	v_mfma_f32_16x16x32_bf16 v[60:63], v[154:157], v[194:197], v[60:63]
	v_mfma_f32_16x16x32_bf16 v[60:63], v[158:161], v[198:201], v[60:63]
	v_mfma_f32_16x16x32_bf16 v[44:47], v[154:157], v[202:205], v[44:47]
	v_mfma_f32_16x16x32_bf16 v[44:47], v[158:161], v[206:209], v[44:47]
	v_mfma_f32_16x16x32_bf16 v[28:31], v[154:157], v[210:213], v[28:31]
	v_mfma_f32_16x16x32_bf16 v[28:31], v[158:161], v[214:217], v[28:31]
	v_mfma_f32_16x16x32_bf16 v[12:15], v[154:157], v[218:221], v[12:15]
	v_mfma_f32_16x16x32_bf16 v[12:15], v[158:161], v[222:225], v[12:15]
	v_mfma_f32_16x16x32_bf16 v[56:59], v[170:173], v[194:197], v[56:59]
	v_mfma_f32_16x16x32_bf16 v[56:59], v[174:177], v[198:201], v[56:59]
	v_mfma_f32_16x16x32_bf16 v[40:43], v[170:173], v[202:205], v[40:43]
	v_mfma_f32_16x16x32_bf16 v[40:43], v[174:177], v[206:209], v[40:43]
	v_mfma_f32_16x16x32_bf16 v[24:27], v[170:173], v[210:213], v[24:27]
	v_mfma_f32_16x16x32_bf16 v[24:27], v[174:177], v[214:217], v[24:27]
	v_mfma_f32_16x16x32_bf16 v[8:11], v[170:173], v[218:221], v[8:11]
	v_mfma_f32_16x16x32_bf16 v[8:11], v[174:177], v[222:225], v[8:11]
	s_setprio 0
	s_setprio 1
	v_mfma_f32_16x16x32_bf16 v[52:55], v[178:181], v[194:197], v[52:55]
	v_mfma_f32_16x16x32_bf16 v[52:55], v[182:185], v[198:201], v[52:55]
	v_mfma_f32_16x16x32_bf16 v[36:39], v[178:181], v[202:205], v[36:39]
	v_mfma_f32_16x16x32_bf16 v[36:39], v[182:185], v[206:209], v[36:39]
	v_mfma_f32_16x16x32_bf16 v[20:23], v[178:181], v[210:213], v[20:23]
	v_mfma_f32_16x16x32_bf16 v[20:23], v[182:185], v[214:217], v[20:23]
	v_mfma_f32_16x16x32_bf16 v[4:7], v[178:181], v[218:221], v[4:7]
	v_mfma_f32_16x16x32_bf16 v[4:7], v[182:185], v[222:225], v[4:7]
	v_mfma_f32_16x16x32_bf16 v[48:51], v[186:189], v[194:197], v[48:51]
	v_mfma_f32_16x16x32_bf16 v[48:51], v[190:193], v[198:201], v[48:51]
	v_mfma_f32_16x16x32_bf16 v[32:35], v[186:189], v[202:205], v[32:35]
	v_mfma_f32_16x16x32_bf16 v[32:35], v[190:193], v[206:209], v[32:35]
	v_mfma_f32_16x16x32_bf16 v[16:19], v[186:189], v[210:213], v[16:19]
	v_mfma_f32_16x16x32_bf16 v[16:19], v[190:193], v[214:217], v[16:19]
	v_mfma_f32_16x16x32_bf16 v[0:3], v[186:189], v[218:221], v[0:3]
	v_mfma_f32_16x16x32_bf16 v[0:3], v[190:193], v[222:225], v[0:3]
	s_setprio 0
	s_barrier
	s_add_i32 s56, 0, 0x18000
	v_add_u32_e32 v165, s56, v146
	s_add_i32 s57, 0, 0x1c000
	ds_read_b128 v[154:157], v165
	ds_read_b128 v[158:161], v165 offset:1024
	ds_read_b128 v[170:173], v165 offset:2048
	ds_read_b128 v[174:177], v165 offset:3072
	v_add_u32_e32 v165, s57, v146
	ds_read_b128 v[178:181], v165
	ds_read_b128 v[182:185], v165 offset:1024
	ds_read_b128 v[186:189], v165 offset:2048
	ds_read_b128 v[190:193], v165 offset:3072
	s_add_u32 s22, s22, 0x164000
	s_addc_u32 s23, s23, 0
	s_mov_b32 m0, s39
	v_lshl_add_u64 v[230:231], s[22:23], 0, v[128:129]
	ds_read_b128 v[194:197], v152 offset:32768
	ds_read_b128 v[198:201], v152 offset:33792
	ds_read_b128 v[202:205], v152 offset:34816
	ds_read_b128 v[206:209], v152 offset:35840
	ds_read_b128 v[210:213], v152 offset:36864
	ds_read_b128 v[214:217], v152 offset:37888
	ds_read_b128 v[218:221], v152 offset:38912
	ds_read_b128 v[222:225], v152 offset:39936
	global_load_lds_dwordx4 v[230:231], off
	v_lshl_add_u64 v[230:231], s[22:23], 0, v[132:133]
	s_mov_b32 m0, s40
	s_nop 0
	global_load_lds_dwordx4 v[230:231], off
	s_waitcnt vmcnt(8)
	s_waitcnt lgkmcnt(0)
	s_barrier
	s_setprio 1
	s_waitcnt lgkmcnt(0)
	v_mfma_f32_16x16x32_bf16 v[124:127], v[154:157], v[194:197], v[124:127]
	v_mfma_f32_16x16x32_bf16 v[124:127], v[158:161], v[198:201], v[124:127]
	v_mfma_f32_16x16x32_bf16 v[108:111], v[154:157], v[202:205], v[108:111]
	v_mfma_f32_16x16x32_bf16 v[108:111], v[158:161], v[206:209], v[108:111]
	v_mfma_f32_16x16x32_bf16 v[92:95], v[154:157], v[210:213], v[92:95]
	v_mfma_f32_16x16x32_bf16 v[92:95], v[158:161], v[214:217], v[92:95]
	v_mfma_f32_16x16x32_bf16 v[76:79], v[154:157], v[218:221], v[76:79]
	v_mfma_f32_16x16x32_bf16 v[76:79], v[158:161], v[222:225], v[76:79]
	v_mfma_f32_16x16x32_bf16 v[120:123], v[170:173], v[194:197], v[120:123]
	v_mfma_f32_16x16x32_bf16 v[120:123], v[174:177], v[198:201], v[120:123]
	v_mfma_f32_16x16x32_bf16 v[104:107], v[170:173], v[202:205], v[104:107]
	v_mfma_f32_16x16x32_bf16 v[104:107], v[174:177], v[206:209], v[104:107]
	v_mfma_f32_16x16x32_bf16 v[88:91], v[170:173], v[210:213], v[88:91]
	v_mfma_f32_16x16x32_bf16 v[88:91], v[174:177], v[214:217], v[88:91]
	v_mfma_f32_16x16x32_bf16 v[72:75], v[170:173], v[218:221], v[72:75]
	v_mfma_f32_16x16x32_bf16 v[72:75], v[174:177], v[222:225], v[72:75]
	s_setprio 0
	s_setprio 1
	v_mfma_f32_16x16x32_bf16 v[116:119], v[178:181], v[194:197], v[116:119]
	v_mfma_f32_16x16x32_bf16 v[116:119], v[182:185], v[198:201], v[116:119]
	v_mfma_f32_16x16x32_bf16 v[100:103], v[178:181], v[202:205], v[100:103]
	v_mfma_f32_16x16x32_bf16 v[100:103], v[182:185], v[206:209], v[100:103]
	v_mfma_f32_16x16x32_bf16 v[84:87], v[178:181], v[210:213], v[84:87]
	v_mfma_f32_16x16x32_bf16 v[84:87], v[182:185], v[214:217], v[84:87]
	v_mfma_f32_16x16x32_bf16 v[68:71], v[178:181], v[218:221], v[68:71]
	v_mfma_f32_16x16x32_bf16 v[68:71], v[182:185], v[222:225], v[68:71]
	v_mfma_f32_16x16x32_bf16 v[112:115], v[186:189], v[194:197], v[112:115]
	v_mfma_f32_16x16x32_bf16 v[112:115], v[190:193], v[198:201], v[112:115]
	v_mfma_f32_16x16x32_bf16 v[96:99], v[186:189], v[202:205], v[96:99]
	v_mfma_f32_16x16x32_bf16 v[96:99], v[190:193], v[206:209], v[96:99]
	v_mfma_f32_16x16x32_bf16 v[80:83], v[186:189], v[210:213], v[80:83]
	v_mfma_f32_16x16x32_bf16 v[80:83], v[190:193], v[214:217], v[80:83]
	v_mfma_f32_16x16x32_bf16 v[64:67], v[186:189], v[218:221], v[64:67]
	v_mfma_f32_16x16x32_bf16 v[64:67], v[190:193], v[222:225], v[64:67]
	s_setprio 0
	s_barrier
; #define PG8_STAGE(bufoff, gbase, voff) do { _Pragma("unroll") for (int _i = 0; _i < 2; ++_i) \
;         __builtin_amdgcn_global_load_lds((const unsigned*)((const char*)(gbase) + (voff)[_i]), (LAS unsigned*)(lds + (bufoff) + ldsw + _i * 8192), 16, 0, 0); } while (0)
; #define PG8_LDA(dst, b, h) do { _Pragma("unroll") for (int m = 0; m < 4; ++m) _Pragma("unroll") for (int k = 0; k < 2; ++k) dst[m][k] = *(const LAS bf16x8*)(lds + PG8_SA(b, h) + aoff + m * 2048 + k * 1024); } while (0)
; #define PG8_MMA(ai, bj, At, Bt) do { __builtin_amdgcn_s_setprio(1); _Pragma("unroll") for (int m = 0; m < 4; ++m) _Pragma("unroll") for (int n = 0; n < 2; ++n) _Pragma("unroll") for (int k = 0; k < 2; ++k) \
;         acc[ai][bj][m][n] = __builtin_amdgcn_mfma_f32_16x16x32_bf16(Bt[n][k], At[m][k], acc[ai][bj][m][n], 0, 0, 0); __builtin_amdgcn_s_setprio(0); } while (0)
; #define PG8_WAIT_V(n) asm volatile("s_waitcnt vmcnt(" #n ")" ::: "memory")
; #define PG8_WAIT_L(n) asm volatile("s_waitcnt lgkmcnt(" #n ")" ::: "memory")
; #define PG8_BAR __builtin_amdgcn_s_barrier()
; #define PG8_SCHED __builtin_amdgcn_sched_barrier(0)
; template <class EpiT>
; __device__ __forceinline__ void gemm_phase(LAS unsigned char* lds, const Gemm g, const StaticOrder& S, const EpiT& E) {
;     ...
;             PG8_LDA(At, 1, 1); PG8_STAGE(PG8_SB(1, 0), b3, voffB); PG8_STAGE(PG8_SB(1, 1), b3 + hstepB, voffB); PG8_STAGE(PG8_SA(1, 0), a3, voffA);
;             PG8_WAIT_V(8); PG8_WAIT_L(0); PG8_BAR; PG8_MMA(1, 0, At, B0); PG8_MMA(1, 1, At, B1); PG8_BAR; PG8_SCHED;
;         }
;         if (wr == 0) PG8_BAR;
	s_add_i32 s22, s56, s36
	v_lshl_add_u64 v[162:163], v[162:163], 0, s[12:13]
	s_mov_b32 m0, s22
	ds_read_b128 v[194:197], v152 offset:49152
	ds_read_b128 v[198:201], v152 offset:50176
	ds_read_b128 v[202:205], v152 offset:51200
	ds_read_b128 v[206:209], v152 offset:52224
	ds_read_b128 v[210:213], v152 offset:53248
	ds_read_b128 v[214:217], v152 offset:54272
	ds_read_b128 v[218:221], v152 offset:55296
	ds_read_b128 v[222:225], v152 offset:56320
	global_load_lds_dwordx4 v[162:163], off
	s_add_i32 m0, s22, 0x2000
	s_add_u32 s20, s20, 0x164080
	v_lshl_add_u64 v[162:163], v[166:167], 0, s[12:13]
	s_addc_u32 s21, s21, 0
	s_add_i32 s22, s57, s36
	global_load_lds_dwordx4 v[162:163], off
	v_lshl_add_u64 v[162:163], s[20:21], 0, v[130:131]
	s_mov_b32 m0, s22
	s_nop 0
	global_load_lds_dwordx4 v[162:163], off
	v_lshl_add_u64 v[162:163], s[20:21], 0, v[134:135]
	s_add_i32 m0, s22, 0x2000
	s_nop 0
	global_load_lds_dwordx4 v[162:163], off
	v_lshl_add_u64 v[162:163], v[226:227], 0, s[12:13]
	s_mov_b32 m0, s42
	s_nop 0
	global_load_lds_dwordx4 v[162:163], off
	v_lshl_add_u64 v[162:163], v[228:229], 0, s[12:13]
	s_mov_b32 m0, s43
	s_nop 0
	global_load_lds_dwordx4 v[162:163], off
	s_waitcnt vmcnt(8)
	s_waitcnt lgkmcnt(0)
	s_barrier
	s_setprio 1
	s_waitcnt lgkmcnt(0)
	v_mfma_f32_16x16x32_bf16 v[60:63], v[154:157], v[194:197], v[60:63]
	v_mfma_f32_16x16x32_bf16 v[60:63], v[158:161], v[198:201], v[60:63]
	v_mfma_f32_16x16x32_bf16 v[44:47], v[154:157], v[202:205], v[44:47]
	v_mfma_f32_16x16x32_bf16 v[44:47], v[158:161], v[206:209], v[44:47]
	v_mfma_f32_16x16x32_bf16 v[28:31], v[154:157], v[210:213], v[28:31]
	v_mfma_f32_16x16x32_bf16 v[28:31], v[158:161], v[214:217], v[28:31]
	v_mfma_f32_16x16x32_bf16 v[12:15], v[154:157], v[218:221], v[12:15]
	v_mfma_f32_16x16x32_bf16 v[12:15], v[158:161], v[222:225], v[12:15]
	v_mfma_f32_16x16x32_bf16 v[56:59], v[170:173], v[194:197], v[56:59]
	v_mfma_f32_16x16x32_bf16 v[56:59], v[174:177], v[198:201], v[56:59]
	v_mfma_f32_16x16x32_bf16 v[40:43], v[170:173], v[202:205], v[40:43]
	v_mfma_f32_16x16x32_bf16 v[40:43], v[174:177], v[206:209], v[40:43]
	v_mfma_f32_16x16x32_bf16 v[24:27], v[170:173], v[210:213], v[24:27]
	v_mfma_f32_16x16x32_bf16 v[24:27], v[174:177], v[214:217], v[24:27]
	v_mfma_f32_16x16x32_bf16 v[8:11], v[170:173], v[218:221], v[8:11]
	v_mfma_f32_16x16x32_bf16 v[8:11], v[174:177], v[222:225], v[8:11]
	s_setprio 0
	s_setprio 1
	v_mfma_f32_16x16x32_bf16 v[52:55], v[178:181], v[194:197], v[52:55]
	v_mfma_f32_16x16x32_bf16 v[52:55], v[182:185], v[198:201], v[52:55]
	v_mfma_f32_16x16x32_bf16 v[36:39], v[178:181], v[202:205], v[36:39]
	v_mfma_f32_16x16x32_bf16 v[36:39], v[182:185], v[206:209], v[36:39]
	v_mfma_f32_16x16x32_bf16 v[20:23], v[178:181], v[210:213], v[20:23]
	v_mfma_f32_16x16x32_bf16 v[20:23], v[182:185], v[214:217], v[20:23]
	v_mfma_f32_16x16x32_bf16 v[4:7], v[178:181], v[218:221], v[4:7]
	v_mfma_f32_16x16x32_bf16 v[4:7], v[182:185], v[222:225], v[4:7]
	v_mfma_f32_16x16x32_bf16 v[48:51], v[186:189], v[194:197], v[48:51]
	v_mfma_f32_16x16x32_bf16 v[48:51], v[190:193], v[198:201], v[48:51]
	v_mfma_f32_16x16x32_bf16 v[32:35], v[186:189], v[202:205], v[32:35]
	v_mfma_f32_16x16x32_bf16 v[32:35], v[190:193], v[206:209], v[32:35]
	v_mfma_f32_16x16x32_bf16 v[16:19], v[186:189], v[210:213], v[16:19]
	v_mfma_f32_16x16x32_bf16 v[16:19], v[190:193], v[214:217], v[16:19]
	v_mfma_f32_16x16x32_bf16 v[0:3], v[186:189], v[218:221], v[0:3]
	v_mfma_f32_16x16x32_bf16 v[0:3], v[190:193], v[222:225], v[0:3]
	s_setprio 0
	s_barrier
	s_add_i32 s55, s55, 2
	s_add_u32 s18, s18, 0x100
	s_addc_u32 s19, s19, 0
	s_add_u32 s53, s53, 0x100
	s_addc_u32 s54, s54, 0
	s_cmpk_gt_u32 s55, 0x55
	s_cbranch_scc0 .LBB0_595
	s_and_b64 vcc, exec, s[14:15]
	s_cbranch_vccz .LBB0_598
	s_barrier

; #define PG8_STAGE(bufoff, gbase, voff) do { _Pragma("unroll") for (int _i = 0; _i < 2; ++_i) \
;         __builtin_amdgcn_global_load_lds((const unsigned*)((const char*)(gbase) + (voff)[_i]), (LAS unsigned*)(lds + (bufoff) + ldsw + _i * 8192), 16, 0, 0); } while (0)
; #define PG8_LDA(dst, b, h) do { _Pragma("unroll") for (int m = 0; m < 4; ++m) _Pragma("unroll") for (int k = 0; k < 2; ++k) dst[m][k] = *(const LAS bf16x8*)(lds + PG8_SA(b, h) + aoff + m * 2048 + k * 1024); } while (0)
; #define PG8_LDB(dst, b, h) do { _Pragma("unroll") for (int n = 0; n < 2; ++n) _Pragma("unroll") for (int k = 0; k < 2; ++k) dst[n][k] = *(const LAS bf16x8*)(lds + PG8_SB(b, h) + boff + n * 2048 + k * 1024); } while (0)
; #define PG8_MMA(ai, bj, At, Bt) do { __builtin_amdgcn_s_setprio(1); _Pragma("unroll") for (int m = 0; m < 4; ++m) _Pragma("unroll") for (int n = 0; n < 2; ++n) _Pragma("unroll") for (int k = 0; k < 2; ++k) \
;         acc[ai][bj][m][n] = __builtin_amdgcn_mfma_f32_16x16x32_bf16(Bt[n][k], At[m][k], acc[ai][bj][m][n], 0, 0, 0); __builtin_amdgcn_s_setprio(0); } while (0)
; #define PG8_WAIT_V(n) asm volatile("s_waitcnt vmcnt(" #n ")" ::: "memory")
; #define PG8_WAIT_L(n) asm volatile("s_waitcnt lgkmcnt(" #n ")" ::: "memory")
; #define PG8_BAR __builtin_amdgcn_s_barrier()
; #define PG8_SCHED __builtin_amdgcn_sched_barrier(0)
; template <class EpiT>
; __device__ __forceinline__ void gemm_phase(LAS unsigned char* lds, const Gemm g, const StaticOrder& S, const EpiT& E) {
;     ...
;         for (int t = 0; t < nt; t += 2) {
;             const bool last = (t == nt - 2);
;             const char* a1 = cA + (size_t)(t + 1) * kstep;
;             const char* a2 = last ? nA : cA + (size_t)(t + 2) * kstep; const char* b2 = last ? nB : cB + (size_t)(t + 2) * kstep;
;             const char* a3 = a2 + kstep; const char* b3 = b2 + kstep;
;             PG8_LDB(B0, 0, 0); PG8_LDB(B1, 0, 1); PG8_SCHED; PG8_LDA(At, 0, 0); PG8_STAGE(PG8_SA(1, 1), a1 + hstepA, voffA);
;             PG8_WAIT_V(8); PG8_WAIT_L(0); PG8_BAR; PG8_MMA(0, 0, At, B0); PG8_MMA(0, 1, At, B1); PG8_BAR; PG8_SCHED;
;             PG8_LDA(At, 0, 1); PG8_STAGE(PG8_SB(0, 0), b2, voffB); PG8_STAGE(PG8_SB(0, 1), b2 + hstepB, voffB); PG8_STAGE(PG8_SA(0, 0), a2, voffA);
;             PG8_WAIT_V(8); PG8_WAIT_L(0); PG8_BAR; PG8_MMA(1, 0, At, B0); PG8_MMA(1, 1, At, B1); PG8_BAR; PG8_SCHED;
.LBB0_761:
	ds_read_b128 v[156:159], v160
	ds_read_b128 v[164:167], v160 offset:1024
	ds_read_b128 v[170:173], v160 offset:2048
	ds_read_b128 v[174:177], v160 offset:3072
	ds_read_b128 v[178:181], v161
	ds_read_b128 v[182:185], v161 offset:1024
	ds_read_b128 v[186:189], v161 offset:2048
	ds_read_b128 v[190:193], v161 offset:3072
	s_add_u32 s22, s20, 0xfff7c080
	s_addc_u32 s23, s21, -1
	s_cmp_eq_u32 s56, 28
	s_cselect_b32 s25, s5, s23
	s_cselect_b32 s24, s4, s22
	s_cselect_b32 s23, s19, s39
	s_cselect_b32 s22, s18, s8
	v_lshl_add_u64 v[226:227], s[20:21], 0, v[146:147]
	s_add_i32 m0, s40, 0xc000
	ds_read_b128 v[194:197], v162
	ds_read_b128 v[198:201], v162 offset:1024
	ds_read_b128 v[202:205], v162 offset:2048
	ds_read_b128 v[206:209], v162 offset:3072
	ds_read_b128 v[210:213], v162 offset:4096
	ds_read_b128 v[214:217], v162 offset:5120
	ds_read_b128 v[218:221], v162 offset:6144
	ds_read_b128 v[222:225], v162 offset:7168
	global_load_lds_dwordx4 v[226:227], off
	v_lshl_add_u64 v[226:227], s[20:21], 0, v[150:151]
	s_add_i32 m0, s40, 0xe000
	s_nop 0
	global_load_lds_dwordx4 v[226:227], off
	s_waitcnt vmcnt(8)
	s_waitcnt lgkmcnt(0)
	s_barrier
	s_setprio 1
	s_waitcnt lgkmcnt(0)
	v_mfma_f32_16x16x32_bf16 v[124:127], v[156:159], v[194:197], v[124:127]
	v_mfma_f32_16x16x32_bf16 v[124:127], v[164:167], v[198:201], v[124:127]
	v_mfma_f32_16x16x32_bf16 v[108:111], v[156:159], v[202:205], v[108:111]
	v_mfma_f32_16x16x32_bf16 v[108:111], v[164:167], v[206:209], v[108:111]
	v_mfma_f32_16x16x32_bf16 v[92:95], v[156:159], v[210:213], v[92:95]
	v_mfma_f32_16x16x32_bf16 v[92:95], v[164:167], v[214:217], v[92:95]
	v_mfma_f32_16x16x32_bf16 v[76:79], v[156:159], v[218:221], v[76:79]
	v_mfma_f32_16x16x32_bf16 v[76:79], v[164:167], v[222:225], v[76:79]
	v_mfma_f32_16x16x32_bf16 v[120:123], v[170:173], v[194:197], v[120:123]
	v_mfma_f32_16x16x32_bf16 v[120:123], v[174:177], v[198:201], v[120:123]
	v_mfma_f32_16x16x32_bf16 v[104:107], v[170:173], v[202:205], v[104:107]
	v_mfma_f32_16x16x32_bf16 v[104:107], v[174:177], v[206:209], v[104:107]
	v_mfma_f32_16x16x32_bf16 v[88:91], v[170:173], v[210:213], v[88:91]
	v_mfma_f32_16x16x32_bf16 v[88:91], v[174:177], v[214:217], v[88:91]
	v_mfma_f32_16x16x32_bf16 v[72:75], v[170:173], v[218:221], v[72:75]
	v_mfma_f32_16x16x32_bf16 v[72:75], v[174:177], v[222:225], v[72:75]
	s_setprio 0
	s_setprio 1
	v_mfma_f32_16x16x32_bf16 v[116:119], v[178:181], v[194:197], v[116:119]
	v_mfma_f32_16x16x32_bf16 v[116:119], v[182:185], v[198:201], v[116:119]
	v_mfma_f32_16x16x32_bf16 v[100:103], v[178:181], v[202:205], v[100:103]
	v_mfma_f32_16x16x32_bf16 v[100:103], v[182:185], v[206:209], v[100:103]
	v_mfma_f32_16x16x32_bf16 v[84:87], v[178:181], v[210:213], v[84:87]
	v_mfma_f32_16x16x32_bf16 v[84:87], v[182:185], v[214:217], v[84:87]
	v_mfma_f32_16x16x32_bf16 v[68:71], v[178:181], v[218:221], v[68:71]
	v_mfma_f32_16x16x32_bf16 v[68:71], v[182:185], v[222:225], v[68:71]
	v_mfma_f32_16x16x32_bf16 v[112:115], v[186:189], v[194:197], v[112:115]
	v_mfma_f32_16x16x32_bf16 v[112:115], v[190:193], v[198:201], v[112:115]
	v_mfma_f32_16x16x32_bf16 v[96:99], v[186:189], v[202:205], v[96:99]
	v_mfma_f32_16x16x32_bf16 v[96:99], v[190:193], v[206:209], v[96:99]
	v_mfma_f32_16x16x32_bf16 v[80:83], v[186:189], v[210:213], v[80:83]
	v_mfma_f32_16x16x32_bf16 v[80:83], v[190:193], v[214:217], v[80:83]
	v_mfma_f32_16x16x32_bf16 v[64:67], v[186:189], v[218:221], v[64:67]
	v_mfma_f32_16x16x32_bf16 v[64:67], v[190:193], v[222:225], v[64:67]
	s_setprio 0
	s_barrier
	s_add_i32 s57, s49, s37
	v_lshl_add_u64 v[226:227], s[22:23], 0, v[130:131]
	s_mov_b32 m0, s57
	ds_read_b128 v[194:197], v162 offset:16384
	ds_read_b128 v[198:201], v162 offset:17408
	ds_read_b128 v[202:205], v162 offset:18432
	ds_read_b128 v[206:209], v162 offset:19456
	ds_read_b128 v[210:213], v162 offset:20480
	ds_read_b128 v[214:217], v162 offset:21504
	ds_read_b128 v[218:221], v162 offset:22528
	ds_read_b128 v[222:225], v162 offset:23552
	global_load_lds_dwordx4 v[226:227], off
	s_add_i32 m0, s57, 0x2000
	s_add_u32 s58, s22, 0x84000
	v_lshl_add_u64 v[228:229], s[22:23], 0, v[134:135]
	s_addc_u32 s59, s23, 0
	s_add_i32 s57, s50, s37
	global_load_lds_dwordx4 v[228:229], off
	v_lshl_add_u64 v[230:231], s[58:59], 0, v[130:131]
	s_mov_b32 m0, s57
	v_lshl_add_u64 v[232:233], s[24:25], 0, v[132:133]
	global_load_lds_dwordx4 v[230:231], off
	v_lshl_add_u64 v[230:231], s[58:59], 0, v[134:135]
	s_add_i32 m0, s57, 0x2000
	s_nop 0
	global_load_lds_dwordx4 v[230:231], off
	v_lshl_add_u64 v[230:231], s[24:25], 0, v[128:129]
	s_mov_b32 m0, s40
	s_nop 0
	global_load_lds_dwordx4 v[230:231], off
	s_mov_b32 m0, s41
	s_nop 0
	global_load_lds_dwordx4 v[232:233], off
	s_waitcnt vmcnt(8)
	s_waitcnt lgkmcnt(0)
	s_barrier
; #define PG8_STAGE(bufoff, gbase, voff) do { _Pragma("unroll") for (int _i = 0; _i < 2; ++_i) \
;         __builtin_amdgcn_global_load_lds((const unsigned*)((const char*)(gbase) + (voff)[_i]), (LAS unsigned*)(lds + (bufoff) + ldsw + _i * 8192), 16, 0, 0); } while (0)
; #define PG8_LDA(dst, b, h) do { _Pragma("unroll") for (int m = 0; m < 4; ++m) _Pragma("unroll") for (int k = 0; k < 2; ++k) dst[m][k] = *(const LAS bf16x8*)(lds + PG8_SA(b, h) + aoff + m * 2048 + k * 1024); } while (0)
; #define PG8_LDB(dst, b, h) do { _Pragma("unroll") for (int n = 0; n < 2; ++n) _Pragma("unroll") for (int k = 0; k < 2; ++k) dst[n][k] = *(const LAS bf16x8*)(lds + PG8_SB(b, h) + boff + n * 2048 + k * 1024); } while (0)
; #define PG8_MMA(ai, bj, At, Bt) do { __builtin_amdgcn_s_setprio(1); _Pragma("unroll") for (int m = 0; m < 4; ++m) _Pragma("unroll") for (int n = 0; n < 2; ++n) _Pragma("unroll") for (int k = 0; k < 2; ++k) \
;         acc[ai][bj][m][n] = __builtin_amdgcn_mfma_f32_16x16x32_bf16(Bt[n][k], At[m][k], acc[ai][bj][m][n], 0, 0, 0); __builtin_amdgcn_s_setprio(0); } while (0)
; #define PG8_WAIT_V(n) asm volatile("s_waitcnt vmcnt(" #n ")" ::: "memory")
; #define PG8_WAIT_L(n) asm volatile("s_waitcnt lgkmcnt(" #n ")" ::: "memory")
; #define PG8_BAR __builtin_amdgcn_s_barrier()
; #define PG8_SCHED __builtin_amdgcn_sched_barrier(0)
; template <class EpiT>
; __device__ __forceinline__ void gemm_phase(LAS unsigned char* lds, const Gemm g, const StaticOrder& S, const EpiT& E) {
;     ...
;             PG8_WAIT_V(8); PG8_WAIT_L(0); PG8_BAR; PG8_MMA(1, 0, At, B0); PG8_MMA(1, 1, At, B1); PG8_BAR; PG8_SCHED;
;             PG8_LDB(B0, 1, 0); PG8_LDB(B1, 1, 1); PG8_SCHED; PG8_LDA(At, 1, 0); PG8_STAGE(PG8_SA(0, 1), a2 + hstepA, voffA);
;             PG8_WAIT_V(8); PG8_WAIT_L(0); PG8_BAR; PG8_MMA(0, 0, At, B0); PG8_MMA(0, 1, At, B1); PG8_BAR; PG8_SCHED;
	s_setprio 1
	s_waitcnt lgkmcnt(0)
	v_mfma_f32_16x16x32_bf16 v[60:63], v[156:159], v[194:197], v[60:63]
	v_mfma_f32_16x16x32_bf16 v[60:63], v[164:167], v[198:201], v[60:63]
	v_mfma_f32_16x16x32_bf16 v[44:47], v[156:159], v[202:205], v[44:47]
	v_mfma_f32_16x16x32_bf16 v[44:47], v[164:167], v[206:209], v[44:47]
	v_mfma_f32_16x16x32_bf16 v[28:31], v[156:159], v[210:213], v[28:31]
	v_mfma_f32_16x16x32_bf16 v[28:31], v[164:167], v[214:217], v[28:31]
	v_mfma_f32_16x16x32_bf16 v[12:15], v[156:159], v[218:221], v[12:15]
	v_mfma_f32_16x16x32_bf16 v[12:15], v[164:167], v[222:225], v[12:15]
	v_mfma_f32_16x16x32_bf16 v[56:59], v[170:173], v[194:197], v[56:59]
	v_mfma_f32_16x16x32_bf16 v[56:59], v[174:177], v[198:201], v[56:59]
	v_mfma_f32_16x16x32_bf16 v[40:43], v[170:173], v[202:205], v[40:43]
	v_mfma_f32_16x16x32_bf16 v[40:43], v[174:177], v[206:209], v[40:43]
	v_mfma_f32_16x16x32_bf16 v[24:27], v[170:173], v[210:213], v[24:27]
	v_mfma_f32_16x16x32_bf16 v[24:27], v[174:177], v[214:217], v[24:27]
	v_mfma_f32_16x16x32_bf16 v[8:11], v[170:173], v[218:221], v[8:11]
	v_mfma_f32_16x16x32_bf16 v[8:11], v[174:177], v[222:225], v[8:11]
	s_setprio 0
	s_setprio 1
	v_mfma_f32_16x16x32_bf16 v[52:55], v[178:181], v[194:197], v[52:55]
	v_mfma_f32_16x16x32_bf16 v[52:55], v[182:185], v[198:201], v[52:55]
	v_mfma_f32_16x16x32_bf16 v[36:39], v[178:181], v[202:205], v[36:39]
	v_mfma_f32_16x16x32_bf16 v[36:39], v[182:185], v[206:209], v[36:39]
	v_mfma_f32_16x16x32_bf16 v[20:23], v[178:181], v[210:213], v[20:23]
	v_mfma_f32_16x16x32_bf16 v[20:23], v[182:185], v[214:217], v[20:23]
	v_mfma_f32_16x16x32_bf16 v[4:7], v[178:181], v[218:221], v[4:7]
	v_mfma_f32_16x16x32_bf16 v[4:7], v[182:185], v[222:225], v[4:7]
	v_mfma_f32_16x16x32_bf16 v[48:51], v[186:189], v[194:197], v[48:51]
	v_mfma_f32_16x16x32_bf16 v[48:51], v[190:193], v[198:201], v[48:51]
	v_mfma_f32_16x16x32_bf16 v[32:35], v[186:189], v[202:205], v[32:35]
	v_mfma_f32_16x16x32_bf16 v[32:35], v[190:193], v[206:209], v[32:35]
	v_mfma_f32_16x16x32_bf16 v[16:19], v[186:189], v[210:213], v[16:19]
	v_mfma_f32_16x16x32_bf16 v[16:19], v[190:193], v[214:217], v[16:19]
	v_mfma_f32_16x16x32_bf16 v[0:3], v[186:189], v[218:221], v[0:3]
	v_mfma_f32_16x16x32_bf16 v[0:3], v[190:193], v[222:225], v[0:3]
	s_setprio 0
	s_barrier
	s_add_i32 s57, 0, 0x18000
	v_add_u32_e32 v136, s57, v149
	s_add_i32 s58, 0, 0x1c000
	ds_read_b128 v[156:159], v136
	ds_read_b128 v[164:167], v136 offset:1024
	ds_read_b128 v[170:173], v136 offset:2048
	ds_read_b128 v[174:177], v136 offset:3072
	v_add_u32_e32 v136, s58, v149
	ds_read_b128 v[178:181], v136
	ds_read_b128 v[182:185], v136 offset:1024
	ds_read_b128 v[186:189], v136 offset:2048
	ds_read_b128 v[190:193], v136 offset:3072
	s_add_u32 s24, s24, 0x84000
	s_addc_u32 s25, s25, 0
	s_mov_b32 m0, s42
	v_lshl_add_u64 v[234:235], s[24:25], 0, v[128:129]
	ds_read_b128 v[194:197], v162 offset:32768
	ds_read_b128 v[198:201], v162 offset:33792
	ds_read_b128 v[202:205], v162 offset:34816
	ds_read_b128 v[206:209], v162 offset:35840
	ds_read_b128 v[210:213], v162 offset:36864
	ds_read_b128 v[214:217], v162 offset:37888
	ds_read_b128 v[218:221], v162 offset:38912
	ds_read_b128 v[222:225], v162 offset:39936
	global_load_lds_dwordx4 v[234:235], off
	v_lshl_add_u64 v[234:235], s[24:25], 0, v[132:133]
	s_mov_b32 m0, s43
	s_nop 0
	global_load_lds_dwordx4 v[234:235], off
	s_waitcnt vmcnt(8)
	s_waitcnt lgkmcnt(0)
	s_barrier
	s_setprio 1
	s_waitcnt lgkmcnt(0)
	v_mfma_f32_16x16x32_bf16 v[124:127], v[156:159], v[194:197], v[124:127]
	v_mfma_f32_16x16x32_bf16 v[124:127], v[164:167], v[198:201], v[124:127]
	v_mfma_f32_16x16x32_bf16 v[108:111], v[156:159], v[202:205], v[108:111]
	v_mfma_f32_16x16x32_bf16 v[108:111], v[164:167], v[206:209], v[108:111]
	v_mfma_f32_16x16x32_bf16 v[92:95], v[156:159], v[210:213], v[92:95]
	v_mfma_f32_16x16x32_bf16 v[92:95], v[164:167], v[214:217], v[92:95]
	v_mfma_f32_16x16x32_bf16 v[76:79], v[156:159], v[218:221], v[76:79]
	v_mfma_f32_16x16x32_bf16 v[76:79], v[164:167], v[222:225], v[76:79]
	v_mfma_f32_16x16x32_bf16 v[120:123], v[170:173], v[194:197], v[120:123]
	v_mfma_f32_16x16x32_bf16 v[120:123], v[174:177], v[198:201], v[120:123]
	v_mfma_f32_16x16x32_bf16 v[104:107], v[170:173], v[202:205], v[104:107]
	v_mfma_f32_16x16x32_bf16 v[104:107], v[174:177], v[206:209], v[104:107]
	v_mfma_f32_16x16x32_bf16 v[88:91], v[170:173], v[210:213], v[88:91]
	v_mfma_f32_16x16x32_bf16 v[88:91], v[174:177], v[214:217], v[88:91]
	v_mfma_f32_16x16x32_bf16 v[72:75], v[170:173], v[218:221], v[72:75]
	v_mfma_f32_16x16x32_bf16 v[72:75], v[174:177], v[222:225], v[72:75]
	s_setprio 0
	s_setprio 1
	v_mfma_f32_16x16x32_bf16 v[116:119], v[178:181], v[194:197], v[116:119]
	v_mfma_f32_16x16x32_bf16 v[116:119], v[182:185], v[198:201], v[116:119]
	v_mfma_f32_16x16x32_bf16 v[100:103], v[178:181], v[202:205], v[100:103]
	v_mfma_f32_16x16x32_bf16 v[100:103], v[182:185], v[206:209], v[100:103]
	v_mfma_f32_16x16x32_bf16 v[84:87], v[178:181], v[210:213], v[84:87]
	v_mfma_f32_16x16x32_bf16 v[84:87], v[182:185], v[214:217], v[84:87]
	v_mfma_f32_16x16x32_bf16 v[68:71], v[178:181], v[218:221], v[68:71]
	v_mfma_f32_16x16x32_bf16 v[68:71], v[182:185], v[222:225], v[68:71]
	v_mfma_f32_16x16x32_bf16 v[112:115], v[186:189], v[194:197], v[112:115]
	v_mfma_f32_16x16x32_bf16 v[112:115], v[190:193], v[198:201], v[112:115]
	v_mfma_f32_16x16x32_bf16 v[96:99], v[186:189], v[202:205], v[96:99]
	v_mfma_f32_16x16x32_bf16 v[96:99], v[190:193], v[206:209], v[96:99]
	v_mfma_f32_16x16x32_bf16 v[80:83], v[186:189], v[210:213], v[80:83]
	v_mfma_f32_16x16x32_bf16 v[80:83], v[190:193], v[214:217], v[80:83]
	v_mfma_f32_16x16x32_bf16 v[64:67], v[186:189], v[218:221], v[64:67]
	v_mfma_f32_16x16x32_bf16 v[64:67], v[190:193], v[222:225], v[64:67]
	s_setprio 0
	s_barrier
; #define PG8_STAGE(bufoff, gbase, voff) do { _Pragma("unroll") for (int _i = 0; _i < 2; ++_i) \
;         __builtin_amdgcn_global_load_lds((const unsigned*)((const char*)(gbase) + (voff)[_i]), (LAS unsigned*)(lds + (bufoff) + ldsw + _i * 8192), 16, 0, 0); } while (0)
; #define PG8_LDA(dst, b, h) do { _Pragma("unroll") for (int m = 0; m < 4; ++m) _Pragma("unroll") for (int k = 0; k < 2; ++k) dst[m][k] = *(const LAS bf16x8*)(lds + PG8_SA(b, h) + aoff + m * 2048 + k * 1024); } while (0)
; #define PG8_MMA(ai, bj, At, Bt) do { __builtin_amdgcn_s_setprio(1); _Pragma("unroll") for (int m = 0; m < 4; ++m) _Pragma("unroll") for (int n = 0; n < 2; ++n) _Pragma("unroll") for (int k = 0; k < 2; ++k) \
;         acc[ai][bj][m][n] = __builtin_amdgcn_mfma_f32_16x16x32_bf16(Bt[n][k], At[m][k], acc[ai][bj][m][n], 0, 0, 0); __builtin_amdgcn_s_setprio(0); } while (0)
; #define PG8_WAIT_V(n) asm volatile("s_waitcnt vmcnt(" #n ")" ::: "memory")
; #define PG8_WAIT_L(n) asm volatile("s_waitcnt lgkmcnt(" #n ")" ::: "memory")
; #define PG8_BAR __builtin_amdgcn_s_barrier()
; #define PG8_SCHED __builtin_amdgcn_sched_barrier(0)
; template <class EpiT>
; __device__ __forceinline__ void gemm_phase(LAS unsigned char* lds, const Gemm g, const StaticOrder& S, const EpiT& E) {
;     ...
;             PG8_LDA(At, 1, 1); PG8_STAGE(PG8_SB(1, 0), b3, voffB); PG8_STAGE(PG8_SB(1, 1), b3 + hstepB, voffB); PG8_STAGE(PG8_SA(1, 0), a3, voffA);
;             PG8_WAIT_V(8); PG8_WAIT_L(0); PG8_BAR; PG8_MMA(1, 0, At, B0); PG8_MMA(1, 1, At, B1); PG8_BAR; PG8_SCHED;
;         }
;         if (wr == 0) PG8_BAR;
	s_add_i32 s24, s57, s37
	v_lshl_add_u64 v[226:227], v[226:227], 0, s[14:15]
	s_mov_b32 m0, s24
	ds_read_b128 v[194:197], v162 offset:49152
	ds_read_b128 v[198:201], v162 offset:50176
	ds_read_b128 v[202:205], v162 offset:51200
	ds_read_b128 v[206:209], v162 offset:52224
	ds_read_b128 v[210:213], v162 offset:53248
	ds_read_b128 v[214:217], v162 offset:54272
	ds_read_b128 v[218:221], v162 offset:55296
	ds_read_b128 v[222:225], v162 offset:56320
	global_load_lds_dwordx4 v[226:227], off
	s_add_i32 m0, s24, 0x2000
	s_add_u32 s22, s22, 0x84080
	v_lshl_add_u64 v[226:227], v[228:229], 0, s[14:15]
	s_addc_u32 s23, s23, 0
	s_add_i32 s24, s58, s37
	global_load_lds_dwordx4 v[226:227], off
	v_lshl_add_u64 v[226:227], s[22:23], 0, v[130:131]
	s_mov_b32 m0, s24
	s_nop 0
	global_load_lds_dwordx4 v[226:227], off
	v_lshl_add_u64 v[226:227], s[22:23], 0, v[134:135]
	s_add_i32 m0, s24, 0x2000
	s_nop 0
	global_load_lds_dwordx4 v[226:227], off
	v_lshl_add_u64 v[226:227], v[230:231], 0, s[14:15]
	s_mov_b32 m0, s44
	s_nop 0
	global_load_lds_dwordx4 v[226:227], off
	v_lshl_add_u64 v[226:227], v[232:233], 0, s[14:15]
	s_mov_b32 m0, s45
	s_nop 0
	global_load_lds_dwordx4 v[226:227], off
	s_waitcnt vmcnt(8)
	s_waitcnt lgkmcnt(0)
	s_barrier
	s_setprio 1
	s_waitcnt lgkmcnt(0)
	v_mfma_f32_16x16x32_bf16 v[60:63], v[156:159], v[194:197], v[60:63]
	v_mfma_f32_16x16x32_bf16 v[60:63], v[164:167], v[198:201], v[60:63]
	v_mfma_f32_16x16x32_bf16 v[44:47], v[156:159], v[202:205], v[44:47]
	v_mfma_f32_16x16x32_bf16 v[44:47], v[164:167], v[206:209], v[44:47]
	v_mfma_f32_16x16x32_bf16 v[28:31], v[156:159], v[210:213], v[28:31]
	v_mfma_f32_16x16x32_bf16 v[28:31], v[164:167], v[214:217], v[28:31]
	v_mfma_f32_16x16x32_bf16 v[12:15], v[156:159], v[218:221], v[12:15]
	v_mfma_f32_16x16x32_bf16 v[12:15], v[164:167], v[222:225], v[12:15]
	v_mfma_f32_16x16x32_bf16 v[56:59], v[170:173], v[194:197], v[56:59]
	v_mfma_f32_16x16x32_bf16 v[56:59], v[174:177], v[198:201], v[56:59]
	v_mfma_f32_16x16x32_bf16 v[40:43], v[170:173], v[202:205], v[40:43]
	v_mfma_f32_16x16x32_bf16 v[40:43], v[174:177], v[206:209], v[40:43]
	v_mfma_f32_16x16x32_bf16 v[24:27], v[170:173], v[210:213], v[24:27]
	v_mfma_f32_16x16x32_bf16 v[24:27], v[174:177], v[214:217], v[24:27]
	v_mfma_f32_16x16x32_bf16 v[8:11], v[170:173], v[218:221], v[8:11]
	v_mfma_f32_16x16x32_bf16 v[8:11], v[174:177], v[222:225], v[8:11]
	s_setprio 0
	s_setprio 1
	v_mfma_f32_16x16x32_bf16 v[52:55], v[178:181], v[194:197], v[52:55]
	v_mfma_f32_16x16x32_bf16 v[52:55], v[182:185], v[198:201], v[52:55]
	v_mfma_f32_16x16x32_bf16 v[36:39], v[178:181], v[202:205], v[36:39]
	v_mfma_f32_16x16x32_bf16 v[36:39], v[182:185], v[206:209], v[36:39]
	v_mfma_f32_16x16x32_bf16 v[20:23], v[178:181], v[210:213], v[20:23]
	v_mfma_f32_16x16x32_bf16 v[20:23], v[182:185], v[214:217], v[20:23]
	v_mfma_f32_16x16x32_bf16 v[4:7], v[178:181], v[218:221], v[4:7]
	v_mfma_f32_16x16x32_bf16 v[4:7], v[182:185], v[222:225], v[4:7]
	v_mfma_f32_16x16x32_bf16 v[48:51], v[186:189], v[194:197], v[48:51]
	v_mfma_f32_16x16x32_bf16 v[48:51], v[190:193], v[198:201], v[48:51]
	v_mfma_f32_16x16x32_bf16 v[32:35], v[186:189], v[202:205], v[32:35]
	v_mfma_f32_16x16x32_bf16 v[32:35], v[190:193], v[206:209], v[32:35]
	v_mfma_f32_16x16x32_bf16 v[16:19], v[186:189], v[210:213], v[16:19]
	v_mfma_f32_16x16x32_bf16 v[16:19], v[190:193], v[214:217], v[16:19]
	v_mfma_f32_16x16x32_bf16 v[0:3], v[186:189], v[218:221], v[0:3]
	v_mfma_f32_16x16x32_bf16 v[0:3], v[190:193], v[222:225], v[0:3]
	s_setprio 0
	s_barrier
	s_add_i32 s56, s56, 2
	s_add_u32 s20, s20, 0x100
	s_addc_u32 s21, s21, 0
	s_add_u32 s8, s8, 0x100
	s_addc_u32 s39, s39, 0
	s_cmp_gt_u32 s56, 29
	s_cbranch_scc0 .LBB0_761
	s_and_b64 vcc, exec, s[16:17]
	s_cbranch_vccz .LBB0_764
	s_barrier

; #define PG8_STAGE(bufoff, gbase, voff) do { _Pragma("unroll") for (int _i = 0; _i < 2; ++_i) \
;         __builtin_amdgcn_global_load_lds((const unsigned*)((const char*)(gbase) + (voff)[_i]), (LAS unsigned*)(lds + (bufoff) + ldsw + _i * 8192), 16, 0, 0); } while (0)
; #define PG8_LDA(dst, b, h) do { _Pragma("unroll") for (int m = 0; m < 4; ++m) _Pragma("unroll") for (int k = 0; k < 2; ++k) dst[m][k] = *(const LAS bf16x8*)(lds + PG8_SA(b, h) + aoff + m * 2048 + k * 1024); } while (0)
; #define PG8_LDB(dst, b, h) do { _Pragma("unroll") for (int n = 0; n < 2; ++n) _Pragma("unroll") for (int k = 0; k < 2; ++k) dst[n][k] = *(const LAS bf16x8*)(lds + PG8_SB(b, h) + boff + n * 2048 + k * 1024); } while (0)
; #define PG8_MMA(ai, bj, At, Bt) do { __builtin_amdgcn_s_setprio(1); _Pragma("unroll") for (int m = 0; m < 4; ++m) _Pragma("unroll") for (int n = 0; n < 2; ++n) _Pragma("unroll") for (int k = 0; k < 2; ++k) \
;         acc[ai][bj][m][n] = __builtin_amdgcn_mfma_f32_16x16x32_bf16(Bt[n][k], At[m][k], acc[ai][bj][m][n], 0, 0, 0); __builtin_amdgcn_s_setprio(0); } while (0)
; #define PG8_WAIT_V(n) asm volatile("s_waitcnt vmcnt(" #n ")" ::: "memory")
; #define PG8_WAIT_L(n) asm volatile("s_waitcnt lgkmcnt(" #n ")" ::: "memory")
; #define PG8_BAR __builtin_amdgcn_s_barrier()
; #define PG8_SCHED __builtin_amdgcn_sched_barrier(0)
; template <class EpiT>
; __device__ __forceinline__ void gemm_phase(LAS unsigned char* lds, const Gemm g, const StaticOrder& S, const EpiT& E) {
;     ...
;         for (int t = 0; t < nt; t += 2) {
;             const bool last = (t == nt - 2);
;             const char* a1 = cA + (size_t)(t + 1) * kstep;
;             const char* a2 = last ? nA : cA + (size_t)(t + 2) * kstep; const char* b2 = last ? nB : cB + (size_t)(t + 2) * kstep;
;             const char* a3 = a2 + kstep; const char* b3 = b2 + kstep;
;             PG8_LDB(B0, 0, 0); PG8_LDB(B1, 0, 1); PG8_SCHED; PG8_LDA(At, 0, 0); PG8_STAGE(PG8_SA(1, 1), a1 + hstepA, voffA);
;             PG8_WAIT_V(8); PG8_WAIT_L(0); PG8_BAR; PG8_MMA(0, 0, At, B0); PG8_MMA(0, 1, At, B1); PG8_BAR; PG8_SCHED;
;             PG8_LDA(At, 0, 1); PG8_STAGE(PG8_SB(0, 0), b2, voffB); PG8_STAGE(PG8_SB(0, 1), b2 + hstepB, voffB); PG8_STAGE(PG8_SA(0, 0), a2, voffA);
;             PG8_WAIT_V(8); PG8_WAIT_L(0); PG8_BAR; PG8_MMA(1, 0, At, B0); PG8_MMA(1, 1, At, B1); PG8_BAR; PG8_SCHED;
.LBB0_1032:
	ds_read_b128 v[154:157], v150
	ds_read_b128 v[158:161], v150 offset:1024
	ds_read_b128 v[162:165], v150 offset:2048
	ds_read_b128 v[170:173], v150 offset:3072
	ds_read_b128 v[174:177], v151
	ds_read_b128 v[178:181], v151 offset:1024
	ds_read_b128 v[182:185], v151 offset:2048
	ds_read_b128 v[186:189], v151 offset:3072
	s_add_u32 s20, s18, 0xfff7c080
	s_addc_u32 s21, s19, -1
	s_cmp_eq_u32 s55, 28
	s_cselect_b32 s23, s5, s21
	s_cselect_b32 s22, s4, s20
	s_cselect_b32 s21, s17, s54
	s_cselect_b32 s20, s16, s53
	v_lshl_add_u64 v[166:167], s[18:19], 0, v[138:139]
	s_add_i32 m0, s37, 0xc000
	ds_read_b128 v[190:193], v152
	ds_read_b128 v[194:197], v152 offset:1024
	ds_read_b128 v[198:201], v152 offset:2048
	ds_read_b128 v[202:205], v152 offset:3072
	ds_read_b128 v[206:209], v152 offset:4096
	ds_read_b128 v[210:213], v152 offset:5120
	ds_read_b128 v[214:217], v152 offset:6144
	ds_read_b128 v[218:221], v152 offset:7168
	global_load_lds_dwordx4 v[166:167], off
	v_lshl_add_u64 v[166:167], s[18:19], 0, v[140:141]
	s_add_i32 m0, s37, 0xe000
	s_nop 0
	global_load_lds_dwordx4 v[166:167], off
	s_waitcnt vmcnt(8)
	s_waitcnt lgkmcnt(0)
	s_barrier
	s_setprio 1
	s_waitcnt lgkmcnt(0)
	v_mfma_f32_16x16x32_bf16 v[124:127], v[154:157], v[190:193], v[124:127]
	v_mfma_f32_16x16x32_bf16 v[124:127], v[158:161], v[194:197], v[124:127]
	v_mfma_f32_16x16x32_bf16 v[108:111], v[154:157], v[198:201], v[108:111]
	v_mfma_f32_16x16x32_bf16 v[108:111], v[158:161], v[202:205], v[108:111]
	v_mfma_f32_16x16x32_bf16 v[92:95], v[154:157], v[206:209], v[92:95]
	v_mfma_f32_16x16x32_bf16 v[92:95], v[158:161], v[210:213], v[92:95]
	v_mfma_f32_16x16x32_bf16 v[76:79], v[154:157], v[214:217], v[76:79]
	v_mfma_f32_16x16x32_bf16 v[76:79], v[158:161], v[218:221], v[76:79]
	v_mfma_f32_16x16x32_bf16 v[120:123], v[162:165], v[190:193], v[120:123]
	v_mfma_f32_16x16x32_bf16 v[120:123], v[170:173], v[194:197], v[120:123]
	v_mfma_f32_16x16x32_bf16 v[104:107], v[162:165], v[198:201], v[104:107]
	v_mfma_f32_16x16x32_bf16 v[104:107], v[170:173], v[202:205], v[104:107]
	v_mfma_f32_16x16x32_bf16 v[88:91], v[162:165], v[206:209], v[88:91]
	v_mfma_f32_16x16x32_bf16 v[88:91], v[170:173], v[210:213], v[88:91]
	v_mfma_f32_16x16x32_bf16 v[72:75], v[162:165], v[214:217], v[72:75]
	v_mfma_f32_16x16x32_bf16 v[72:75], v[170:173], v[218:221], v[72:75]
	s_setprio 0
	s_setprio 1
	v_mfma_f32_16x16x32_bf16 v[116:119], v[174:177], v[190:193], v[116:119]
	v_mfma_f32_16x16x32_bf16 v[116:119], v[178:181], v[194:197], v[116:119]
	v_mfma_f32_16x16x32_bf16 v[100:103], v[174:177], v[198:201], v[100:103]
	v_mfma_f32_16x16x32_bf16 v[100:103], v[178:181], v[202:205], v[100:103]
	v_mfma_f32_16x16x32_bf16 v[84:87], v[174:177], v[206:209], v[84:87]
	v_mfma_f32_16x16x32_bf16 v[84:87], v[178:181], v[210:213], v[84:87]
	v_mfma_f32_16x16x32_bf16 v[68:71], v[174:177], v[214:217], v[68:71]
	v_mfma_f32_16x16x32_bf16 v[68:71], v[178:181], v[218:221], v[68:71]
	v_mfma_f32_16x16x32_bf16 v[112:115], v[182:185], v[190:193], v[112:115]
	v_mfma_f32_16x16x32_bf16 v[112:115], v[186:189], v[194:197], v[112:115]
	v_mfma_f32_16x16x32_bf16 v[96:99], v[182:185], v[198:201], v[96:99]
	v_mfma_f32_16x16x32_bf16 v[96:99], v[186:189], v[202:205], v[96:99]
	v_mfma_f32_16x16x32_bf16 v[80:83], v[182:185], v[206:209], v[80:83]
	v_mfma_f32_16x16x32_bf16 v[80:83], v[186:189], v[210:213], v[80:83]
	v_mfma_f32_16x16x32_bf16 v[64:67], v[182:185], v[214:217], v[64:67]
	v_mfma_f32_16x16x32_bf16 v[64:67], v[186:189], v[218:221], v[64:67]
	s_setprio 0
	s_barrier
	s_add_i32 s56, s46, s36
	v_lshl_add_u64 v[166:167], s[20:21], 0, v[130:131]
	s_mov_b32 m0, s56
	ds_read_b128 v[190:193], v152 offset:16384
	ds_read_b128 v[194:197], v152 offset:17408
	ds_read_b128 v[198:201], v152 offset:18432
	ds_read_b128 v[202:205], v152 offset:19456
	ds_read_b128 v[206:209], v152 offset:20480
	ds_read_b128 v[210:213], v152 offset:21504
	ds_read_b128 v[214:217], v152 offset:22528
	ds_read_b128 v[218:221], v152 offset:23552
	global_load_lds_dwordx4 v[166:167], off
	s_add_i32 m0, s56, 0x2000
	s_add_u32 s56, s20, 0x84000
	v_lshl_add_u64 v[222:223], s[20:21], 0, v[134:135]
	s_addc_u32 s57, s21, 0
	s_add_i32 s58, s47, s36
	global_load_lds_dwordx4 v[222:223], off
	v_lshl_add_u64 v[224:225], s[56:57], 0, v[130:131]
	s_mov_b32 m0, s58
	v_lshl_add_u64 v[226:227], s[22:23], 0, v[132:133]
	global_load_lds_dwordx4 v[224:225], off
	v_lshl_add_u64 v[224:225], s[56:57], 0, v[134:135]
	s_add_i32 m0, s58, 0x2000
	s_nop 0
	global_load_lds_dwordx4 v[224:225], off
	v_lshl_add_u64 v[224:225], s[22:23], 0, v[128:129]
	s_mov_b32 m0, s37
	s_nop 0
	global_load_lds_dwordx4 v[224:225], off
	s_mov_b32 m0, s38
	s_nop 0
	global_load_lds_dwordx4 v[226:227], off
	s_waitcnt vmcnt(8)
	s_waitcnt lgkmcnt(0)
	s_barrier
; #define PG8_STAGE(bufoff, gbase, voff) do { _Pragma("unroll") for (int _i = 0; _i < 2; ++_i) \
;         __builtin_amdgcn_global_load_lds((const unsigned*)((const char*)(gbase) + (voff)[_i]), (LAS unsigned*)(lds + (bufoff) + ldsw + _i * 8192), 16, 0, 0); } while (0)
; #define PG8_LDA(dst, b, h) do { _Pragma("unroll") for (int m = 0; m < 4; ++m) _Pragma("unroll") for (int k = 0; k < 2; ++k) dst[m][k] = *(const LAS bf16x8*)(lds + PG8_SA(b, h) + aoff + m * 2048 + k * 1024); } while (0)
; #define PG8_LDB(dst, b, h) do { _Pragma("unroll") for (int n = 0; n < 2; ++n) _Pragma("unroll") for (int k = 0; k < 2; ++k) dst[n][k] = *(const LAS bf16x8*)(lds + PG8_SB(b, h) + boff + n * 2048 + k * 1024); } while (0)
; #define PG8_MMA(ai, bj, At, Bt) do { __builtin_amdgcn_s_setprio(1); _Pragma("unroll") for (int m = 0; m < 4; ++m) _Pragma("unroll") for (int n = 0; n < 2; ++n) _Pragma("unroll") for (int k = 0; k < 2; ++k) \
;         acc[ai][bj][m][n] = __builtin_amdgcn_mfma_f32_16x16x32_bf16(Bt[n][k], At[m][k], acc[ai][bj][m][n], 0, 0, 0); __builtin_amdgcn_s_setprio(0); } while (0)
; #define PG8_WAIT_V(n) asm volatile("s_waitcnt vmcnt(" #n ")" ::: "memory")
; #define PG8_WAIT_L(n) asm volatile("s_waitcnt lgkmcnt(" #n ")" ::: "memory")
; #define PG8_BAR __builtin_amdgcn_s_barrier()
; #define PG8_SCHED __builtin_amdgcn_sched_barrier(0)
; template <class EpiT>
; __device__ __forceinline__ void gemm_phase(LAS unsigned char* lds, const Gemm g, const StaticOrder& S, const EpiT& E) {
;     ...
;             PG8_WAIT_V(8); PG8_WAIT_L(0); PG8_BAR; PG8_MMA(1, 0, At, B0); PG8_MMA(1, 1, At, B1); PG8_BAR; PG8_SCHED;
;             PG8_LDB(B0, 1, 0); PG8_LDB(B1, 1, 1); PG8_SCHED; PG8_LDA(At, 1, 0); PG8_STAGE(PG8_SA(0, 1), a2 + hstepA, voffA);
;             PG8_WAIT_V(8); PG8_WAIT_L(0); PG8_BAR; PG8_MMA(0, 0, At, B0); PG8_MMA(0, 1, At, B1); PG8_BAR; PG8_SCHED;
	s_setprio 1
	s_waitcnt lgkmcnt(0)
	v_mfma_f32_16x16x32_bf16 v[60:63], v[154:157], v[190:193], v[60:63]
	v_mfma_f32_16x16x32_bf16 v[60:63], v[158:161], v[194:197], v[60:63]
	v_mfma_f32_16x16x32_bf16 v[44:47], v[154:157], v[198:201], v[44:47]
	v_mfma_f32_16x16x32_bf16 v[44:47], v[158:161], v[202:205], v[44:47]
	v_mfma_f32_16x16x32_bf16 v[28:31], v[154:157], v[206:209], v[28:31]
	v_mfma_f32_16x16x32_bf16 v[28:31], v[158:161], v[210:213], v[28:31]
	v_mfma_f32_16x16x32_bf16 v[12:15], v[154:157], v[214:217], v[12:15]
	v_mfma_f32_16x16x32_bf16 v[12:15], v[158:161], v[218:221], v[12:15]
	v_mfma_f32_16x16x32_bf16 v[56:59], v[162:165], v[190:193], v[56:59]
	v_mfma_f32_16x16x32_bf16 v[56:59], v[170:173], v[194:197], v[56:59]
	v_mfma_f32_16x16x32_bf16 v[40:43], v[162:165], v[198:201], v[40:43]
	v_mfma_f32_16x16x32_bf16 v[40:43], v[170:173], v[202:205], v[40:43]
	v_mfma_f32_16x16x32_bf16 v[24:27], v[162:165], v[206:209], v[24:27]
	v_mfma_f32_16x16x32_bf16 v[24:27], v[170:173], v[210:213], v[24:27]
	v_mfma_f32_16x16x32_bf16 v[8:11], v[162:165], v[214:217], v[8:11]
	v_mfma_f32_16x16x32_bf16 v[8:11], v[170:173], v[218:221], v[8:11]
	s_setprio 0
	s_setprio 1
	v_mfma_f32_16x16x32_bf16 v[52:55], v[174:177], v[190:193], v[52:55]
	v_mfma_f32_16x16x32_bf16 v[52:55], v[178:181], v[194:197], v[52:55]
	v_mfma_f32_16x16x32_bf16 v[36:39], v[174:177], v[198:201], v[36:39]
	v_mfma_f32_16x16x32_bf16 v[36:39], v[178:181], v[202:205], v[36:39]
	v_mfma_f32_16x16x32_bf16 v[20:23], v[174:177], v[206:209], v[20:23]
	v_mfma_f32_16x16x32_bf16 v[20:23], v[178:181], v[210:213], v[20:23]
	v_mfma_f32_16x16x32_bf16 v[4:7], v[174:177], v[214:217], v[4:7]
	v_mfma_f32_16x16x32_bf16 v[4:7], v[178:181], v[218:221], v[4:7]
	v_mfma_f32_16x16x32_bf16 v[48:51], v[182:185], v[190:193], v[48:51]
	v_mfma_f32_16x16x32_bf16 v[48:51], v[186:189], v[194:197], v[48:51]
	v_mfma_f32_16x16x32_bf16 v[32:35], v[182:185], v[198:201], v[32:35]
	v_mfma_f32_16x16x32_bf16 v[32:35], v[186:189], v[202:205], v[32:35]
	v_mfma_f32_16x16x32_bf16 v[16:19], v[182:185], v[206:209], v[16:19]
	v_mfma_f32_16x16x32_bf16 v[16:19], v[186:189], v[210:213], v[16:19]
	v_mfma_f32_16x16x32_bf16 v[0:3], v[182:185], v[214:217], v[0:3]
	v_mfma_f32_16x16x32_bf16 v[0:3], v[186:189], v[218:221], v[0:3]
	s_setprio 0
	s_barrier
	s_add_i32 s56, 0, 0x18000
	s_add_i32 s57, 0, 0x1c000
	v_add_u32_e32 v170, s56, v146
	v_add_u32_e32 v186, s57, v146
	ds_read_b128 v[154:157], v170
	ds_read_b128 v[158:161], v170 offset:1024
	ds_read_b128 v[162:165], v170 offset:2048
	ds_read_b128 v[170:173], v170 offset:3072
	ds_read_b128 v[174:177], v186
	ds_read_b128 v[178:181], v186 offset:1024
	ds_read_b128 v[182:185], v186 offset:2048
	ds_read_b128 v[186:189], v186 offset:3072
	s_add_u32 s22, s22, 0x84000
	s_addc_u32 s23, s23, 0
	s_mov_b32 m0, s39
	v_lshl_add_u64 v[228:229], s[22:23], 0, v[128:129]
	ds_read_b128 v[190:193], v152 offset:32768
	ds_read_b128 v[194:197], v152 offset:33792
	ds_read_b128 v[198:201], v152 offset:34816
	ds_read_b128 v[202:205], v152 offset:35840
	ds_read_b128 v[206:209], v152 offset:36864
	ds_read_b128 v[210:213], v152 offset:37888
	ds_read_b128 v[214:217], v152 offset:38912
	ds_read_b128 v[218:221], v152 offset:39936
	global_load_lds_dwordx4 v[228:229], off
	v_lshl_add_u64 v[228:229], s[22:23], 0, v[132:133]
	s_mov_b32 m0, s40
	s_nop 0
	global_load_lds_dwordx4 v[228:229], off
	s_waitcnt vmcnt(8)
	s_waitcnt lgkmcnt(0)
	s_barrier
	s_setprio 1
	s_waitcnt lgkmcnt(0)
	v_mfma_f32_16x16x32_bf16 v[124:127], v[154:157], v[190:193], v[124:127]
	v_mfma_f32_16x16x32_bf16 v[124:127], v[158:161], v[194:197], v[124:127]
	v_mfma_f32_16x16x32_bf16 v[108:111], v[154:157], v[198:201], v[108:111]
	v_mfma_f32_16x16x32_bf16 v[108:111], v[158:161], v[202:205], v[108:111]
	v_mfma_f32_16x16x32_bf16 v[92:95], v[154:157], v[206:209], v[92:95]
	v_mfma_f32_16x16x32_bf16 v[92:95], v[158:161], v[210:213], v[92:95]
	v_mfma_f32_16x16x32_bf16 v[76:79], v[154:157], v[214:217], v[76:79]
	v_mfma_f32_16x16x32_bf16 v[76:79], v[158:161], v[218:221], v[76:79]
	v_mfma_f32_16x16x32_bf16 v[120:123], v[162:165], v[190:193], v[120:123]
	v_mfma_f32_16x16x32_bf16 v[120:123], v[170:173], v[194:197], v[120:123]
	v_mfma_f32_16x16x32_bf16 v[104:107], v[162:165], v[198:201], v[104:107]
	v_mfma_f32_16x16x32_bf16 v[104:107], v[170:173], v[202:205], v[104:107]
	v_mfma_f32_16x16x32_bf16 v[88:91], v[162:165], v[206:209], v[88:91]
	v_mfma_f32_16x16x32_bf16 v[88:91], v[170:173], v[210:213], v[88:91]
	v_mfma_f32_16x16x32_bf16 v[72:75], v[162:165], v[214:217], v[72:75]
	v_mfma_f32_16x16x32_bf16 v[72:75], v[170:173], v[218:221], v[72:75]
	s_setprio 0
	s_setprio 1
	v_mfma_f32_16x16x32_bf16 v[116:119], v[174:177], v[190:193], v[116:119]
	v_mfma_f32_16x16x32_bf16 v[116:119], v[178:181], v[194:197], v[116:119]
	v_mfma_f32_16x16x32_bf16 v[100:103], v[174:177], v[198:201], v[100:103]
	v_mfma_f32_16x16x32_bf16 v[100:103], v[178:181], v[202:205], v[100:103]
	v_mfma_f32_16x16x32_bf16 v[84:87], v[174:177], v[206:209], v[84:87]
	v_mfma_f32_16x16x32_bf16 v[84:87], v[178:181], v[210:213], v[84:87]
	v_mfma_f32_16x16x32_bf16 v[68:71], v[174:177], v[214:217], v[68:71]
	v_mfma_f32_16x16x32_bf16 v[68:71], v[178:181], v[218:221], v[68:71]
	v_mfma_f32_16x16x32_bf16 v[112:115], v[182:185], v[190:193], v[112:115]
	v_mfma_f32_16x16x32_bf16 v[112:115], v[186:189], v[194:197], v[112:115]
	v_mfma_f32_16x16x32_bf16 v[96:99], v[182:185], v[198:201], v[96:99]
	v_mfma_f32_16x16x32_bf16 v[96:99], v[186:189], v[202:205], v[96:99]
	v_mfma_f32_16x16x32_bf16 v[80:83], v[182:185], v[206:209], v[80:83]
	v_mfma_f32_16x16x32_bf16 v[80:83], v[186:189], v[210:213], v[80:83]
	v_mfma_f32_16x16x32_bf16 v[64:67], v[182:185], v[214:217], v[64:67]
	v_mfma_f32_16x16x32_bf16 v[64:67], v[186:189], v[218:221], v[64:67]
	s_setprio 0
	s_barrier
; #define PG8_STAGE(bufoff, gbase, voff) do { _Pragma("unroll") for (int _i = 0; _i < 2; ++_i) \
;         __builtin_amdgcn_global_load_lds((const unsigned*)((const char*)(gbase) + (voff)[_i]), (LAS unsigned*)(lds + (bufoff) + ldsw + _i * 8192), 16, 0, 0); } while (0)
; #define PG8_LDA(dst, b, h) do { _Pragma("unroll") for (int m = 0; m < 4; ++m) _Pragma("unroll") for (int k = 0; k < 2; ++k) dst[m][k] = *(const LAS bf16x8*)(lds + PG8_SA(b, h) + aoff + m * 2048 + k * 1024); } while (0)
; #define PG8_MMA(ai, bj, At, Bt) do { __builtin_amdgcn_s_setprio(1); _Pragma("unroll") for (int m = 0; m < 4; ++m) _Pragma("unroll") for (int n = 0; n < 2; ++n) _Pragma("unroll") for (int k = 0; k < 2; ++k) \
;         acc[ai][bj][m][n] = __builtin_amdgcn_mfma_f32_16x16x32_bf16(Bt[n][k], At[m][k], acc[ai][bj][m][n], 0, 0, 0); __builtin_amdgcn_s_setprio(0); } while (0)
; #define PG8_WAIT_V(n) asm volatile("s_waitcnt vmcnt(" #n ")" ::: "memory")
; #define PG8_WAIT_L(n) asm volatile("s_waitcnt lgkmcnt(" #n ")" ::: "memory")
; #define PG8_BAR __builtin_amdgcn_s_barrier()
; #define PG8_SCHED __builtin_amdgcn_sched_barrier(0)
; template <class EpiT>
; __device__ __forceinline__ void gemm_phase(LAS unsigned char* lds, const Gemm g, const StaticOrder& S, const EpiT& E) {
;     ...
;             PG8_LDA(At, 1, 1); PG8_STAGE(PG8_SB(1, 0), b3, voffB); PG8_STAGE(PG8_SB(1, 1), b3 + hstepB, voffB); PG8_STAGE(PG8_SA(1, 0), a3, voffA);
;             PG8_WAIT_V(8); PG8_WAIT_L(0); PG8_BAR; PG8_MMA(1, 0, At, B0); PG8_MMA(1, 1, At, B1); PG8_BAR; PG8_SCHED;
;         }
;         if (wr == 0) PG8_BAR;
	s_add_i32 s22, s56, s36
	v_lshl_add_u64 v[166:167], v[166:167], 0, s[12:13]
	s_mov_b32 m0, s22
	ds_read_b128 v[190:193], v152 offset:49152
	ds_read_b128 v[194:197], v152 offset:50176
	ds_read_b128 v[198:201], v152 offset:51200
	ds_read_b128 v[202:205], v152 offset:52224
	ds_read_b128 v[206:209], v152 offset:53248
	ds_read_b128 v[210:213], v152 offset:54272
	ds_read_b128 v[214:217], v152 offset:55296
	ds_read_b128 v[218:221], v152 offset:56320
	global_load_lds_dwordx4 v[166:167], off
	s_add_i32 m0, s22, 0x2000
	s_add_u32 s20, s20, 0x84080
	v_lshl_add_u64 v[166:167], v[222:223], 0, s[12:13]
	s_addc_u32 s21, s21, 0
	s_add_i32 s22, s57, s36
	global_load_lds_dwordx4 v[166:167], off
	v_lshl_add_u64 v[166:167], s[20:21], 0, v[130:131]
	s_mov_b32 m0, s22
	s_nop 0
	global_load_lds_dwordx4 v[166:167], off
	v_lshl_add_u64 v[166:167], s[20:21], 0, v[134:135]
	s_add_i32 m0, s22, 0x2000
	s_nop 0
	global_load_lds_dwordx4 v[166:167], off
	v_lshl_add_u64 v[166:167], v[224:225], 0, s[12:13]
	s_mov_b32 m0, s42
	s_nop 0
	global_load_lds_dwordx4 v[166:167], off
	v_lshl_add_u64 v[166:167], v[226:227], 0, s[12:13]
	s_mov_b32 m0, s43
	s_nop 0
	global_load_lds_dwordx4 v[166:167], off
	s_waitcnt vmcnt(8)
	s_waitcnt lgkmcnt(0)
	s_barrier
	s_setprio 1
	s_waitcnt lgkmcnt(0)
	v_mfma_f32_16x16x32_bf16 v[60:63], v[154:157], v[190:193], v[60:63]
	v_mfma_f32_16x16x32_bf16 v[60:63], v[158:161], v[194:197], v[60:63]
	v_mfma_f32_16x16x32_bf16 v[44:47], v[154:157], v[198:201], v[44:47]
	v_mfma_f32_16x16x32_bf16 v[44:47], v[158:161], v[202:205], v[44:47]
	v_mfma_f32_16x16x32_bf16 v[28:31], v[154:157], v[206:209], v[28:31]
	v_mfma_f32_16x16x32_bf16 v[28:31], v[158:161], v[210:213], v[28:31]
	v_mfma_f32_16x16x32_bf16 v[12:15], v[154:157], v[214:217], v[12:15]
	v_mfma_f32_16x16x32_bf16 v[12:15], v[158:161], v[218:221], v[12:15]
	v_mfma_f32_16x16x32_bf16 v[56:59], v[162:165], v[190:193], v[56:59]
	v_mfma_f32_16x16x32_bf16 v[56:59], v[170:173], v[194:197], v[56:59]
	v_mfma_f32_16x16x32_bf16 v[40:43], v[162:165], v[198:201], v[40:43]
	v_mfma_f32_16x16x32_bf16 v[40:43], v[170:173], v[202:205], v[40:43]
	v_mfma_f32_16x16x32_bf16 v[24:27], v[162:165], v[206:209], v[24:27]
	v_mfma_f32_16x16x32_bf16 v[24:27], v[170:173], v[210:213], v[24:27]
	v_mfma_f32_16x16x32_bf16 v[8:11], v[162:165], v[214:217], v[8:11]
	v_mfma_f32_16x16x32_bf16 v[8:11], v[170:173], v[218:221], v[8:11]
	s_setprio 0
	s_setprio 1
	v_mfma_f32_16x16x32_bf16 v[52:55], v[174:177], v[190:193], v[52:55]
	v_mfma_f32_16x16x32_bf16 v[52:55], v[178:181], v[194:197], v[52:55]
	v_mfma_f32_16x16x32_bf16 v[36:39], v[174:177], v[198:201], v[36:39]
	v_mfma_f32_16x16x32_bf16 v[36:39], v[178:181], v[202:205], v[36:39]
	v_mfma_f32_16x16x32_bf16 v[20:23], v[174:177], v[206:209], v[20:23]
	v_mfma_f32_16x16x32_bf16 v[20:23], v[178:181], v[210:213], v[20:23]
	v_mfma_f32_16x16x32_bf16 v[4:7], v[174:177], v[214:217], v[4:7]
	v_mfma_f32_16x16x32_bf16 v[4:7], v[178:181], v[218:221], v[4:7]
	v_mfma_f32_16x16x32_bf16 v[48:51], v[182:185], v[190:193], v[48:51]
	v_mfma_f32_16x16x32_bf16 v[48:51], v[186:189], v[194:197], v[48:51]
	v_mfma_f32_16x16x32_bf16 v[32:35], v[182:185], v[198:201], v[32:35]
	v_mfma_f32_16x16x32_bf16 v[32:35], v[186:189], v[202:205], v[32:35]
	v_mfma_f32_16x16x32_bf16 v[16:19], v[182:185], v[206:209], v[16:19]
	v_mfma_f32_16x16x32_bf16 v[16:19], v[186:189], v[210:213], v[16:19]
	v_mfma_f32_16x16x32_bf16 v[0:3], v[182:185], v[214:217], v[0:3]
	v_mfma_f32_16x16x32_bf16 v[0:3], v[186:189], v[218:221], v[0:3]
	s_setprio 0
	s_barrier
	s_add_i32 s55, s55, 2
	s_add_u32 s18, s18, 0x100
	s_addc_u32 s19, s19, 0
	s_add_u32 s53, s53, 0x100
	s_addc_u32 s54, s54, 0
	s_cmp_gt_u32 s55, 29
	s_cbranch_scc0 .LBB0_1032
	s_and_b64 vcc, exec, s[14:15]
	s_cbranch_vccz .LBB0_1035
	s_barrier

; #define PG8_STAGE(bufoff, gbase, voff) do { _Pragma("unroll") for (int _i = 0; _i < 2; ++_i) \
;         __builtin_amdgcn_global_load_lds((const unsigned*)((const char*)(gbase) + (voff)[_i]), (LAS unsigned*)(lds + (bufoff) + ldsw + _i * 8192), 16, 0, 0); } while (0)
; #define PG8_LDA(dst, b, h) do { _Pragma("unroll") for (int m = 0; m < 4; ++m) _Pragma("unroll") for (int k = 0; k < 2; ++k) dst[m][k] = *(const LAS bf16x8*)(lds + PG8_SA(b, h) + aoff + m * 2048 + k * 1024); } while (0)
; #define PG8_LDB(dst, b, h) do { _Pragma("unroll") for (int n = 0; n < 2; ++n) _Pragma("unroll") for (int k = 0; k < 2; ++k) dst[n][k] = *(const LAS bf16x8*)(lds + PG8_SB(b, h) + boff + n * 2048 + k * 1024); } while (0)
; #define PG8_MMA(ai, bj, At, Bt) do { __builtin_amdgcn_s_setprio(1); _Pragma("unroll") for (int m = 0; m < 4; ++m) _Pragma("unroll") for (int n = 0; n < 2; ++n) _Pragma("unroll") for (int k = 0; k < 2; ++k) \
;         acc[ai][bj][m][n] = __builtin_amdgcn_mfma_f32_16x16x32_bf16(Bt[n][k], At[m][k], acc[ai][bj][m][n], 0, 0, 0); __builtin_amdgcn_s_setprio(0); } while (0)
; #define PG8_WAIT_V(n) asm volatile("s_waitcnt vmcnt(" #n ")" ::: "memory")
; #define PG8_WAIT_L(n) asm volatile("s_waitcnt lgkmcnt(" #n ")" ::: "memory")
; #define PG8_BAR __builtin_amdgcn_s_barrier()
; #define PG8_SCHED __builtin_amdgcn_sched_barrier(0)
; template <class EpiT>
; __device__ __forceinline__ void gemm_phase(LAS unsigned char* lds, const Gemm g, const StaticOrder& S, const EpiT& E) {
;     ...
;         for (int t = 0; t < nt; t += 2) {
;             const bool last = (t == nt - 2);
;             const char* a1 = cA + (size_t)(t + 1) * kstep;
;             const char* a2 = last ? nA : cA + (size_t)(t + 2) * kstep; const char* b2 = last ? nB : cB + (size_t)(t + 2) * kstep;
;             const char* a3 = a2 + kstep; const char* b3 = b2 + kstep;
;             PG8_LDB(B0, 0, 0); PG8_LDB(B1, 0, 1); PG8_SCHED; PG8_LDA(At, 0, 0); PG8_STAGE(PG8_SA(1, 1), a1 + hstepA, voffA);
;             PG8_WAIT_V(8); PG8_WAIT_L(0); PG8_BAR; PG8_MMA(0, 0, At, B0); PG8_MMA(0, 1, At, B1); PG8_BAR; PG8_SCHED;
;             PG8_LDA(At, 0, 1); PG8_STAGE(PG8_SB(0, 0), b2, voffB); PG8_STAGE(PG8_SB(0, 1), b2 + hstepB, voffB); PG8_STAGE(PG8_SA(0, 0), a2, voffA);
;             PG8_WAIT_V(8); PG8_WAIT_L(0); PG8_BAR; PG8_MMA(1, 0, At, B0); PG8_MMA(1, 1, At, B1); PG8_BAR; PG8_SCHED;
.LBB0_1156:
	ds_read_b128 v[154:157], v150
	ds_read_b128 v[158:161], v150 offset:1024
	ds_read_b128 v[162:165], v150 offset:2048
	ds_read_b128 v[170:173], v150 offset:3072
	ds_read_b128 v[174:177], v151
	ds_read_b128 v[178:181], v151 offset:1024
	ds_read_b128 v[182:185], v151 offset:2048
	ds_read_b128 v[186:189], v151 offset:3072
	s_add_u32 s18, s16, 0xfff7c080
	s_addc_u32 s19, s17, -1
	s_cmp_eq_u32 s53, 28
	s_cselect_b32 s21, s3, s19
	s_cselect_b32 s20, s2, s18
	s_cselect_b32 s19, s15, s52
	s_cselect_b32 s18, s14, s51
	v_lshl_add_u64 v[144:145], s[16:17], 0, v[136:137]
	s_add_i32 m0, s36, 0xc000
	ds_read_b128 v[190:193], v152
	ds_read_b128 v[194:197], v152 offset:1024
	ds_read_b128 v[198:201], v152 offset:2048
	ds_read_b128 v[202:205], v152 offset:3072
	ds_read_b128 v[206:209], v152 offset:4096
	ds_read_b128 v[210:213], v152 offset:5120
	ds_read_b128 v[214:217], v152 offset:6144
	ds_read_b128 v[218:221], v152 offset:7168
	global_load_lds_dwordx4 v[144:145], off
	v_lshl_add_u64 v[144:145], s[16:17], 0, v[138:139]
	s_add_i32 m0, s36, 0xe000
	s_nop 0
	global_load_lds_dwordx4 v[144:145], off
	s_waitcnt vmcnt(8)
	s_waitcnt lgkmcnt(0)
	s_barrier
	s_setprio 1
	s_waitcnt lgkmcnt(0)
	v_mfma_f32_16x16x32_bf16 v[124:127], v[154:157], v[190:193], v[124:127]
	v_mfma_f32_16x16x32_bf16 v[124:127], v[158:161], v[194:197], v[124:127]
	v_mfma_f32_16x16x32_bf16 v[108:111], v[154:157], v[198:201], v[108:111]
	v_mfma_f32_16x16x32_bf16 v[108:111], v[158:161], v[202:205], v[108:111]
	v_mfma_f32_16x16x32_bf16 v[92:95], v[154:157], v[206:209], v[92:95]
	v_mfma_f32_16x16x32_bf16 v[92:95], v[158:161], v[210:213], v[92:95]
	v_mfma_f32_16x16x32_bf16 v[76:79], v[154:157], v[214:217], v[76:79]
	v_mfma_f32_16x16x32_bf16 v[76:79], v[158:161], v[218:221], v[76:79]
	v_mfma_f32_16x16x32_bf16 v[120:123], v[162:165], v[190:193], v[120:123]
	v_mfma_f32_16x16x32_bf16 v[120:123], v[170:173], v[194:197], v[120:123]
	v_mfma_f32_16x16x32_bf16 v[104:107], v[162:165], v[198:201], v[104:107]
	v_mfma_f32_16x16x32_bf16 v[104:107], v[170:173], v[202:205], v[104:107]
	v_mfma_f32_16x16x32_bf16 v[88:91], v[162:165], v[206:209], v[88:91]
	v_mfma_f32_16x16x32_bf16 v[88:91], v[170:173], v[210:213], v[88:91]
	v_mfma_f32_16x16x32_bf16 v[72:75], v[162:165], v[214:217], v[72:75]
	v_mfma_f32_16x16x32_bf16 v[72:75], v[170:173], v[218:221], v[72:75]
	s_setprio 0
	s_setprio 1
	v_mfma_f32_16x16x32_bf16 v[116:119], v[174:177], v[190:193], v[116:119]
	v_mfma_f32_16x16x32_bf16 v[116:119], v[178:181], v[194:197], v[116:119]
	v_mfma_f32_16x16x32_bf16 v[100:103], v[174:177], v[198:201], v[100:103]
	v_mfma_f32_16x16x32_bf16 v[100:103], v[178:181], v[202:205], v[100:103]
	v_mfma_f32_16x16x32_bf16 v[84:87], v[174:177], v[206:209], v[84:87]
	v_mfma_f32_16x16x32_bf16 v[84:87], v[178:181], v[210:213], v[84:87]
	v_mfma_f32_16x16x32_bf16 v[68:71], v[174:177], v[214:217], v[68:71]
	v_mfma_f32_16x16x32_bf16 v[68:71], v[178:181], v[218:221], v[68:71]
	v_mfma_f32_16x16x32_bf16 v[112:115], v[182:185], v[190:193], v[112:115]
	v_mfma_f32_16x16x32_bf16 v[112:115], v[186:189], v[194:197], v[112:115]
	v_mfma_f32_16x16x32_bf16 v[96:99], v[182:185], v[198:201], v[96:99]
	v_mfma_f32_16x16x32_bf16 v[96:99], v[186:189], v[202:205], v[96:99]
	v_mfma_f32_16x16x32_bf16 v[80:83], v[182:185], v[206:209], v[80:83]
	v_mfma_f32_16x16x32_bf16 v[80:83], v[186:189], v[210:213], v[80:83]
	v_mfma_f32_16x16x32_bf16 v[64:67], v[182:185], v[214:217], v[64:67]
	v_mfma_f32_16x16x32_bf16 v[64:67], v[186:189], v[218:221], v[64:67]
	s_setprio 0
	s_barrier
	s_add_i32 s54, s44, s27
	v_lshl_add_u64 v[144:145], s[18:19], 0, v[132:133]
	s_mov_b32 m0, s54
	ds_read_b128 v[190:193], v152 offset:16384
	ds_read_b128 v[194:197], v152 offset:17408
	ds_read_b128 v[198:201], v152 offset:18432
	ds_read_b128 v[202:205], v152 offset:19456
	ds_read_b128 v[206:209], v152 offset:20480
	ds_read_b128 v[210:213], v152 offset:21504
	ds_read_b128 v[214:217], v152 offset:22528
	ds_read_b128 v[218:221], v152 offset:23552
	global_load_lds_dwordx4 v[144:145], off
	s_add_i32 m0, s54, 0x2000
	s_add_u32 s54, s18, 0x84000
	v_lshl_add_u64 v[166:167], s[18:19], 0, v[128:129]
	s_addc_u32 s55, s19, 0
	s_add_i32 s56, s45, s27
	global_load_lds_dwordx4 v[166:167], off
	v_lshl_add_u64 v[222:223], s[54:55], 0, v[132:133]
	s_mov_b32 m0, s56
	v_lshl_add_u64 v[224:225], s[20:21], 0, v[130:131]
	global_load_lds_dwordx4 v[222:223], off
	v_lshl_add_u64 v[222:223], s[54:55], 0, v[128:129]
	s_add_i32 m0, s56, 0x2000
	s_nop 0
	global_load_lds_dwordx4 v[222:223], off
	v_lshl_add_u64 v[222:223], s[20:21], 0, v[134:135]
	s_mov_b32 m0, s36
	s_nop 0
	global_load_lds_dwordx4 v[222:223], off
	s_mov_b32 m0, s37
	s_nop 0
	global_load_lds_dwordx4 v[224:225], off
	s_waitcnt vmcnt(8)
	s_waitcnt lgkmcnt(0)
	s_barrier
; #define PG8_STAGE(bufoff, gbase, voff) do { _Pragma("unroll") for (int _i = 0; _i < 2; ++_i) \
;         __builtin_amdgcn_global_load_lds((const unsigned*)((const char*)(gbase) + (voff)[_i]), (LAS unsigned*)(lds + (bufoff) + ldsw + _i * 8192), 16, 0, 0); } while (0)
; #define PG8_LDA(dst, b, h) do { _Pragma("unroll") for (int m = 0; m < 4; ++m) _Pragma("unroll") for (int k = 0; k < 2; ++k) dst[m][k] = *(const LAS bf16x8*)(lds + PG8_SA(b, h) + aoff + m * 2048 + k * 1024); } while (0)
; #define PG8_LDB(dst, b, h) do { _Pragma("unroll") for (int n = 0; n < 2; ++n) _Pragma("unroll") for (int k = 0; k < 2; ++k) dst[n][k] = *(const LAS bf16x8*)(lds + PG8_SB(b, h) + boff + n * 2048 + k * 1024); } while (0)
; #define PG8_MMA(ai, bj, At, Bt) do { __builtin_amdgcn_s_setprio(1); _Pragma("unroll") for (int m = 0; m < 4; ++m) _Pragma("unroll") for (int n = 0; n < 2; ++n) _Pragma("unroll") for (int k = 0; k < 2; ++k) \
;         acc[ai][bj][m][n] = __builtin_amdgcn_mfma_f32_16x16x32_bf16(Bt[n][k], At[m][k], acc[ai][bj][m][n], 0, 0, 0); __builtin_amdgcn_s_setprio(0); } while (0)
; #define PG8_WAIT_V(n) asm volatile("s_waitcnt vmcnt(" #n ")" ::: "memory")
; #define PG8_WAIT_L(n) asm volatile("s_waitcnt lgkmcnt(" #n ")" ::: "memory")
; #define PG8_BAR __builtin_amdgcn_s_barrier()
; #define PG8_SCHED __builtin_amdgcn_sched_barrier(0)
; template <class EpiT>
; __device__ __forceinline__ void gemm_phase(LAS unsigned char* lds, const Gemm g, const StaticOrder& S, const EpiT& E) {
;     ...
;             PG8_WAIT_V(8); PG8_WAIT_L(0); PG8_BAR; PG8_MMA(1, 0, At, B0); PG8_MMA(1, 1, At, B1); PG8_BAR; PG8_SCHED;
;             PG8_LDB(B0, 1, 0); PG8_LDB(B1, 1, 1); PG8_SCHED; PG8_LDA(At, 1, 0); PG8_STAGE(PG8_SA(0, 1), a2 + hstepA, voffA);
;             PG8_WAIT_V(8); PG8_WAIT_L(0); PG8_BAR; PG8_MMA(0, 0, At, B0); PG8_MMA(0, 1, At, B1); PG8_BAR; PG8_SCHED;
	s_setprio 1
	s_waitcnt lgkmcnt(0)
	v_mfma_f32_16x16x32_bf16 v[60:63], v[154:157], v[190:193], v[60:63]
	v_mfma_f32_16x16x32_bf16 v[60:63], v[158:161], v[194:197], v[60:63]
	v_mfma_f32_16x16x32_bf16 v[44:47], v[154:157], v[198:201], v[44:47]
	v_mfma_f32_16x16x32_bf16 v[44:47], v[158:161], v[202:205], v[44:47]
	v_mfma_f32_16x16x32_bf16 v[28:31], v[154:157], v[206:209], v[28:31]
	v_mfma_f32_16x16x32_bf16 v[28:31], v[158:161], v[210:213], v[28:31]
	v_mfma_f32_16x16x32_bf16 v[12:15], v[154:157], v[214:217], v[12:15]
	v_mfma_f32_16x16x32_bf16 v[12:15], v[158:161], v[218:221], v[12:15]
	v_mfma_f32_16x16x32_bf16 v[56:59], v[162:165], v[190:193], v[56:59]
	v_mfma_f32_16x16x32_bf16 v[56:59], v[170:173], v[194:197], v[56:59]
	v_mfma_f32_16x16x32_bf16 v[40:43], v[162:165], v[198:201], v[40:43]
	v_mfma_f32_16x16x32_bf16 v[40:43], v[170:173], v[202:205], v[40:43]
	v_mfma_f32_16x16x32_bf16 v[24:27], v[162:165], v[206:209], v[24:27]
	v_mfma_f32_16x16x32_bf16 v[24:27], v[170:173], v[210:213], v[24:27]
	v_mfma_f32_16x16x32_bf16 v[8:11], v[162:165], v[214:217], v[8:11]
	v_mfma_f32_16x16x32_bf16 v[8:11], v[170:173], v[218:221], v[8:11]
	s_setprio 0
	s_setprio 1
	v_mfma_f32_16x16x32_bf16 v[52:55], v[174:177], v[190:193], v[52:55]
	v_mfma_f32_16x16x32_bf16 v[52:55], v[178:181], v[194:197], v[52:55]
	v_mfma_f32_16x16x32_bf16 v[36:39], v[174:177], v[198:201], v[36:39]
	v_mfma_f32_16x16x32_bf16 v[36:39], v[178:181], v[202:205], v[36:39]
	v_mfma_f32_16x16x32_bf16 v[20:23], v[174:177], v[206:209], v[20:23]
	v_mfma_f32_16x16x32_bf16 v[20:23], v[178:181], v[210:213], v[20:23]
	v_mfma_f32_16x16x32_bf16 v[4:7], v[174:177], v[214:217], v[4:7]
	v_mfma_f32_16x16x32_bf16 v[4:7], v[178:181], v[218:221], v[4:7]
	v_mfma_f32_16x16x32_bf16 v[48:51], v[182:185], v[190:193], v[48:51]
	v_mfma_f32_16x16x32_bf16 v[48:51], v[186:189], v[194:197], v[48:51]
	v_mfma_f32_16x16x32_bf16 v[32:35], v[182:185], v[198:201], v[32:35]
	v_mfma_f32_16x16x32_bf16 v[32:35], v[186:189], v[202:205], v[32:35]
	v_mfma_f32_16x16x32_bf16 v[16:19], v[182:185], v[206:209], v[16:19]
	v_mfma_f32_16x16x32_bf16 v[16:19], v[186:189], v[210:213], v[16:19]
	v_mfma_f32_16x16x32_bf16 v[0:3], v[182:185], v[214:217], v[0:3]
	v_mfma_f32_16x16x32_bf16 v[0:3], v[186:189], v[218:221], v[0:3]
	s_setprio 0
	s_barrier
	s_add_i32 s54, 0, 0x18000
	v_add_u32_e32 v153, s54, v147
	s_add_i32 s55, 0, 0x1c000
	ds_read_b128 v[154:157], v153
	ds_read_b128 v[158:161], v153 offset:1024
	ds_read_b128 v[162:165], v153 offset:2048
	ds_read_b128 v[170:173], v153 offset:3072
	v_add_u32_e32 v153, s55, v147
	ds_read_b128 v[174:177], v153
	ds_read_b128 v[178:181], v153 offset:1024
	ds_read_b128 v[182:185], v153 offset:2048
	ds_read_b128 v[186:189], v153 offset:3072
	s_add_u32 s20, s20, 0x84000
	s_addc_u32 s21, s21, 0
	s_mov_b32 m0, s38
	v_lshl_add_u64 v[226:227], s[20:21], 0, v[134:135]
	ds_read_b128 v[190:193], v152 offset:32768
	ds_read_b128 v[194:197], v152 offset:33792
	ds_read_b128 v[198:201], v152 offset:34816
	ds_read_b128 v[202:205], v152 offset:35840
	ds_read_b128 v[206:209], v152 offset:36864
	ds_read_b128 v[210:213], v152 offset:37888
	ds_read_b128 v[214:217], v152 offset:38912
	ds_read_b128 v[218:221], v152 offset:39936
	global_load_lds_dwordx4 v[226:227], off
	v_lshl_add_u64 v[226:227], s[20:21], 0, v[130:131]
	s_mov_b32 m0, s39
	s_nop 0
	global_load_lds_dwordx4 v[226:227], off
	s_waitcnt vmcnt(8)
	s_waitcnt lgkmcnt(0)
	s_barrier
	s_setprio 1
	s_waitcnt lgkmcnt(0)
	v_mfma_f32_16x16x32_bf16 v[124:127], v[154:157], v[190:193], v[124:127]
	v_mfma_f32_16x16x32_bf16 v[124:127], v[158:161], v[194:197], v[124:127]
	v_mfma_f32_16x16x32_bf16 v[108:111], v[154:157], v[198:201], v[108:111]
	v_mfma_f32_16x16x32_bf16 v[108:111], v[158:161], v[202:205], v[108:111]
	v_mfma_f32_16x16x32_bf16 v[92:95], v[154:157], v[206:209], v[92:95]
	v_mfma_f32_16x16x32_bf16 v[92:95], v[158:161], v[210:213], v[92:95]
	v_mfma_f32_16x16x32_bf16 v[76:79], v[154:157], v[214:217], v[76:79]
	v_mfma_f32_16x16x32_bf16 v[76:79], v[158:161], v[218:221], v[76:79]
	v_mfma_f32_16x16x32_bf16 v[120:123], v[162:165], v[190:193], v[120:123]
	v_mfma_f32_16x16x32_bf16 v[120:123], v[170:173], v[194:197], v[120:123]
	v_mfma_f32_16x16x32_bf16 v[104:107], v[162:165], v[198:201], v[104:107]
	v_mfma_f32_16x16x32_bf16 v[104:107], v[170:173], v[202:205], v[104:107]
	v_mfma_f32_16x16x32_bf16 v[88:91], v[162:165], v[206:209], v[88:91]
	v_mfma_f32_16x16x32_bf16 v[88:91], v[170:173], v[210:213], v[88:91]
	v_mfma_f32_16x16x32_bf16 v[72:75], v[162:165], v[214:217], v[72:75]
	v_mfma_f32_16x16x32_bf16 v[72:75], v[170:173], v[218:221], v[72:75]
	s_setprio 0
	s_setprio 1
	v_mfma_f32_16x16x32_bf16 v[116:119], v[174:177], v[190:193], v[116:119]
	v_mfma_f32_16x16x32_bf16 v[116:119], v[178:181], v[194:197], v[116:119]
	v_mfma_f32_16x16x32_bf16 v[100:103], v[174:177], v[198:201], v[100:103]
	v_mfma_f32_16x16x32_bf16 v[100:103], v[178:181], v[202:205], v[100:103]
	v_mfma_f32_16x16x32_bf16 v[84:87], v[174:177], v[206:209], v[84:87]
	v_mfma_f32_16x16x32_bf16 v[84:87], v[178:181], v[210:213], v[84:87]
	v_mfma_f32_16x16x32_bf16 v[68:71], v[174:177], v[214:217], v[68:71]
	v_mfma_f32_16x16x32_bf16 v[68:71], v[178:181], v[218:221], v[68:71]
	v_mfma_f32_16x16x32_bf16 v[112:115], v[182:185], v[190:193], v[112:115]
	v_mfma_f32_16x16x32_bf16 v[112:115], v[186:189], v[194:197], v[112:115]
	v_mfma_f32_16x16x32_bf16 v[96:99], v[182:185], v[198:201], v[96:99]
	v_mfma_f32_16x16x32_bf16 v[96:99], v[186:189], v[202:205], v[96:99]
	v_mfma_f32_16x16x32_bf16 v[80:83], v[182:185], v[206:209], v[80:83]
	v_mfma_f32_16x16x32_bf16 v[80:83], v[186:189], v[210:213], v[80:83]
	v_mfma_f32_16x16x32_bf16 v[64:67], v[182:185], v[214:217], v[64:67]
	v_mfma_f32_16x16x32_bf16 v[64:67], v[186:189], v[218:221], v[64:67]
	s_setprio 0
	s_barrier
; #define PG8_STAGE(bufoff, gbase, voff) do { _Pragma("unroll") for (int _i = 0; _i < 2; ++_i) \
;         __builtin_amdgcn_global_load_lds((const unsigned*)((const char*)(gbase) + (voff)[_i]), (LAS unsigned*)(lds + (bufoff) + ldsw + _i * 8192), 16, 0, 0); } while (0)
; #define PG8_LDA(dst, b, h) do { _Pragma("unroll") for (int m = 0; m < 4; ++m) _Pragma("unroll") for (int k = 0; k < 2; ++k) dst[m][k] = *(const LAS bf16x8*)(lds + PG8_SA(b, h) + aoff + m * 2048 + k * 1024); } while (0)
; #define PG8_MMA(ai, bj, At, Bt) do { __builtin_amdgcn_s_setprio(1); _Pragma("unroll") for (int m = 0; m < 4; ++m) _Pragma("unroll") for (int n = 0; n < 2; ++n) _Pragma("unroll") for (int k = 0; k < 2; ++k) \
;         acc[ai][bj][m][n] = __builtin_amdgcn_mfma_f32_16x16x32_bf16(Bt[n][k], At[m][k], acc[ai][bj][m][n], 0, 0, 0); __builtin_amdgcn_s_setprio(0); } while (0)
; #define PG8_WAIT_V(n) asm volatile("s_waitcnt vmcnt(" #n ")" ::: "memory")
; #define PG8_WAIT_L(n) asm volatile("s_waitcnt lgkmcnt(" #n ")" ::: "memory")
; #define PG8_BAR __builtin_amdgcn_s_barrier()
; #define PG8_SCHED __builtin_amdgcn_sched_barrier(0)
; template <class EpiT>
; __device__ __forceinline__ void gemm_phase(LAS unsigned char* lds, const Gemm g, const StaticOrder& S, const EpiT& E) {
;     ...
;             PG8_LDA(At, 1, 1); PG8_STAGE(PG8_SB(1, 0), b3, voffB); PG8_STAGE(PG8_SB(1, 1), b3 + hstepB, voffB); PG8_STAGE(PG8_SA(1, 0), a3, voffA);
;             PG8_WAIT_V(8); PG8_WAIT_L(0); PG8_BAR; PG8_MMA(1, 0, At, B0); PG8_MMA(1, 1, At, B1); PG8_BAR; PG8_SCHED;
;         }
;         if (wr == 0) PG8_BAR;
	s_add_i32 s20, s54, s27
	v_lshl_add_u64 v[144:145], v[144:145], 0, s[10:11]
	s_mov_b32 m0, s20
	ds_read_b128 v[190:193], v152 offset:49152
	ds_read_b128 v[194:197], v152 offset:50176
	ds_read_b128 v[198:201], v152 offset:51200
	ds_read_b128 v[202:205], v152 offset:52224
	ds_read_b128 v[206:209], v152 offset:53248
	ds_read_b128 v[210:213], v152 offset:54272
	ds_read_b128 v[214:217], v152 offset:55296
	ds_read_b128 v[218:221], v152 offset:56320
	global_load_lds_dwordx4 v[144:145], off
	s_add_i32 m0, s20, 0x2000
	s_add_u32 s18, s18, 0x84080
	v_lshl_add_u64 v[144:145], v[166:167], 0, s[10:11]
	s_addc_u32 s19, s19, 0
	s_add_i32 s20, s55, s27
	global_load_lds_dwordx4 v[144:145], off
	v_lshl_add_u64 v[144:145], s[18:19], 0, v[132:133]
	s_mov_b32 m0, s20
	s_nop 0
	global_load_lds_dwordx4 v[144:145], off
	v_lshl_add_u64 v[144:145], s[18:19], 0, v[128:129]
	s_add_i32 m0, s20, 0x2000
	s_nop 0
	global_load_lds_dwordx4 v[144:145], off
	v_lshl_add_u64 v[144:145], v[222:223], 0, s[10:11]
	s_mov_b32 m0, s41
	s_nop 0
	global_load_lds_dwordx4 v[144:145], off
	v_lshl_add_u64 v[144:145], v[224:225], 0, s[10:11]
	s_mov_b32 m0, s42
	s_nop 0
	global_load_lds_dwordx4 v[144:145], off
	s_waitcnt vmcnt(8)
	s_waitcnt lgkmcnt(0)
	s_barrier
	s_setprio 1
	s_waitcnt lgkmcnt(0)
	v_mfma_f32_16x16x32_bf16 v[60:63], v[154:157], v[190:193], v[60:63]
	v_mfma_f32_16x16x32_bf16 v[60:63], v[158:161], v[194:197], v[60:63]
	v_mfma_f32_16x16x32_bf16 v[44:47], v[154:157], v[198:201], v[44:47]
	v_mfma_f32_16x16x32_bf16 v[44:47], v[158:161], v[202:205], v[44:47]
	v_mfma_f32_16x16x32_bf16 v[28:31], v[154:157], v[206:209], v[28:31]
	v_mfma_f32_16x16x32_bf16 v[28:31], v[158:161], v[210:213], v[28:31]
	v_mfma_f32_16x16x32_bf16 v[12:15], v[154:157], v[214:217], v[12:15]
	v_mfma_f32_16x16x32_bf16 v[12:15], v[158:161], v[218:221], v[12:15]
	v_mfma_f32_16x16x32_bf16 v[56:59], v[162:165], v[190:193], v[56:59]
	v_mfma_f32_16x16x32_bf16 v[56:59], v[170:173], v[194:197], v[56:59]
	v_mfma_f32_16x16x32_bf16 v[40:43], v[162:165], v[198:201], v[40:43]
	v_mfma_f32_16x16x32_bf16 v[40:43], v[170:173], v[202:205], v[40:43]
	v_mfma_f32_16x16x32_bf16 v[24:27], v[162:165], v[206:209], v[24:27]
	v_mfma_f32_16x16x32_bf16 v[24:27], v[170:173], v[210:213], v[24:27]
	v_mfma_f32_16x16x32_bf16 v[8:11], v[162:165], v[214:217], v[8:11]
	v_mfma_f32_16x16x32_bf16 v[8:11], v[170:173], v[218:221], v[8:11]
	s_setprio 0
	s_setprio 1
	v_mfma_f32_16x16x32_bf16 v[52:55], v[174:177], v[190:193], v[52:55]
	v_mfma_f32_16x16x32_bf16 v[52:55], v[178:181], v[194:197], v[52:55]
	v_mfma_f32_16x16x32_bf16 v[36:39], v[174:177], v[198:201], v[36:39]
	v_mfma_f32_16x16x32_bf16 v[36:39], v[178:181], v[202:205], v[36:39]
	v_mfma_f32_16x16x32_bf16 v[20:23], v[174:177], v[206:209], v[20:23]
	v_mfma_f32_16x16x32_bf16 v[20:23], v[178:181], v[210:213], v[20:23]
	v_mfma_f32_16x16x32_bf16 v[4:7], v[174:177], v[214:217], v[4:7]
	v_mfma_f32_16x16x32_bf16 v[4:7], v[178:181], v[218:221], v[4:7]
	v_mfma_f32_16x16x32_bf16 v[48:51], v[182:185], v[190:193], v[48:51]
	v_mfma_f32_16x16x32_bf16 v[48:51], v[186:189], v[194:197], v[48:51]
	v_mfma_f32_16x16x32_bf16 v[32:35], v[182:185], v[198:201], v[32:35]
	v_mfma_f32_16x16x32_bf16 v[32:35], v[186:189], v[202:205], v[32:35]
	v_mfma_f32_16x16x32_bf16 v[16:19], v[182:185], v[206:209], v[16:19]
	v_mfma_f32_16x16x32_bf16 v[16:19], v[186:189], v[210:213], v[16:19]
	v_mfma_f32_16x16x32_bf16 v[0:3], v[182:185], v[214:217], v[0:3]
	v_mfma_f32_16x16x32_bf16 v[0:3], v[186:189], v[218:221], v[0:3]
	s_setprio 0
	s_barrier
	s_add_i32 s53, s53, 2
	s_add_u32 s16, s16, 0x100
	s_addc_u32 s17, s17, 0
	s_add_u32 s51, s51, 0x100
	s_addc_u32 s52, s52, 0
	s_cmp_gt_u32 s53, 29
	s_cbranch_scc0 .LBB0_1156
	s_and_b64 vcc, exec, s[12:13]
	s_cbranch_vccz .LBB0_1159
	s_barrier

; #define PG8_STAGE(bufoff, gbase, voff) do { _Pragma("unroll") for (int _i = 0; _i < 2; ++_i) \
;         __builtin_amdgcn_global_load_lds((const unsigned*)((const char*)(gbase) + (voff)[_i]), (LAS unsigned*)(lds + (bufoff) + ldsw + _i * 8192), 16, 0, 0); } while (0)
; #define PG8_LDA(dst, b, h) do { _Pragma("unroll") for (int m = 0; m < 4; ++m) _Pragma("unroll") for (int k = 0; k < 2; ++k) dst[m][k] = *(const LAS bf16x8*)(lds + PG8_SA(b, h) + aoff + m * 2048 + k * 1024); } while (0)
; #define PG8_LDB(dst, b, h) do { _Pragma("unroll") for (int n = 0; n < 2; ++n) _Pragma("unroll") for (int k = 0; k < 2; ++k) dst[n][k] = *(const LAS bf16x8*)(lds + PG8_SB(b, h) + boff + n * 2048 + k * 1024); } while (0)
; #define PG8_MMA(ai, bj, At, Bt) do { __builtin_amdgcn_s_setprio(1); _Pragma("unroll") for (int m = 0; m < 4; ++m) _Pragma("unroll") for (int n = 0; n < 2; ++n) _Pragma("unroll") for (int k = 0; k < 2; ++k) \
;         acc[ai][bj][m][n] = __builtin_amdgcn_mfma_f32_16x16x32_bf16(Bt[n][k], At[m][k], acc[ai][bj][m][n], 0, 0, 0); __builtin_amdgcn_s_setprio(0); } while (0)
; #define PG8_WAIT_V(n) asm volatile("s_waitcnt vmcnt(" #n ")" ::: "memory")
; #define PG8_WAIT_L(n) asm volatile("s_waitcnt lgkmcnt(" #n ")" ::: "memory")
; #define PG8_BAR __builtin_amdgcn_s_barrier()
; #define PG8_SCHED __builtin_amdgcn_sched_barrier(0)
; template <class EpiT>
; __device__ __forceinline__ void gemm_phase(LAS unsigned char* lds, const Gemm g, const StaticOrder& S, const EpiT& E) {
;     ...
;         for (int t = 0; t < nt; t += 2) {
;             const bool last = (t == nt - 2);
;             const char* a1 = cA + (size_t)(t + 1) * kstep;
;             const char* a2 = last ? nA : cA + (size_t)(t + 2) * kstep; const char* b2 = last ? nB : cB + (size_t)(t + 2) * kstep;
;             const char* a3 = a2 + kstep; const char* b3 = b2 + kstep;
;             PG8_LDB(B0, 0, 0); PG8_LDB(B1, 0, 1); PG8_SCHED; PG8_LDA(At, 0, 0); PG8_STAGE(PG8_SA(1, 1), a1 + hstepA, voffA);
;             PG8_WAIT_V(8); PG8_WAIT_L(0); PG8_BAR; PG8_MMA(0, 0, At, B0); PG8_MMA(0, 1, At, B1); PG8_BAR; PG8_SCHED;
;             PG8_LDA(At, 0, 1); PG8_STAGE(PG8_SB(0, 0), b2, voffB); PG8_STAGE(PG8_SB(0, 1), b2 + hstepB, voffB); PG8_STAGE(PG8_SA(0, 0), a2, voffA);
;             PG8_WAIT_V(8); PG8_WAIT_L(0); PG8_BAR; PG8_MMA(1, 0, At, B0); PG8_MMA(1, 1, At, B1); PG8_BAR; PG8_SCHED;
.LBB0_1235:
	ds_read_b128 v[154:157], v150
	ds_read_b128 v[158:161], v150 offset:1024
	ds_read_b128 v[162:165], v150 offset:2048
	ds_read_b128 v[170:173], v150 offset:3072
	ds_read_b128 v[174:177], v151
	ds_read_b128 v[178:181], v151 offset:1024
	ds_read_b128 v[182:185], v151 offset:2048
	ds_read_b128 v[186:189], v151 offset:3072
	s_add_u32 s20, s18, 0xffe9c080
	s_addc_u32 s21, s19, -1
	s_cmpk_eq_i32 s55, 0x54
	s_cselect_b32 s23, s5, s21
	s_cselect_b32 s22, s4, s20
	s_cselect_b32 s21, s17, s54
	s_cselect_b32 s20, s16, s53
	v_lshl_add_u64 v[166:167], s[18:19], 0, v[138:139]
	s_add_i32 m0, s37, 0xc000
	ds_read_b128 v[190:193], v152
	ds_read_b128 v[194:197], v152 offset:1024
	ds_read_b128 v[198:201], v152 offset:2048
	ds_read_b128 v[202:205], v152 offset:3072
	ds_read_b128 v[206:209], v152 offset:4096
	ds_read_b128 v[210:213], v152 offset:5120
	ds_read_b128 v[214:217], v152 offset:6144
	ds_read_b128 v[218:221], v152 offset:7168
	global_load_lds_dwordx4 v[166:167], off
	v_lshl_add_u64 v[166:167], s[18:19], 0, v[140:141]
	s_add_i32 m0, s37, 0xe000
	s_nop 0
	global_load_lds_dwordx4 v[166:167], off
	s_waitcnt vmcnt(8)
	s_waitcnt lgkmcnt(0)
	s_barrier
	s_setprio 1
	s_waitcnt lgkmcnt(0)
	v_mfma_f32_16x16x32_bf16 v[124:127], v[154:157], v[190:193], v[124:127]
	v_mfma_f32_16x16x32_bf16 v[124:127], v[158:161], v[194:197], v[124:127]
	v_mfma_f32_16x16x32_bf16 v[108:111], v[154:157], v[198:201], v[108:111]
	v_mfma_f32_16x16x32_bf16 v[108:111], v[158:161], v[202:205], v[108:111]
	v_mfma_f32_16x16x32_bf16 v[92:95], v[154:157], v[206:209], v[92:95]
	v_mfma_f32_16x16x32_bf16 v[92:95], v[158:161], v[210:213], v[92:95]
	v_mfma_f32_16x16x32_bf16 v[76:79], v[154:157], v[214:217], v[76:79]
	v_mfma_f32_16x16x32_bf16 v[76:79], v[158:161], v[218:221], v[76:79]
	v_mfma_f32_16x16x32_bf16 v[120:123], v[162:165], v[190:193], v[120:123]
	v_mfma_f32_16x16x32_bf16 v[120:123], v[170:173], v[194:197], v[120:123]
	v_mfma_f32_16x16x32_bf16 v[104:107], v[162:165], v[198:201], v[104:107]
	v_mfma_f32_16x16x32_bf16 v[104:107], v[170:173], v[202:205], v[104:107]
	v_mfma_f32_16x16x32_bf16 v[88:91], v[162:165], v[206:209], v[88:91]
	v_mfma_f32_16x16x32_bf16 v[88:91], v[170:173], v[210:213], v[88:91]
	v_mfma_f32_16x16x32_bf16 v[72:75], v[162:165], v[214:217], v[72:75]
	v_mfma_f32_16x16x32_bf16 v[72:75], v[170:173], v[218:221], v[72:75]
	s_setprio 0
	s_setprio 1
	v_mfma_f32_16x16x32_bf16 v[116:119], v[174:177], v[190:193], v[116:119]
	v_mfma_f32_16x16x32_bf16 v[116:119], v[178:181], v[194:197], v[116:119]
	v_mfma_f32_16x16x32_bf16 v[100:103], v[174:177], v[198:201], v[100:103]
	v_mfma_f32_16x16x32_bf16 v[100:103], v[178:181], v[202:205], v[100:103]
	v_mfma_f32_16x16x32_bf16 v[84:87], v[174:177], v[206:209], v[84:87]
	v_mfma_f32_16x16x32_bf16 v[84:87], v[178:181], v[210:213], v[84:87]
	v_mfma_f32_16x16x32_bf16 v[68:71], v[174:177], v[214:217], v[68:71]
	v_mfma_f32_16x16x32_bf16 v[68:71], v[178:181], v[218:221], v[68:71]
	v_mfma_f32_16x16x32_bf16 v[112:115], v[182:185], v[190:193], v[112:115]
	v_mfma_f32_16x16x32_bf16 v[112:115], v[186:189], v[194:197], v[112:115]
	v_mfma_f32_16x16x32_bf16 v[96:99], v[182:185], v[198:201], v[96:99]
	v_mfma_f32_16x16x32_bf16 v[96:99], v[186:189], v[202:205], v[96:99]
	v_mfma_f32_16x16x32_bf16 v[80:83], v[182:185], v[206:209], v[80:83]
	v_mfma_f32_16x16x32_bf16 v[80:83], v[186:189], v[210:213], v[80:83]
	v_mfma_f32_16x16x32_bf16 v[64:67], v[182:185], v[214:217], v[64:67]
	v_mfma_f32_16x16x32_bf16 v[64:67], v[186:189], v[218:221], v[64:67]
	s_setprio 0
	s_barrier
	s_add_i32 s56, s46, s36
	v_lshl_add_u64 v[166:167], s[20:21], 0, v[130:131]
	s_mov_b32 m0, s56
	ds_read_b128 v[190:193], v152 offset:16384
	ds_read_b128 v[194:197], v152 offset:17408
	ds_read_b128 v[198:201], v152 offset:18432
	ds_read_b128 v[202:205], v152 offset:19456
	ds_read_b128 v[206:209], v152 offset:20480
	ds_read_b128 v[210:213], v152 offset:21504
	ds_read_b128 v[214:217], v152 offset:22528
	ds_read_b128 v[218:221], v152 offset:23552
	global_load_lds_dwordx4 v[166:167], off
	s_add_i32 m0, s56, 0x2000
	s_add_u32 s56, s20, 0x164000
	v_lshl_add_u64 v[222:223], s[20:21], 0, v[134:135]
	s_addc_u32 s57, s21, 0
	s_add_i32 s58, s47, s36
	global_load_lds_dwordx4 v[222:223], off
	v_lshl_add_u64 v[224:225], s[56:57], 0, v[130:131]
	s_mov_b32 m0, s58
	v_lshl_add_u64 v[226:227], s[22:23], 0, v[132:133]
	global_load_lds_dwordx4 v[224:225], off
	v_lshl_add_u64 v[224:225], s[56:57], 0, v[134:135]
	s_add_i32 m0, s58, 0x2000
	s_nop 0
	global_load_lds_dwordx4 v[224:225], off
	v_lshl_add_u64 v[224:225], s[22:23], 0, v[128:129]
	s_mov_b32 m0, s37
	s_nop 0
	global_load_lds_dwordx4 v[224:225], off
	s_mov_b32 m0, s38
	s_nop 0
	global_load_lds_dwordx4 v[226:227], off
	s_waitcnt vmcnt(8)
	s_waitcnt lgkmcnt(0)
	s_barrier
; #define PG8_STAGE(bufoff, gbase, voff) do { _Pragma("unroll") for (int _i = 0; _i < 2; ++_i) \
;         __builtin_amdgcn_global_load_lds((const unsigned*)((const char*)(gbase) + (voff)[_i]), (LAS unsigned*)(lds + (bufoff) + ldsw + _i * 8192), 16, 0, 0); } while (0)
; #define PG8_LDA(dst, b, h) do { _Pragma("unroll") for (int m = 0; m < 4; ++m) _Pragma("unroll") for (int k = 0; k < 2; ++k) dst[m][k] = *(const LAS bf16x8*)(lds + PG8_SA(b, h) + aoff + m * 2048 + k * 1024); } while (0)
; #define PG8_LDB(dst, b, h) do { _Pragma("unroll") for (int n = 0; n < 2; ++n) _Pragma("unroll") for (int k = 0; k < 2; ++k) dst[n][k] = *(const LAS bf16x8*)(lds + PG8_SB(b, h) + boff + n * 2048 + k * 1024); } while (0)
; #define PG8_MMA(ai, bj, At, Bt) do { __builtin_amdgcn_s_setprio(1); _Pragma("unroll") for (int m = 0; m < 4; ++m) _Pragma("unroll") for (int n = 0; n < 2; ++n) _Pragma("unroll") for (int k = 0; k < 2; ++k) \
;         acc[ai][bj][m][n] = __builtin_amdgcn_mfma_f32_16x16x32_bf16(Bt[n][k], At[m][k], acc[ai][bj][m][n], 0, 0, 0); __builtin_amdgcn_s_setprio(0); } while (0)
; #define PG8_WAIT_V(n) asm volatile("s_waitcnt vmcnt(" #n ")" ::: "memory")
; #define PG8_WAIT_L(n) asm volatile("s_waitcnt lgkmcnt(" #n ")" ::: "memory")
; #define PG8_BAR __builtin_amdgcn_s_barrier()
; #define PG8_SCHED __builtin_amdgcn_sched_barrier(0)
; template <class EpiT>
; __device__ __forceinline__ void gemm_phase(LAS unsigned char* lds, const Gemm g, const StaticOrder& S, const EpiT& E) {
;     ...
;             PG8_WAIT_V(8); PG8_WAIT_L(0); PG8_BAR; PG8_MMA(1, 0, At, B0); PG8_MMA(1, 1, At, B1); PG8_BAR; PG8_SCHED;
;             PG8_LDB(B0, 1, 0); PG8_LDB(B1, 1, 1); PG8_SCHED; PG8_LDA(At, 1, 0); PG8_STAGE(PG8_SA(0, 1), a2 + hstepA, voffA);
;             PG8_WAIT_V(8); PG8_WAIT_L(0); PG8_BAR; PG8_MMA(0, 0, At, B0); PG8_MMA(0, 1, At, B1); PG8_BAR; PG8_SCHED;
	s_setprio 1
	s_waitcnt lgkmcnt(0)
	v_mfma_f32_16x16x32_bf16 v[60:63], v[154:157], v[190:193], v[60:63]
	v_mfma_f32_16x16x32_bf16 v[60:63], v[158:161], v[194:197], v[60:63]
	v_mfma_f32_16x16x32_bf16 v[44:47], v[154:157], v[198:201], v[44:47]
	v_mfma_f32_16x16x32_bf16 v[44:47], v[158:161], v[202:205], v[44:47]
	v_mfma_f32_16x16x32_bf16 v[28:31], v[154:157], v[206:209], v[28:31]
	v_mfma_f32_16x16x32_bf16 v[28:31], v[158:161], v[210:213], v[28:31]
	v_mfma_f32_16x16x32_bf16 v[12:15], v[154:157], v[214:217], v[12:15]
	v_mfma_f32_16x16x32_bf16 v[12:15], v[158:161], v[218:221], v[12:15]
	v_mfma_f32_16x16x32_bf16 v[56:59], v[162:165], v[190:193], v[56:59]
	v_mfma_f32_16x16x32_bf16 v[56:59], v[170:173], v[194:197], v[56:59]
	v_mfma_f32_16x16x32_bf16 v[40:43], v[162:165], v[198:201], v[40:43]
	v_mfma_f32_16x16x32_bf16 v[40:43], v[170:173], v[202:205], v[40:43]
	v_mfma_f32_16x16x32_bf16 v[24:27], v[162:165], v[206:209], v[24:27]
	v_mfma_f32_16x16x32_bf16 v[24:27], v[170:173], v[210:213], v[24:27]
	v_mfma_f32_16x16x32_bf16 v[8:11], v[162:165], v[214:217], v[8:11]
	v_mfma_f32_16x16x32_bf16 v[8:11], v[170:173], v[218:221], v[8:11]
	s_setprio 0
	s_setprio 1
	v_mfma_f32_16x16x32_bf16 v[52:55], v[174:177], v[190:193], v[52:55]
	v_mfma_f32_16x16x32_bf16 v[52:55], v[178:181], v[194:197], v[52:55]
	v_mfma_f32_16x16x32_bf16 v[36:39], v[174:177], v[198:201], v[36:39]
	v_mfma_f32_16x16x32_bf16 v[36:39], v[178:181], v[202:205], v[36:39]
	v_mfma_f32_16x16x32_bf16 v[20:23], v[174:177], v[206:209], v[20:23]
	v_mfma_f32_16x16x32_bf16 v[20:23], v[178:181], v[210:213], v[20:23]
	v_mfma_f32_16x16x32_bf16 v[4:7], v[174:177], v[214:217], v[4:7]
	v_mfma_f32_16x16x32_bf16 v[4:7], v[178:181], v[218:221], v[4:7]
	v_mfma_f32_16x16x32_bf16 v[48:51], v[182:185], v[190:193], v[48:51]
	v_mfma_f32_16x16x32_bf16 v[48:51], v[186:189], v[194:197], v[48:51]
	v_mfma_f32_16x16x32_bf16 v[32:35], v[182:185], v[198:201], v[32:35]
	v_mfma_f32_16x16x32_bf16 v[32:35], v[186:189], v[202:205], v[32:35]
	v_mfma_f32_16x16x32_bf16 v[16:19], v[182:185], v[206:209], v[16:19]
	v_mfma_f32_16x16x32_bf16 v[16:19], v[186:189], v[210:213], v[16:19]
	v_mfma_f32_16x16x32_bf16 v[0:3], v[182:185], v[214:217], v[0:3]
	v_mfma_f32_16x16x32_bf16 v[0:3], v[186:189], v[218:221], v[0:3]
	s_setprio 0
	s_barrier
	s_add_i32 s56, 0, 0x18000
	s_add_i32 s57, 0, 0x1c000
	v_add_u32_e32 v170, s56, v146
	v_add_u32_e32 v186, s57, v146
	ds_read_b128 v[154:157], v170
	ds_read_b128 v[158:161], v170 offset:1024
	ds_read_b128 v[162:165], v170 offset:2048
	ds_read_b128 v[170:173], v170 offset:3072
	ds_read_b128 v[174:177], v186
	ds_read_b128 v[178:181], v186 offset:1024
	ds_read_b128 v[182:185], v186 offset:2048
	ds_read_b128 v[186:189], v186 offset:3072
	s_add_u32 s22, s22, 0x164000
	s_addc_u32 s23, s23, 0
	s_mov_b32 m0, s39
	v_lshl_add_u64 v[228:229], s[22:23], 0, v[128:129]
	ds_read_b128 v[190:193], v152 offset:32768
	ds_read_b128 v[194:197], v152 offset:33792
	ds_read_b128 v[198:201], v152 offset:34816
	ds_read_b128 v[202:205], v152 offset:35840
	ds_read_b128 v[206:209], v152 offset:36864
	ds_read_b128 v[210:213], v152 offset:37888
	ds_read_b128 v[214:217], v152 offset:38912
	ds_read_b128 v[218:221], v152 offset:39936
	global_load_lds_dwordx4 v[228:229], off
	v_lshl_add_u64 v[228:229], s[22:23], 0, v[132:133]
	s_mov_b32 m0, s40
	s_nop 0
	global_load_lds_dwordx4 v[228:229], off
	s_waitcnt vmcnt(8)
	s_waitcnt lgkmcnt(0)
	s_barrier
	s_setprio 1
	s_waitcnt lgkmcnt(0)
	v_mfma_f32_16x16x32_bf16 v[124:127], v[154:157], v[190:193], v[124:127]
	v_mfma_f32_16x16x32_bf16 v[124:127], v[158:161], v[194:197], v[124:127]
	v_mfma_f32_16x16x32_bf16 v[108:111], v[154:157], v[198:201], v[108:111]
	v_mfma_f32_16x16x32_bf16 v[108:111], v[158:161], v[202:205], v[108:111]
	v_mfma_f32_16x16x32_bf16 v[92:95], v[154:157], v[206:209], v[92:95]
	v_mfma_f32_16x16x32_bf16 v[92:95], v[158:161], v[210:213], v[92:95]
	v_mfma_f32_16x16x32_bf16 v[76:79], v[154:157], v[214:217], v[76:79]
	v_mfma_f32_16x16x32_bf16 v[76:79], v[158:161], v[218:221], v[76:79]
	v_mfma_f32_16x16x32_bf16 v[120:123], v[162:165], v[190:193], v[120:123]
	v_mfma_f32_16x16x32_bf16 v[120:123], v[170:173], v[194:197], v[120:123]
	v_mfma_f32_16x16x32_bf16 v[104:107], v[162:165], v[198:201], v[104:107]
	v_mfma_f32_16x16x32_bf16 v[104:107], v[170:173], v[202:205], v[104:107]
	v_mfma_f32_16x16x32_bf16 v[88:91], v[162:165], v[206:209], v[88:91]
	v_mfma_f32_16x16x32_bf16 v[88:91], v[170:173], v[210:213], v[88:91]
	v_mfma_f32_16x16x32_bf16 v[72:75], v[162:165], v[214:217], v[72:75]
	v_mfma_f32_16x16x32_bf16 v[72:75], v[170:173], v[218:221], v[72:75]
	s_setprio 0
	s_setprio 1
	v_mfma_f32_16x16x32_bf16 v[116:119], v[174:177], v[190:193], v[116:119]
	v_mfma_f32_16x16x32_bf16 v[116:119], v[178:181], v[194:197], v[116:119]
	v_mfma_f32_16x16x32_bf16 v[100:103], v[174:177], v[198:201], v[100:103]
	v_mfma_f32_16x16x32_bf16 v[100:103], v[178:181], v[202:205], v[100:103]
	v_mfma_f32_16x16x32_bf16 v[84:87], v[174:177], v[206:209], v[84:87]
	v_mfma_f32_16x16x32_bf16 v[84:87], v[178:181], v[210:213], v[84:87]
	v_mfma_f32_16x16x32_bf16 v[68:71], v[174:177], v[214:217], v[68:71]
	v_mfma_f32_16x16x32_bf16 v[68:71], v[178:181], v[218:221], v[68:71]
	v_mfma_f32_16x16x32_bf16 v[112:115], v[182:185], v[190:193], v[112:115]
	v_mfma_f32_16x16x32_bf16 v[112:115], v[186:189], v[194:197], v[112:115]
	v_mfma_f32_16x16x32_bf16 v[96:99], v[182:185], v[198:201], v[96:99]
	v_mfma_f32_16x16x32_bf16 v[96:99], v[186:189], v[202:205], v[96:99]
	v_mfma_f32_16x16x32_bf16 v[80:83], v[182:185], v[206:209], v[80:83]
	v_mfma_f32_16x16x32_bf16 v[80:83], v[186:189], v[210:213], v[80:83]
	v_mfma_f32_16x16x32_bf16 v[64:67], v[182:185], v[214:217], v[64:67]
	v_mfma_f32_16x16x32_bf16 v[64:67], v[186:189], v[218:221], v[64:67]
	s_setprio 0
	s_barrier
; #define PG8_STAGE(bufoff, gbase, voff) do { _Pragma("unroll") for (int _i = 0; _i < 2; ++_i) \
;         __builtin_amdgcn_global_load_lds((const unsigned*)((const char*)(gbase) + (voff)[_i]), (LAS unsigned*)(lds + (bufoff) + ldsw + _i * 8192), 16, 0, 0); } while (0)
; #define PG8_LDA(dst, b, h) do { _Pragma("unroll") for (int m = 0; m < 4; ++m) _Pragma("unroll") for (int k = 0; k < 2; ++k) dst[m][k] = *(const LAS bf16x8*)(lds + PG8_SA(b, h) + aoff + m * 2048 + k * 1024); } while (0)
; #define PG8_MMA(ai, bj, At, Bt) do { __builtin_amdgcn_s_setprio(1); _Pragma("unroll") for (int m = 0; m < 4; ++m) _Pragma("unroll") for (int n = 0; n < 2; ++n) _Pragma("unroll") for (int k = 0; k < 2; ++k) \
;         acc[ai][bj][m][n] = __builtin_amdgcn_mfma_f32_16x16x32_bf16(Bt[n][k], At[m][k], acc[ai][bj][m][n], 0, 0, 0); __builtin_amdgcn_s_setprio(0); } while (0)
; #define PG8_WAIT_V(n) asm volatile("s_waitcnt vmcnt(" #n ")" ::: "memory")
; #define PG8_WAIT_L(n) asm volatile("s_waitcnt lgkmcnt(" #n ")" ::: "memory")
; #define PG8_BAR __builtin_amdgcn_s_barrier()
; #define PG8_SCHED __builtin_amdgcn_sched_barrier(0)
; template <class EpiT>
; __device__ __forceinline__ void gemm_phase(LAS unsigned char* lds, const Gemm g, const StaticOrder& S, const EpiT& E) {
;     ...
;             PG8_LDA(At, 1, 1); PG8_STAGE(PG8_SB(1, 0), b3, voffB); PG8_STAGE(PG8_SB(1, 1), b3 + hstepB, voffB); PG8_STAGE(PG8_SA(1, 0), a3, voffA);
;             PG8_WAIT_V(8); PG8_WAIT_L(0); PG8_BAR; PG8_MMA(1, 0, At, B0); PG8_MMA(1, 1, At, B1); PG8_BAR; PG8_SCHED;
;         }
;         if (wr == 0) PG8_BAR;
	s_add_i32 s22, s56, s36
	v_lshl_add_u64 v[166:167], v[166:167], 0, s[12:13]
	s_mov_b32 m0, s22
	ds_read_b128 v[190:193], v152 offset:49152
	ds_read_b128 v[194:197], v152 offset:50176
	ds_read_b128 v[198:201], v152 offset:51200
	ds_read_b128 v[202:205], v152 offset:52224
	ds_read_b128 v[206:209], v152 offset:53248
	ds_read_b128 v[210:213], v152 offset:54272
	ds_read_b128 v[214:217], v152 offset:55296
	ds_read_b128 v[218:221], v152 offset:56320
	global_load_lds_dwordx4 v[166:167], off
	s_add_i32 m0, s22, 0x2000
	s_add_u32 s20, s20, 0x164080
	v_lshl_add_u64 v[166:167], v[222:223], 0, s[12:13]
	s_addc_u32 s21, s21, 0
	s_add_i32 s22, s57, s36
	global_load_lds_dwordx4 v[166:167], off
	v_lshl_add_u64 v[166:167], s[20:21], 0, v[130:131]
	s_mov_b32 m0, s22
	s_nop 0
	global_load_lds_dwordx4 v[166:167], off
	v_lshl_add_u64 v[166:167], s[20:21], 0, v[134:135]
	s_add_i32 m0, s22, 0x2000
	s_nop 0
	global_load_lds_dwordx4 v[166:167], off
	v_lshl_add_u64 v[166:167], v[224:225], 0, s[12:13]
	s_mov_b32 m0, s42
	s_nop 0
	global_load_lds_dwordx4 v[166:167], off
	v_lshl_add_u64 v[166:167], v[226:227], 0, s[12:13]
	s_mov_b32 m0, s43
	s_nop 0
	global_load_lds_dwordx4 v[166:167], off
	s_waitcnt vmcnt(8)
	s_waitcnt lgkmcnt(0)
	s_barrier
	s_setprio 1
	s_waitcnt lgkmcnt(0)
	v_mfma_f32_16x16x32_bf16 v[60:63], v[154:157], v[190:193], v[60:63]
	v_mfma_f32_16x16x32_bf16 v[60:63], v[158:161], v[194:197], v[60:63]
	v_mfma_f32_16x16x32_bf16 v[44:47], v[154:157], v[198:201], v[44:47]
	v_mfma_f32_16x16x32_bf16 v[44:47], v[158:161], v[202:205], v[44:47]
	v_mfma_f32_16x16x32_bf16 v[28:31], v[154:157], v[206:209], v[28:31]
	v_mfma_f32_16x16x32_bf16 v[28:31], v[158:161], v[210:213], v[28:31]
	v_mfma_f32_16x16x32_bf16 v[12:15], v[154:157], v[214:217], v[12:15]
	v_mfma_f32_16x16x32_bf16 v[12:15], v[158:161], v[218:221], v[12:15]
	v_mfma_f32_16x16x32_bf16 v[56:59], v[162:165], v[190:193], v[56:59]
	v_mfma_f32_16x16x32_bf16 v[56:59], v[170:173], v[194:197], v[56:59]
	v_mfma_f32_16x16x32_bf16 v[40:43], v[162:165], v[198:201], v[40:43]
	v_mfma_f32_16x16x32_bf16 v[40:43], v[170:173], v[202:205], v[40:43]
	v_mfma_f32_16x16x32_bf16 v[24:27], v[162:165], v[206:209], v[24:27]
	v_mfma_f32_16x16x32_bf16 v[24:27], v[170:173], v[210:213], v[24:27]
	v_mfma_f32_16x16x32_bf16 v[8:11], v[162:165], v[214:217], v[8:11]
	v_mfma_f32_16x16x32_bf16 v[8:11], v[170:173], v[218:221], v[8:11]
	s_setprio 0
	s_setprio 1
	v_mfma_f32_16x16x32_bf16 v[52:55], v[174:177], v[190:193], v[52:55]
	v_mfma_f32_16x16x32_bf16 v[52:55], v[178:181], v[194:197], v[52:55]
	v_mfma_f32_16x16x32_bf16 v[36:39], v[174:177], v[198:201], v[36:39]
	v_mfma_f32_16x16x32_bf16 v[36:39], v[178:181], v[202:205], v[36:39]
	v_mfma_f32_16x16x32_bf16 v[20:23], v[174:177], v[206:209], v[20:23]
	v_mfma_f32_16x16x32_bf16 v[20:23], v[178:181], v[210:213], v[20:23]
	v_mfma_f32_16x16x32_bf16 v[4:7], v[174:177], v[214:217], v[4:7]
	v_mfma_f32_16x16x32_bf16 v[4:7], v[178:181], v[218:221], v[4:7]
	v_mfma_f32_16x16x32_bf16 v[48:51], v[182:185], v[190:193], v[48:51]
	v_mfma_f32_16x16x32_bf16 v[48:51], v[186:189], v[194:197], v[48:51]
	v_mfma_f32_16x16x32_bf16 v[32:35], v[182:185], v[198:201], v[32:35]
	v_mfma_f32_16x16x32_bf16 v[32:35], v[186:189], v[202:205], v[32:35]
	v_mfma_f32_16x16x32_bf16 v[16:19], v[182:185], v[206:209], v[16:19]
	v_mfma_f32_16x16x32_bf16 v[16:19], v[186:189], v[210:213], v[16:19]
	v_mfma_f32_16x16x32_bf16 v[0:3], v[182:185], v[214:217], v[0:3]
	v_mfma_f32_16x16x32_bf16 v[0:3], v[186:189], v[218:221], v[0:3]
	s_setprio 0
	s_barrier
	s_add_i32 s55, s55, 2
	s_add_u32 s18, s18, 0x100
	s_addc_u32 s19, s19, 0
	s_add_u32 s53, s53, 0x100
	s_addc_u32 s54, s54, 0
	s_cmpk_gt_u32 s55, 0x55
	s_cbranch_scc0 .LBB0_1235
	s_and_b64 vcc, exec, s[14:15]
	s_cbranch_vccz .LBB0_1238
	s_barrier
